# f32 store regrouping now uses DPP row_ror:8 moves instead of ds_swizzle (no LDS round trip / lgkmcnt wait per step)
# speedup vs baseline: 1.0124x; 1.0115x over previous
; __device__ __forceinline__ unsigned cvt_pk_bf16(float lo, float hi) { const f32x2_t v = {lo, hi}; const bf16x2_t b = __builtin_convertvector(v, bf16x2_t); return __builtin_bit_cast(unsigned, b); }
;     __device__ __forceinline__ void operator()(const f32x4 (&acc)[2][2][4][2], const Unit& u, int wr, int wc, int fr, int fq, const PG8_LAS float*) const {
;     ...
;             for (int m = 0; m < 4; ++m) { const int row = row0 + ai * HALF + m * 16; const size_t off = (size_t)row * ldc + col0; float ss = 0.f;
; #pragma unroll
;                 for (int bj = 0; bj < 2; ++bj) {
;                     const f32x4 b0 = *(const f32x4*)(base + off + bj * HALF), b1 = *(const f32x4*)(base + off + bj * HALF + 4);
;                     const f32x4 v0 = b0 + acc[ai][bj][m][0], v1 = b1 + acc[ai][bj][m][1];
;                     *(f32x4*)(out + off + bj * HALF) = v0; *(f32x4*)(out + off + bj * HALF + 4) = v1;
;                     if (xb) { u32x4 w; w.x = cvt_pk_bf16(v0[0], v0[1]); w.y = cvt_pk_bf16(v0[2], v0[3]); w.z = cvt_pk_bf16(v1[0], v1[1]); w.w = cvt_pk_bf16(v1[2], v1[3]);
;                         *(u32x4*)(xb + off + bj * HALF) = w;
;                         ss += ((v0[0] * v0[0] + v0[1] * v0[1]) + (v0[2] * v0[2] + v0[3] * v0[3])) + ((v1[0] * v1[0] + v1[1] * v1[1]) + (v1[2] * v1[2] + v1[3] * v1[3])); } }
;                 if (xb) { ss += __shfl_xor(ss, 16); ss += __shfl_xor(ss, 32); if (fq == 0) ssq[(size_t)row * 16 + u.pn * 4 + wc] = ss; } }
.LBB0_661:
	v_lshl_add_u32 v146, s22, 8, v148
	v_lshl_or_b32 v144, s6, 8, v150
	v_ashrrev_i32_e32 v147, 31, v146
	v_ashrrev_i32_e32 v145, 31, v144
	v_lshlrev_b64 v[156:157], 10, v[146:147]
	v_lshl_add_u64 v[164:165], v[156:157], 0, v[144:145]
	v_readlane_b32 s48, v254, 3
	v_lshlrev_b64 v[168:169], 2, v[164:165]
	v_readlane_b32 s49, v254, 4
	v_readlane_b32 s22, v254, 39
	v_readlane_b32 s23, v254, 40
	v_lshl_add_u64 v[170:171], s[48:49], 0, v[168:169]
	global_load_dwordx4 v[156:159], v[170:171], off
	global_load_dwordx4 v[160:163], v[170:171], off offset:16
	v_lshl_add_u64 v[164:165], v[164:165], 1, s[22:23]
	v_lshl_add_u64 v[172:173], s[68:69], 0, v[168:169]
	v_xor_b32_e32 v155, 32, v154
	s_lshl_b32 s22, s6, 2
	s_ashr_i32 s23, s22, 31
	v_readlane_b32 s50, v254, 5
	v_readlane_b32 s51, v254, 6
	v_readlane_b32 s52, v254, 7
	v_readlane_b32 s53, v254, 8
	v_readlane_b32 s54, v254, 9
	v_readlane_b32 s55, v254, 10
	v_readlane_b32 s56, v254, 11
	v_readlane_b32 s57, v254, 12
	v_readlane_b32 s58, v254, 13
	v_readlane_b32 s59, v254, 14
	v_readlane_b32 s60, v254, 15
	v_readlane_b32 s61, v254, 16
	v_readlane_b32 s62, v254, 17
	v_readlane_b32 s63, v254, 18
	s_waitcnt vmcnt(0)
	v_pk_add_f32 v[126:127], v[126:127], v[158:159]
	v_pk_add_f32 v[124:125], v[124:125], v[156:157]
	v_pk_add_f32 v[158:159], v[122:123], v[162:163]
	v_pk_add_f32 v[156:157], v[120:121], v[160:161]
	v_cvt_pk_bf16_f32 v120, v124, v125
	v_cvt_pk_bf16_f32 v121, v126, v127
	v_cvt_pk_bf16_f32 v122, v156, v157
	v_cvt_pk_bf16_f32 v123, v158, v159
	v_lshl_add_u64 v[228:229], v[172:173], 0, v[230:231]
	v_lshl_add_u64 v[232:233], v[172:173], 0, v[244:245]
	s_nop 1
	v_mov_b32_dpp v236, v156 row_ror:8 row_mask:0xf bank_mask:0xf
	v_mov_b32_dpp v237, v157 row_ror:8 row_mask:0xf bank_mask:0xf
	v_mov_b32_dpp v238, v158 row_ror:8 row_mask:0xf bank_mask:0xf
	v_mov_b32_dpp v239, v159 row_ror:8 row_mask:0xf bank_mask:0xf
	v_mov_b32_dpp v240, v124 row_ror:8 row_mask:0xf bank_mask:0xf
	v_mov_b32_dpp v241, v125 row_ror:8 row_mask:0xf bank_mask:0xf
	v_mov_b32_dpp v242, v126 row_ror:8 row_mask:0xf bank_mask:0xf
	v_mov_b32_dpp v243, v127 row_ror:8 row_mask:0xf bank_mask:0xf
	s_nop 0
	v_cndmask_b32_e64 v236, v236, v124, s[98:99]
	v_cndmask_b32_e64 v237, v237, v125, s[98:99]
	v_cndmask_b32_e64 v238, v238, v126, s[98:99]
	v_cndmask_b32_e64 v239, v239, v127, s[98:99]
	v_cndmask_b32_e64 v240, v156, v240, s[98:99]
	v_cndmask_b32_e64 v241, v157, v241, s[98:99]
	v_cndmask_b32_e64 v242, v158, v242, s[98:99]
	v_cndmask_b32_e64 v243, v159, v243, s[98:99]
	global_store_dwordx4 v[228:229], v[236:239], off
	global_store_dwordx4 v[232:233], v[240:243], off
	global_store_dwordx4 v[164:165], v[120:123], off
	global_load_dwordx4 v[160:163], v[170:171], off offset:512
	s_nop 0
	global_load_dwordx4 v[168:171], v[170:171], off offset:528
	v_mul_f32_e32 v122, v125, v125
	v_mul_f32_e32 v123, v127, v127
	v_mul_f32_e32 v125, v157, v157
	v_mul_f32_e32 v127, v159, v159
	v_fmac_f32_e32 v122, v124, v124
	v_fmac_f32_e32 v123, v126, v126
	v_fmac_f32_e32 v125, v156, v156
	v_fmac_f32_e32 v127, v158, v158
	v_add_f32_e32 v122, v122, v123
	v_add_f32_e32 v123, v125, v127
	v_add_f32_e32 v126, v122, v123
	v_and_b32_e32 v121, 64, v154
	v_xor_b32_e32 v120, 16, v154
	v_add_u32_e32 v121, 64, v121
	v_cmp_lt_i32_e32 vcc, v120, v121
	s_waitcnt vmcnt(1)
	v_pk_add_f32 v[118:119], v[118:119], v[162:163]
	v_pk_add_f32 v[116:117], v[116:117], v[160:161]
	s_waitcnt vmcnt(0)
	v_pk_add_f32 v[124:125], v[114:115], v[170:171]
	v_pk_add_f32 v[122:123], v[112:113], v[168:169]
	v_mul_f32_e32 v112, v117, v117
	v_mul_f32_e32 v113, v119, v119
	v_mul_f32_e32 v114, v123, v123
	v_mul_f32_e32 v115, v125, v125
	v_fmac_f32_e32 v112, v116, v116
	v_fmac_f32_e32 v113, v118, v118
	v_fmac_f32_e32 v114, v122, v122
	v_fmac_f32_e32 v115, v124, v124
	v_add_f32_e32 v112, v112, v113
	v_add_f32_e32 v113, v114, v115
	v_cndmask_b32_e32 v120, v154, v120, vcc
	v_add_f32_e32 v112, v112, v113
	v_lshlrev_b32_e32 v120, 2, v120
	v_add_f32_e32 v112, v126, v112
	ds_bpermute_b32 v113, v120, v112
	v_cmp_lt_i32_e32 vcc, v155, v121
	v_lshl_add_u64 v[228:229], v[172:173], 0, v[230:231]
	v_lshl_add_u64 v[232:233], v[172:173], 0, v[244:245]
	s_nop 1
	v_mov_b32_dpp v236, v122 row_ror:8 row_mask:0xf bank_mask:0xf
	v_mov_b32_dpp v237, v123 row_ror:8 row_mask:0xf bank_mask:0xf
	v_mov_b32_dpp v238, v124 row_ror:8 row_mask:0xf bank_mask:0xf
	v_mov_b32_dpp v239, v125 row_ror:8 row_mask:0xf bank_mask:0xf
	v_mov_b32_dpp v240, v116 row_ror:8 row_mask:0xf bank_mask:0xf
	v_mov_b32_dpp v241, v117 row_ror:8 row_mask:0xf bank_mask:0xf
	v_mov_b32_dpp v242, v118 row_ror:8 row_mask:0xf bank_mask:0xf
	v_mov_b32_dpp v243, v119 row_ror:8 row_mask:0xf bank_mask:0xf
	s_nop 0
	v_cndmask_b32_e64 v236, v236, v116, s[98:99]
	v_cndmask_b32_e64 v237, v237, v117, s[98:99]
	v_cndmask_b32_e64 v238, v238, v118, s[98:99]
	v_cndmask_b32_e64 v239, v239, v119, s[98:99]
	v_cndmask_b32_e64 v240, v122, v240, s[98:99]
	v_cndmask_b32_e64 v241, v123, v241, s[98:99]
	v_cndmask_b32_e64 v242, v124, v242, s[98:99]
	v_cndmask_b32_e64 v243, v125, v243, s[98:99]
	global_store_dwordx4 v[228:229], v[236:239], off offset:512
	global_store_dwordx4 v[232:233], v[240:243], off offset:512
	v_cndmask_b32_e32 v114, v154, v155, vcc
	v_lshlrev_b32_e32 v114, 2, v114
	s_waitcnt lgkmcnt(0)
	v_add_f32_e32 v112, v112, v113
	ds_bpermute_b32 v113, v114, v112
	v_cvt_pk_bf16_f32 v116, v116, v117
	v_cvt_pk_bf16_f32 v117, v118, v119
	v_cvt_pk_bf16_f32 v118, v122, v123
	v_cvt_pk_bf16_f32 v119, v124, v125
	global_store_dwordx4 v[164:165], v[116:119], off offset:256
	s_and_saveexec_b64 s[24:25], s[2:3]
	s_cbranch_execz .LBB0_663
	v_readlane_b32 s26, v254, 41
	s_waitcnt lgkmcnt(0)
	v_add_f32_e32 v115, v112, v113
	v_lshlrev_b64 v[112:113], 6, v[146:147]
	v_readlane_b32 s27, v254, 42
	s_lshl_b32 s6, s38, 2
	s_nop 0
	v_lshl_add_u64 v[112:113], s[26:27], 0, v[112:113]
	v_lshl_add_u64 v[112:113], s[22:23], 2, v[112:113]
	v_lshl_add_u64 v[112:113], v[112:113], 0, s[6:7]
	global_store_dword v[112:113], v115, off
; __device__ __forceinline__ unsigned cvt_pk_bf16(float lo, float hi) { const f32x2_t v = {lo, hi}; const bf16x2_t b = __builtin_convertvector(v, bf16x2_t); return __builtin_bit_cast(unsigned, b); }
;     __device__ __forceinline__ void operator()(const f32x4 (&acc)[2][2][4][2], const Unit& u, int wr, int wc, int fr, int fq, const PG8_LAS float*) const {
;     ...
;             for (int m = 0; m < 4; ++m) { const int row = row0 + ai * HALF + m * 16; const size_t off = (size_t)row * ldc + col0; float ss = 0.f;
; #pragma unroll
;                 for (int bj = 0; bj < 2; ++bj) {
;                     const f32x4 b0 = *(const f32x4*)(base + off + bj * HALF), b1 = *(const f32x4*)(base + off + bj * HALF + 4);
;                     const f32x4 v0 = b0 + acc[ai][bj][m][0], v1 = b1 + acc[ai][bj][m][1];
;                     *(f32x4*)(out + off + bj * HALF) = v0; *(f32x4*)(out + off + bj * HALF + 4) = v1;
;                     if (xb) { u32x4 w; w.x = cvt_pk_bf16(v0[0], v0[1]); w.y = cvt_pk_bf16(v0[2], v0[3]); w.z = cvt_pk_bf16(v1[0], v1[1]); w.w = cvt_pk_bf16(v1[2], v1[3]);
;                         *(u32x4*)(xb + off + bj * HALF) = w;
;                         ss += ((v0[0] * v0[0] + v0[1] * v0[1]) + (v0[2] * v0[2] + v0[3] * v0[3])) + ((v1[0] * v1[0] + v1[1] * v1[1]) + (v1[2] * v1[2] + v1[3] * v1[3])); } }
;                 if (xb) { ss += __shfl_xor(ss, 16); ss += __shfl_xor(ss, 32); if (fq == 0) ssq[(size_t)row * 16 + u.pn * 4 + wc] = ss; } }
.LBB0_663:
	s_or_b64 exec, exec, s[24:25]
	v_or_b32_e32 v112, 16, v146
	s_waitcnt lgkmcnt(0)
	v_ashrrev_i32_e32 v113, 31, v112
	v_lshlrev_b64 v[116:117], 10, v[112:113]
	v_lshl_add_u64 v[126:127], v[116:117], 0, v[144:145]
	v_readlane_b32 s48, v254, 3
	v_lshlrev_b64 v[156:157], 2, v[126:127]
	v_readlane_b32 s49, v254, 4
	v_readlane_b32 s24, v254, 39
	v_readlane_b32 s25, v254, 40
	v_lshl_add_u64 v[158:159], s[48:49], 0, v[156:157]
	global_load_dwordx4 v[116:119], v[158:159], off
	global_load_dwordx4 v[122:125], v[158:159], off offset:16
	v_lshl_add_u64 v[126:127], v[126:127], 1, s[24:25]
	v_lshl_add_u64 v[156:157], s[68:69], 0, v[156:157]
	v_readlane_b32 s50, v254, 5
	v_readlane_b32 s51, v254, 6
	v_readlane_b32 s52, v254, 7
	v_readlane_b32 s53, v254, 8
	v_readlane_b32 s54, v254, 9
	v_readlane_b32 s55, v254, 10
	v_readlane_b32 s56, v254, 11
	v_readlane_b32 s57, v254, 12
	v_readlane_b32 s58, v254, 13
	v_readlane_b32 s59, v254, 14
	v_readlane_b32 s60, v254, 15
	v_readlane_b32 s61, v254, 16
	v_readlane_b32 s62, v254, 17
	v_readlane_b32 s63, v254, 18
	s_waitcnt vmcnt(1)
	v_pk_add_f32 v[110:111], v[110:111], v[118:119]
	v_pk_add_f32 v[108:109], v[108:109], v[116:117]
	s_waitcnt vmcnt(0)
	v_pk_add_f32 v[106:107], v[106:107], v[124:125]
	v_pk_add_f32 v[104:105], v[104:105], v[122:123]
	v_cvt_pk_bf16_f32 v116, v108, v109
	v_cvt_pk_bf16_f32 v117, v110, v111
	v_cvt_pk_bf16_f32 v118, v104, v105
	v_cvt_pk_bf16_f32 v119, v106, v107
	v_lshl_add_u64 v[228:229], v[156:157], 0, v[230:231]
	v_lshl_add_u64 v[232:233], v[156:157], 0, v[244:245]
	s_nop 1
	v_mov_b32_dpp v236, v104 row_ror:8 row_mask:0xf bank_mask:0xf
	v_mov_b32_dpp v237, v105 row_ror:8 row_mask:0xf bank_mask:0xf
	v_mov_b32_dpp v238, v106 row_ror:8 row_mask:0xf bank_mask:0xf
	v_mov_b32_dpp v239, v107 row_ror:8 row_mask:0xf bank_mask:0xf
	v_mov_b32_dpp v240, v108 row_ror:8 row_mask:0xf bank_mask:0xf
	v_mov_b32_dpp v241, v109 row_ror:8 row_mask:0xf bank_mask:0xf
	v_mov_b32_dpp v242, v110 row_ror:8 row_mask:0xf bank_mask:0xf
	v_mov_b32_dpp v243, v111 row_ror:8 row_mask:0xf bank_mask:0xf
	s_nop 0
	v_cndmask_b32_e64 v236, v236, v108, s[98:99]
	v_cndmask_b32_e64 v237, v237, v109, s[98:99]
	v_cndmask_b32_e64 v238, v238, v110, s[98:99]
	v_cndmask_b32_e64 v239, v239, v111, s[98:99]
	v_cndmask_b32_e64 v240, v104, v240, s[98:99]
	v_cndmask_b32_e64 v241, v105, v241, s[98:99]
	v_cndmask_b32_e64 v242, v106, v242, s[98:99]
	v_cndmask_b32_e64 v243, v107, v243, s[98:99]
	global_store_dwordx4 v[228:229], v[236:239], off
	global_store_dwordx4 v[232:233], v[240:243], off
	global_store_dwordx4 v[126:127], v[116:119], off
	global_load_dwordx4 v[116:119], v[158:159], off offset:512
	s_nop 0
	global_load_dwordx4 v[122:125], v[158:159], off offset:528
	v_mul_f32_e32 v109, v109, v109
	v_mul_f32_e32 v111, v111, v111
	v_mul_f32_e32 v105, v105, v105
	v_mul_f32_e32 v107, v107, v107
	v_fmac_f32_e32 v109, v108, v108
	v_fmac_f32_e32 v111, v110, v110
	v_fmac_f32_e32 v105, v104, v104
	v_fmac_f32_e32 v107, v106, v106
	v_add_f32_e32 v104, v109, v111
	v_add_f32_e32 v105, v105, v107
	v_add_f32_e32 v108, v104, v105
	s_waitcnt vmcnt(1)
	v_pk_add_f32 v[102:103], v[102:103], v[118:119]
	v_pk_add_f32 v[100:101], v[100:101], v[116:117]
	s_waitcnt vmcnt(0)
	v_pk_add_f32 v[106:107], v[98:99], v[124:125]
	v_pk_add_f32 v[104:105], v[96:97], v[122:123]
	v_mul_f32_e32 v96, v101, v101
	v_mul_f32_e32 v97, v103, v103
	v_mul_f32_e32 v98, v105, v105
	v_mul_f32_e32 v99, v107, v107
	v_fmac_f32_e32 v96, v100, v100
	v_fmac_f32_e32 v97, v102, v102
	v_fmac_f32_e32 v98, v104, v104
	v_fmac_f32_e32 v99, v106, v106
	v_add_f32_e32 v96, v96, v97
	v_add_f32_e32 v97, v98, v99
	v_add_f32_e32 v96, v96, v97
	v_add_f32_e32 v96, v108, v96
	ds_bpermute_b32 v97, v120, v96
	v_lshl_add_u64 v[228:229], v[156:157], 0, v[230:231]
	v_lshl_add_u64 v[232:233], v[156:157], 0, v[244:245]
	s_nop 1
	v_mov_b32_dpp v236, v104 row_ror:8 row_mask:0xf bank_mask:0xf
	v_mov_b32_dpp v237, v105 row_ror:8 row_mask:0xf bank_mask:0xf
	v_mov_b32_dpp v238, v106 row_ror:8 row_mask:0xf bank_mask:0xf
	v_mov_b32_dpp v239, v107 row_ror:8 row_mask:0xf bank_mask:0xf
	v_mov_b32_dpp v240, v100 row_ror:8 row_mask:0xf bank_mask:0xf
	v_mov_b32_dpp v241, v101 row_ror:8 row_mask:0xf bank_mask:0xf
	v_mov_b32_dpp v242, v102 row_ror:8 row_mask:0xf bank_mask:0xf
	v_mov_b32_dpp v243, v103 row_ror:8 row_mask:0xf bank_mask:0xf
	s_nop 0
	v_cndmask_b32_e64 v236, v236, v100, s[98:99]
	v_cndmask_b32_e64 v237, v237, v101, s[98:99]
	v_cndmask_b32_e64 v238, v238, v102, s[98:99]
	v_cndmask_b32_e64 v239, v239, v103, s[98:99]
	v_cndmask_b32_e64 v240, v104, v240, s[98:99]
	v_cndmask_b32_e64 v241, v105, v241, s[98:99]
	v_cndmask_b32_e64 v242, v106, v242, s[98:99]
	v_cndmask_b32_e64 v243, v107, v243, s[98:99]
	global_store_dwordx4 v[228:229], v[236:239], off offset:512
	global_store_dwordx4 v[232:233], v[240:243], off offset:512
	v_cvt_pk_bf16_f32 v98, v100, v101
	v_cvt_pk_bf16_f32 v99, v102, v103
	v_cvt_pk_bf16_f32 v100, v104, v105
	s_waitcnt lgkmcnt(0)
	v_add_f32_e32 v96, v96, v97
	ds_bpermute_b32 v97, v114, v96
	v_cvt_pk_bf16_f32 v101, v106, v107
	global_store_dwordx4 v[126:127], v[98:101], off offset:256
	s_and_saveexec_b64 s[24:25], s[2:3]
	s_cbranch_execz .LBB0_665
	v_readlane_b32 s26, v254, 41
	s_waitcnt lgkmcnt(0)
	v_add_f32_e32 v98, v96, v97
	v_lshlrev_b64 v[96:97], 6, v[112:113]
	v_readlane_b32 s27, v254, 42
	s_lshl_b32 s6, s38, 2
	s_nop 0
	v_lshl_add_u64 v[96:97], s[26:27], 0, v[96:97]
	v_lshl_add_u64 v[96:97], s[22:23], 2, v[96:97]
	v_lshl_add_u64 v[96:97], v[96:97], 0, s[6:7]
	global_store_dword v[96:97], v98, off
; __device__ __forceinline__ unsigned cvt_pk_bf16(float lo, float hi) { const f32x2_t v = {lo, hi}; const bf16x2_t b = __builtin_convertvector(v, bf16x2_t); return __builtin_bit_cast(unsigned, b); }
;     __device__ __forceinline__ void operator()(const f32x4 (&acc)[2][2][4][2], const Unit& u, int wr, int wc, int fr, int fq, const PG8_LAS float*) const {
;     ...
;             for (int m = 0; m < 4; ++m) { const int row = row0 + ai * HALF + m * 16; const size_t off = (size_t)row * ldc + col0; float ss = 0.f;
; #pragma unroll
;                 for (int bj = 0; bj < 2; ++bj) {
;                     const f32x4 b0 = *(const f32x4*)(base + off + bj * HALF), b1 = *(const f32x4*)(base + off + bj * HALF + 4);
;                     const f32x4 v0 = b0 + acc[ai][bj][m][0], v1 = b1 + acc[ai][bj][m][1];
;                     *(f32x4*)(out + off + bj * HALF) = v0; *(f32x4*)(out + off + bj * HALF + 4) = v1;
;                     if (xb) { u32x4 w; w.x = cvt_pk_bf16(v0[0], v0[1]); w.y = cvt_pk_bf16(v0[2], v0[3]); w.z = cvt_pk_bf16(v1[0], v1[1]); w.w = cvt_pk_bf16(v1[2], v1[3]);
;                         *(u32x4*)(xb + off + bj * HALF) = w;
;                         ss += ((v0[0] * v0[0] + v0[1] * v0[1]) + (v0[2] * v0[2] + v0[3] * v0[3])) + ((v1[0] * v1[0] + v1[1] * v1[1]) + (v1[2] * v1[2] + v1[3] * v1[3])); } }
;                 if (xb) { ss += __shfl_xor(ss, 16); ss += __shfl_xor(ss, 32); if (fq == 0) ssq[(size_t)row * 16 + u.pn * 4 + wc] = ss; } }
.LBB0_665:
	s_or_b64 exec, exec, s[24:25]
	v_or_b32_e32 v96, 32, v146
	s_waitcnt lgkmcnt(0)
	v_ashrrev_i32_e32 v97, 31, v96
	v_lshlrev_b64 v[98:99], 10, v[96:97]
	v_lshl_add_u64 v[106:107], v[98:99], 0, v[144:145]
	v_readlane_b32 s48, v254, 3
	v_lshlrev_b64 v[108:109], 2, v[106:107]
	v_readlane_b32 s49, v254, 4
	v_readlane_b32 s24, v254, 39
	v_readlane_b32 s25, v254, 40
	v_lshl_add_u64 v[110:111], s[48:49], 0, v[108:109]
	global_load_dwordx4 v[98:101], v[110:111], off
	global_load_dwordx4 v[102:105], v[110:111], off offset:16
	v_lshl_add_u64 v[106:107], v[106:107], 1, s[24:25]
	v_lshl_add_u64 v[108:109], s[68:69], 0, v[108:109]
	v_readlane_b32 s50, v254, 5
	v_readlane_b32 s51, v254, 6
	v_readlane_b32 s52, v254, 7
	v_readlane_b32 s53, v254, 8
	v_readlane_b32 s54, v254, 9
	v_readlane_b32 s55, v254, 10
	v_readlane_b32 s56, v254, 11
	v_readlane_b32 s57, v254, 12
	v_readlane_b32 s58, v254, 13
	v_readlane_b32 s59, v254, 14
	v_readlane_b32 s60, v254, 15
	v_readlane_b32 s61, v254, 16
	v_readlane_b32 s62, v254, 17
	v_readlane_b32 s63, v254, 18
	s_waitcnt vmcnt(1)
	v_pk_add_f32 v[94:95], v[94:95], v[100:101]
	v_pk_add_f32 v[92:93], v[92:93], v[98:99]
	s_waitcnt vmcnt(0)
	v_pk_add_f32 v[90:91], v[90:91], v[104:105]
	v_pk_add_f32 v[88:89], v[88:89], v[102:103]
	v_cvt_pk_bf16_f32 v98, v92, v93
	v_cvt_pk_bf16_f32 v99, v94, v95
	v_cvt_pk_bf16_f32 v100, v88, v89
	v_cvt_pk_bf16_f32 v101, v90, v91
	v_lshl_add_u64 v[228:229], v[108:109], 0, v[230:231]
	v_lshl_add_u64 v[232:233], v[108:109], 0, v[244:245]
	s_nop 1
	v_mov_b32_dpp v236, v88 row_ror:8 row_mask:0xf bank_mask:0xf
	v_mov_b32_dpp v237, v89 row_ror:8 row_mask:0xf bank_mask:0xf
	v_mov_b32_dpp v238, v90 row_ror:8 row_mask:0xf bank_mask:0xf
	v_mov_b32_dpp v239, v91 row_ror:8 row_mask:0xf bank_mask:0xf
	v_mov_b32_dpp v240, v92 row_ror:8 row_mask:0xf bank_mask:0xf
	v_mov_b32_dpp v241, v93 row_ror:8 row_mask:0xf bank_mask:0xf
	v_mov_b32_dpp v242, v94 row_ror:8 row_mask:0xf bank_mask:0xf
	v_mov_b32_dpp v243, v95 row_ror:8 row_mask:0xf bank_mask:0xf
	s_nop 0
	v_cndmask_b32_e64 v236, v236, v92, s[98:99]
	v_cndmask_b32_e64 v237, v237, v93, s[98:99]
	v_cndmask_b32_e64 v238, v238, v94, s[98:99]
	v_cndmask_b32_e64 v239, v239, v95, s[98:99]
	v_cndmask_b32_e64 v240, v88, v240, s[98:99]
	v_cndmask_b32_e64 v241, v89, v241, s[98:99]
	v_cndmask_b32_e64 v242, v90, v242, s[98:99]
	v_cndmask_b32_e64 v243, v91, v243, s[98:99]
	global_store_dwordx4 v[228:229], v[236:239], off
	global_store_dwordx4 v[232:233], v[240:243], off
	global_store_dwordx4 v[106:107], v[98:101], off
	global_load_dwordx4 v[98:101], v[110:111], off offset:512
	s_nop 0
	global_load_dwordx4 v[102:105], v[110:111], off offset:528
	v_mul_f32_e32 v93, v93, v93
	v_mul_f32_e32 v95, v95, v95
	v_mul_f32_e32 v89, v89, v89
	v_mul_f32_e32 v91, v91, v91
	v_fmac_f32_e32 v93, v92, v92
	v_fmac_f32_e32 v95, v94, v94
	v_fmac_f32_e32 v89, v88, v88
	v_fmac_f32_e32 v91, v90, v90
	v_add_f32_e32 v88, v93, v95
	v_add_f32_e32 v89, v89, v91
	v_add_f32_e32 v92, v88, v89
	s_waitcnt vmcnt(1)
	v_pk_add_f32 v[86:87], v[86:87], v[100:101]
	v_pk_add_f32 v[84:85], v[84:85], v[98:99]
	s_waitcnt vmcnt(0)
	v_pk_add_f32 v[90:91], v[82:83], v[104:105]
	v_pk_add_f32 v[88:89], v[80:81], v[102:103]
	v_mul_f32_e32 v80, v85, v85
	v_mul_f32_e32 v81, v87, v87
	v_mul_f32_e32 v82, v89, v89
	v_mul_f32_e32 v83, v91, v91
	v_fmac_f32_e32 v80, v84, v84
	v_fmac_f32_e32 v81, v86, v86
	v_fmac_f32_e32 v82, v88, v88
	v_fmac_f32_e32 v83, v90, v90
	v_add_f32_e32 v80, v80, v81
	v_add_f32_e32 v81, v82, v83
	v_add_f32_e32 v80, v80, v81
	v_add_f32_e32 v80, v92, v80
	ds_bpermute_b32 v81, v120, v80
	v_lshl_add_u64 v[228:229], v[108:109], 0, v[230:231]
	v_lshl_add_u64 v[232:233], v[108:109], 0, v[244:245]
	s_nop 1
	v_mov_b32_dpp v236, v88 row_ror:8 row_mask:0xf bank_mask:0xf
	v_mov_b32_dpp v237, v89 row_ror:8 row_mask:0xf bank_mask:0xf
	v_mov_b32_dpp v238, v90 row_ror:8 row_mask:0xf bank_mask:0xf
	v_mov_b32_dpp v239, v91 row_ror:8 row_mask:0xf bank_mask:0xf
	v_mov_b32_dpp v240, v84 row_ror:8 row_mask:0xf bank_mask:0xf
	v_mov_b32_dpp v241, v85 row_ror:8 row_mask:0xf bank_mask:0xf
	v_mov_b32_dpp v242, v86 row_ror:8 row_mask:0xf bank_mask:0xf
	v_mov_b32_dpp v243, v87 row_ror:8 row_mask:0xf bank_mask:0xf
	s_nop 0
	v_cndmask_b32_e64 v236, v236, v84, s[98:99]
	v_cndmask_b32_e64 v237, v237, v85, s[98:99]
	v_cndmask_b32_e64 v238, v238, v86, s[98:99]
	v_cndmask_b32_e64 v239, v239, v87, s[98:99]
	v_cndmask_b32_e64 v240, v88, v240, s[98:99]
	v_cndmask_b32_e64 v241, v89, v241, s[98:99]
	v_cndmask_b32_e64 v242, v90, v242, s[98:99]
	v_cndmask_b32_e64 v243, v91, v243, s[98:99]
	global_store_dwordx4 v[228:229], v[236:239], off offset:512
	global_store_dwordx4 v[232:233], v[240:243], off offset:512
	v_cvt_pk_bf16_f32 v82, v84, v85
	v_cvt_pk_bf16_f32 v83, v86, v87
	v_cvt_pk_bf16_f32 v84, v88, v89
	s_waitcnt lgkmcnt(0)
	v_add_f32_e32 v80, v80, v81
	ds_bpermute_b32 v81, v114, v80
	v_cvt_pk_bf16_f32 v85, v90, v91
	global_store_dwordx4 v[106:107], v[82:85], off offset:256
	s_and_saveexec_b64 s[24:25], s[2:3]
	s_cbranch_execz .LBB0_667
	v_readlane_b32 s26, v254, 41
	s_waitcnt lgkmcnt(0)
	v_add_f32_e32 v82, v80, v81
	v_lshlrev_b64 v[80:81], 6, v[96:97]
	v_readlane_b32 s27, v254, 42
	s_lshl_b32 s6, s38, 2
	s_nop 0
	v_lshl_add_u64 v[80:81], s[26:27], 0, v[80:81]
	v_lshl_add_u64 v[80:81], s[22:23], 2, v[80:81]
	v_lshl_add_u64 v[80:81], v[80:81], 0, s[6:7]
	global_store_dword v[80:81], v82, off
; __device__ __forceinline__ unsigned cvt_pk_bf16(float lo, float hi) { const f32x2_t v = {lo, hi}; const bf16x2_t b = __builtin_convertvector(v, bf16x2_t); return __builtin_bit_cast(unsigned, b); }
;     __device__ __forceinline__ void operator()(const f32x4 (&acc)[2][2][4][2], const Unit& u, int wr, int wc, int fr, int fq, const PG8_LAS float*) const {
;     ...
;             for (int m = 0; m < 4; ++m) { const int row = row0 + ai * HALF + m * 16; const size_t off = (size_t)row * ldc + col0; float ss = 0.f;
; #pragma unroll
;                 for (int bj = 0; bj < 2; ++bj) {
;                     const f32x4 b0 = *(const f32x4*)(base + off + bj * HALF), b1 = *(const f32x4*)(base + off + bj * HALF + 4);
;                     const f32x4 v0 = b0 + acc[ai][bj][m][0], v1 = b1 + acc[ai][bj][m][1];
;                     *(f32x4*)(out + off + bj * HALF) = v0; *(f32x4*)(out + off + bj * HALF + 4) = v1;
;                     if (xb) { u32x4 w; w.x = cvt_pk_bf16(v0[0], v0[1]); w.y = cvt_pk_bf16(v0[2], v0[3]); w.z = cvt_pk_bf16(v1[0], v1[1]); w.w = cvt_pk_bf16(v1[2], v1[3]);
;                         *(u32x4*)(xb + off + bj * HALF) = w;
;                         ss += ((v0[0] * v0[0] + v0[1] * v0[1]) + (v0[2] * v0[2] + v0[3] * v0[3])) + ((v1[0] * v1[0] + v1[1] * v1[1]) + (v1[2] * v1[2] + v1[3] * v1[3])); } }
;                 if (xb) { ss += __shfl_xor(ss, 16); ss += __shfl_xor(ss, 32); if (fq == 0) ssq[(size_t)row * 16 + u.pn * 4 + wc] = ss; } }
.LBB0_667:
	s_or_b64 exec, exec, s[24:25]
	v_or_b32_e32 v80, 48, v146
	s_waitcnt lgkmcnt(0)
	v_ashrrev_i32_e32 v81, 31, v80
	v_lshlrev_b64 v[82:83], 10, v[80:81]
	v_lshl_add_u64 v[90:91], v[82:83], 0, v[144:145]
	v_readlane_b32 s48, v254, 3
	v_lshlrev_b64 v[92:93], 2, v[90:91]
	v_readlane_b32 s49, v254, 4
	v_readlane_b32 s24, v254, 39
	v_readlane_b32 s25, v254, 40
	v_lshl_add_u64 v[94:95], s[48:49], 0, v[92:93]
	global_load_dwordx4 v[82:85], v[94:95], off
	global_load_dwordx4 v[86:89], v[94:95], off offset:16
	v_lshl_add_u64 v[90:91], v[90:91], 1, s[24:25]
	v_lshl_add_u64 v[92:93], s[68:69], 0, v[92:93]
	v_readlane_b32 s50, v254, 5
	v_readlane_b32 s51, v254, 6
	v_readlane_b32 s52, v254, 7
	v_readlane_b32 s53, v254, 8
	v_readlane_b32 s54, v254, 9
	v_readlane_b32 s55, v254, 10
	v_readlane_b32 s56, v254, 11
	v_readlane_b32 s57, v254, 12
	v_readlane_b32 s58, v254, 13
	v_readlane_b32 s59, v254, 14
	v_readlane_b32 s60, v254, 15
	v_readlane_b32 s61, v254, 16
	v_readlane_b32 s62, v254, 17
	v_readlane_b32 s63, v254, 18
	s_waitcnt vmcnt(1)
	v_pk_add_f32 v[78:79], v[78:79], v[84:85]
	v_pk_add_f32 v[76:77], v[76:77], v[82:83]
	s_waitcnt vmcnt(0)
	v_pk_add_f32 v[74:75], v[74:75], v[88:89]
	v_pk_add_f32 v[72:73], v[72:73], v[86:87]
	v_cvt_pk_bf16_f32 v82, v76, v77
	v_cvt_pk_bf16_f32 v83, v78, v79
	v_cvt_pk_bf16_f32 v84, v72, v73
	v_cvt_pk_bf16_f32 v85, v74, v75
	v_lshl_add_u64 v[228:229], v[92:93], 0, v[230:231]
	v_lshl_add_u64 v[232:233], v[92:93], 0, v[244:245]
	s_nop 1
	v_mov_b32_dpp v236, v72 row_ror:8 row_mask:0xf bank_mask:0xf
	v_mov_b32_dpp v237, v73 row_ror:8 row_mask:0xf bank_mask:0xf
	v_mov_b32_dpp v238, v74 row_ror:8 row_mask:0xf bank_mask:0xf
	v_mov_b32_dpp v239, v75 row_ror:8 row_mask:0xf bank_mask:0xf
	v_mov_b32_dpp v240, v76 row_ror:8 row_mask:0xf bank_mask:0xf
	v_mov_b32_dpp v241, v77 row_ror:8 row_mask:0xf bank_mask:0xf
	v_mov_b32_dpp v242, v78 row_ror:8 row_mask:0xf bank_mask:0xf
	v_mov_b32_dpp v243, v79 row_ror:8 row_mask:0xf bank_mask:0xf
	s_nop 0
	v_cndmask_b32_e64 v236, v236, v76, s[98:99]
	v_cndmask_b32_e64 v237, v237, v77, s[98:99]
	v_cndmask_b32_e64 v238, v238, v78, s[98:99]
	v_cndmask_b32_e64 v239, v239, v79, s[98:99]
	v_cndmask_b32_e64 v240, v72, v240, s[98:99]
	v_cndmask_b32_e64 v241, v73, v241, s[98:99]
	v_cndmask_b32_e64 v242, v74, v242, s[98:99]
	v_cndmask_b32_e64 v243, v75, v243, s[98:99]
	global_store_dwordx4 v[228:229], v[236:239], off
	global_store_dwordx4 v[232:233], v[240:243], off
	global_store_dwordx4 v[90:91], v[82:85], off
	global_load_dwordx4 v[82:85], v[94:95], off offset:512
	s_nop 0
	global_load_dwordx4 v[86:89], v[94:95], off offset:528
	v_mul_f32_e32 v77, v77, v77
	v_mul_f32_e32 v79, v79, v79
	v_mul_f32_e32 v73, v73, v73
	v_mul_f32_e32 v75, v75, v75
	v_fmac_f32_e32 v77, v76, v76
	v_fmac_f32_e32 v79, v78, v78
	v_fmac_f32_e32 v73, v72, v72
	v_fmac_f32_e32 v75, v74, v74
	v_add_f32_e32 v72, v77, v79
	v_add_f32_e32 v73, v73, v75
	v_add_f32_e32 v76, v72, v73
	s_waitcnt vmcnt(1)
	v_pk_add_f32 v[70:71], v[70:71], v[84:85]
	v_pk_add_f32 v[68:69], v[68:69], v[82:83]
	s_waitcnt vmcnt(0)
	v_pk_add_f32 v[74:75], v[66:67], v[88:89]
	v_pk_add_f32 v[72:73], v[64:65], v[86:87]
	v_mul_f32_e32 v64, v69, v69
	v_mul_f32_e32 v65, v71, v71
	v_mul_f32_e32 v66, v73, v73
	v_mul_f32_e32 v67, v75, v75
	v_fmac_f32_e32 v64, v68, v68
	v_fmac_f32_e32 v65, v70, v70
	v_fmac_f32_e32 v66, v72, v72
	v_fmac_f32_e32 v67, v74, v74
	v_add_f32_e32 v64, v64, v65
	v_add_f32_e32 v65, v66, v67
	v_add_f32_e32 v64, v64, v65
	v_add_f32_e32 v64, v76, v64
	ds_bpermute_b32 v65, v120, v64
	v_lshl_add_u64 v[228:229], v[92:93], 0, v[230:231]
	v_lshl_add_u64 v[232:233], v[92:93], 0, v[244:245]
	s_nop 1
	v_mov_b32_dpp v236, v72 row_ror:8 row_mask:0xf bank_mask:0xf
	v_mov_b32_dpp v237, v73 row_ror:8 row_mask:0xf bank_mask:0xf
	v_mov_b32_dpp v238, v74 row_ror:8 row_mask:0xf bank_mask:0xf
	v_mov_b32_dpp v239, v75 row_ror:8 row_mask:0xf bank_mask:0xf
	v_mov_b32_dpp v240, v68 row_ror:8 row_mask:0xf bank_mask:0xf
	v_mov_b32_dpp v241, v69 row_ror:8 row_mask:0xf bank_mask:0xf
	v_mov_b32_dpp v242, v70 row_ror:8 row_mask:0xf bank_mask:0xf
	v_mov_b32_dpp v243, v71 row_ror:8 row_mask:0xf bank_mask:0xf
	s_nop 0
	v_cndmask_b32_e64 v236, v236, v68, s[98:99]
	v_cndmask_b32_e64 v237, v237, v69, s[98:99]
	v_cndmask_b32_e64 v238, v238, v70, s[98:99]
	v_cndmask_b32_e64 v239, v239, v71, s[98:99]
	v_cndmask_b32_e64 v240, v72, v240, s[98:99]
	v_cndmask_b32_e64 v241, v73, v241, s[98:99]
	v_cndmask_b32_e64 v242, v74, v242, s[98:99]
	v_cndmask_b32_e64 v243, v75, v243, s[98:99]
	global_store_dwordx4 v[228:229], v[236:239], off offset:512
	global_store_dwordx4 v[232:233], v[240:243], off offset:512
	v_cvt_pk_bf16_f32 v66, v68, v69
	v_cvt_pk_bf16_f32 v67, v70, v71
	v_cvt_pk_bf16_f32 v68, v72, v73
	s_waitcnt lgkmcnt(0)
	v_add_f32_e32 v64, v64, v65
	ds_bpermute_b32 v65, v114, v64
	v_cvt_pk_bf16_f32 v69, v74, v75
	global_store_dwordx4 v[90:91], v[66:69], off offset:256
	s_and_saveexec_b64 s[24:25], s[2:3]
	s_cbranch_execz .LBB0_669
	v_readlane_b32 s26, v254, 41
	s_waitcnt lgkmcnt(0)
	v_add_f32_e32 v66, v64, v65
	v_lshlrev_b64 v[64:65], 6, v[80:81]
	v_readlane_b32 s27, v254, 42
	s_lshl_b32 s6, s38, 2
	s_nop 0
	v_lshl_add_u64 v[64:65], s[26:27], 0, v[64:65]
	v_lshl_add_u64 v[64:65], s[22:23], 2, v[64:65]
	v_lshl_add_u64 v[64:65], v[64:65], 0, s[6:7]
	global_store_dword v[64:65], v66, off
; __device__ __forceinline__ unsigned cvt_pk_bf16(float lo, float hi) { const f32x2_t v = {lo, hi}; const bf16x2_t b = __builtin_convertvector(v, bf16x2_t); return __builtin_bit_cast(unsigned, b); }
;     __device__ __forceinline__ void operator()(const f32x4 (&acc)[2][2][4][2], const Unit& u, int wr, int wc, int fr, int fq, const PG8_LAS float*) const {
;     ...
;             for (int m = 0; m < 4; ++m) { const int row = row0 + ai * HALF + m * 16; const size_t off = (size_t)row * ldc + col0; float ss = 0.f;
; #pragma unroll
;                 for (int bj = 0; bj < 2; ++bj) {
;                     const f32x4 b0 = *(const f32x4*)(base + off + bj * HALF), b1 = *(const f32x4*)(base + off + bj * HALF + 4);
;                     const f32x4 v0 = b0 + acc[ai][bj][m][0], v1 = b1 + acc[ai][bj][m][1];
;                     *(f32x4*)(out + off + bj * HALF) = v0; *(f32x4*)(out + off + bj * HALF + 4) = v1;
;                     if (xb) { u32x4 w; w.x = cvt_pk_bf16(v0[0], v0[1]); w.y = cvt_pk_bf16(v0[2], v0[3]); w.z = cvt_pk_bf16(v1[0], v1[1]); w.w = cvt_pk_bf16(v1[2], v1[3]);
;                         *(u32x4*)(xb + off + bj * HALF) = w;
;                         ss += ((v0[0] * v0[0] + v0[1] * v0[1]) + (v0[2] * v0[2] + v0[3] * v0[3])) + ((v1[0] * v1[0] + v1[1] * v1[1]) + (v1[2] * v1[2] + v1[3] * v1[3])); } }
;                 if (xb) { ss += __shfl_xor(ss, 16); ss += __shfl_xor(ss, 32); if (fq == 0) ssq[(size_t)row * 16 + u.pn * 4 + wc] = ss; } }
.LBB0_669:
	s_or_b64 exec, exec, s[24:25]
	v_add_u32_e32 v64, 0x80, v146
	s_waitcnt lgkmcnt(0)
	v_ashrrev_i32_e32 v65, 31, v64
	v_lshlrev_b64 v[66:67], 10, v[64:65]
	v_lshl_add_u64 v[74:75], v[66:67], 0, v[144:145]
	v_readlane_b32 s48, v254, 3
	v_lshlrev_b64 v[76:77], 2, v[74:75]
	v_readlane_b32 s49, v254, 4
	v_readlane_b32 s24, v254, 39
	v_readlane_b32 s25, v254, 40
	v_lshl_add_u64 v[78:79], s[48:49], 0, v[76:77]
	global_load_dwordx4 v[66:69], v[78:79], off
	global_load_dwordx4 v[70:73], v[78:79], off offset:16
	v_lshl_add_u64 v[74:75], v[74:75], 1, s[24:25]
	v_lshl_add_u64 v[76:77], s[68:69], 0, v[76:77]
	v_readlane_b32 s50, v254, 5
	v_readlane_b32 s51, v254, 6
	v_readlane_b32 s52, v254, 7
	v_readlane_b32 s53, v254, 8
	v_readlane_b32 s54, v254, 9
	v_readlane_b32 s55, v254, 10
	v_readlane_b32 s56, v254, 11
	v_readlane_b32 s57, v254, 12
	v_readlane_b32 s58, v254, 13
	v_readlane_b32 s59, v254, 14
	v_readlane_b32 s60, v254, 15
	v_readlane_b32 s61, v254, 16
	v_readlane_b32 s62, v254, 17
	v_readlane_b32 s63, v254, 18
	s_waitcnt vmcnt(1)
	v_pk_add_f32 v[62:63], v[62:63], v[68:69]
	v_pk_add_f32 v[60:61], v[60:61], v[66:67]
	s_waitcnt vmcnt(0)
	v_pk_add_f32 v[58:59], v[58:59], v[72:73]
	v_pk_add_f32 v[56:57], v[56:57], v[70:71]
	v_cvt_pk_bf16_f32 v66, v60, v61
	v_cvt_pk_bf16_f32 v67, v62, v63
	v_cvt_pk_bf16_f32 v68, v56, v57
	v_cvt_pk_bf16_f32 v69, v58, v59
	v_lshl_add_u64 v[228:229], v[76:77], 0, v[230:231]
	v_lshl_add_u64 v[232:233], v[76:77], 0, v[244:245]
	s_nop 1
	v_mov_b32_dpp v236, v56 row_ror:8 row_mask:0xf bank_mask:0xf
	v_mov_b32_dpp v237, v57 row_ror:8 row_mask:0xf bank_mask:0xf
	v_mov_b32_dpp v238, v58 row_ror:8 row_mask:0xf bank_mask:0xf
	v_mov_b32_dpp v239, v59 row_ror:8 row_mask:0xf bank_mask:0xf
	v_mov_b32_dpp v240, v60 row_ror:8 row_mask:0xf bank_mask:0xf
	v_mov_b32_dpp v241, v61 row_ror:8 row_mask:0xf bank_mask:0xf
	v_mov_b32_dpp v242, v62 row_ror:8 row_mask:0xf bank_mask:0xf
	v_mov_b32_dpp v243, v63 row_ror:8 row_mask:0xf bank_mask:0xf
	s_nop 0
	v_cndmask_b32_e64 v236, v236, v60, s[98:99]
	v_cndmask_b32_e64 v237, v237, v61, s[98:99]
	v_cndmask_b32_e64 v238, v238, v62, s[98:99]
	v_cndmask_b32_e64 v239, v239, v63, s[98:99]
	v_cndmask_b32_e64 v240, v56, v240, s[98:99]
	v_cndmask_b32_e64 v241, v57, v241, s[98:99]
	v_cndmask_b32_e64 v242, v58, v242, s[98:99]
	v_cndmask_b32_e64 v243, v59, v243, s[98:99]
	global_store_dwordx4 v[228:229], v[236:239], off
	global_store_dwordx4 v[232:233], v[240:243], off
	global_store_dwordx4 v[74:75], v[66:69], off
	global_load_dwordx4 v[66:69], v[78:79], off offset:512
	s_nop 0
	global_load_dwordx4 v[70:73], v[78:79], off offset:528
	v_mul_f32_e32 v61, v61, v61
	v_mul_f32_e32 v63, v63, v63
	v_mul_f32_e32 v57, v57, v57
	v_mul_f32_e32 v59, v59, v59
	v_fmac_f32_e32 v61, v60, v60
	v_fmac_f32_e32 v63, v62, v62
	v_fmac_f32_e32 v57, v56, v56
	v_fmac_f32_e32 v59, v58, v58
	v_add_f32_e32 v56, v61, v63
	v_add_f32_e32 v57, v57, v59
	v_add_f32_e32 v60, v56, v57
	s_waitcnt vmcnt(1)
	v_pk_add_f32 v[54:55], v[54:55], v[68:69]
	v_pk_add_f32 v[52:53], v[52:53], v[66:67]
	s_waitcnt vmcnt(0)
	v_pk_add_f32 v[58:59], v[50:51], v[72:73]
	v_pk_add_f32 v[56:57], v[48:49], v[70:71]
	v_mul_f32_e32 v48, v53, v53
	v_mul_f32_e32 v49, v55, v55
	v_mul_f32_e32 v50, v57, v57
	v_mul_f32_e32 v51, v59, v59
	v_fmac_f32_e32 v48, v52, v52
	v_fmac_f32_e32 v49, v54, v54
	v_fmac_f32_e32 v50, v56, v56
	v_fmac_f32_e32 v51, v58, v58
	v_add_f32_e32 v48, v48, v49
	v_add_f32_e32 v49, v50, v51
	v_add_f32_e32 v48, v48, v49
	v_add_f32_e32 v48, v60, v48
	ds_bpermute_b32 v49, v120, v48
	v_lshl_add_u64 v[228:229], v[76:77], 0, v[230:231]
	v_lshl_add_u64 v[232:233], v[76:77], 0, v[244:245]
	s_nop 1
	v_mov_b32_dpp v236, v56 row_ror:8 row_mask:0xf bank_mask:0xf
	v_mov_b32_dpp v237, v57 row_ror:8 row_mask:0xf bank_mask:0xf
	v_mov_b32_dpp v238, v58 row_ror:8 row_mask:0xf bank_mask:0xf
	v_mov_b32_dpp v239, v59 row_ror:8 row_mask:0xf bank_mask:0xf
	v_mov_b32_dpp v240, v52 row_ror:8 row_mask:0xf bank_mask:0xf
	v_mov_b32_dpp v241, v53 row_ror:8 row_mask:0xf bank_mask:0xf
	v_mov_b32_dpp v242, v54 row_ror:8 row_mask:0xf bank_mask:0xf
	v_mov_b32_dpp v243, v55 row_ror:8 row_mask:0xf bank_mask:0xf
	s_nop 0
	v_cndmask_b32_e64 v236, v236, v52, s[98:99]
	v_cndmask_b32_e64 v237, v237, v53, s[98:99]
	v_cndmask_b32_e64 v238, v238, v54, s[98:99]
	v_cndmask_b32_e64 v239, v239, v55, s[98:99]
	v_cndmask_b32_e64 v240, v56, v240, s[98:99]
	v_cndmask_b32_e64 v241, v57, v241, s[98:99]
	v_cndmask_b32_e64 v242, v58, v242, s[98:99]
	v_cndmask_b32_e64 v243, v59, v243, s[98:99]
	global_store_dwordx4 v[228:229], v[236:239], off offset:512
	global_store_dwordx4 v[232:233], v[240:243], off offset:512
	v_cvt_pk_bf16_f32 v50, v52, v53
	v_cvt_pk_bf16_f32 v51, v54, v55
	v_cvt_pk_bf16_f32 v52, v56, v57
	s_waitcnt lgkmcnt(0)
	v_add_f32_e32 v48, v48, v49
	ds_bpermute_b32 v49, v114, v48
	v_cvt_pk_bf16_f32 v53, v58, v59
	global_store_dwordx4 v[74:75], v[50:53], off offset:256
	s_and_saveexec_b64 s[24:25], s[2:3]
	s_cbranch_execz .LBB0_671
	v_readlane_b32 s26, v254, 41
	s_waitcnt lgkmcnt(0)
	v_add_f32_e32 v50, v48, v49
	v_lshlrev_b64 v[48:49], 6, v[64:65]
	v_readlane_b32 s27, v254, 42
	s_lshl_b32 s6, s38, 2
	s_nop 0
	v_lshl_add_u64 v[48:49], s[26:27], 0, v[48:49]
	v_lshl_add_u64 v[48:49], s[22:23], 2, v[48:49]
	v_lshl_add_u64 v[48:49], v[48:49], 0, s[6:7]
	global_store_dword v[48:49], v50, off
; __device__ __forceinline__ unsigned cvt_pk_bf16(float lo, float hi) { const f32x2_t v = {lo, hi}; const bf16x2_t b = __builtin_convertvector(v, bf16x2_t); return __builtin_bit_cast(unsigned, b); }
;     __device__ __forceinline__ void operator()(const f32x4 (&acc)[2][2][4][2], const Unit& u, int wr, int wc, int fr, int fq, const PG8_LAS float*) const {
;     ...
;             for (int m = 0; m < 4; ++m) { const int row = row0 + ai * HALF + m * 16; const size_t off = (size_t)row * ldc + col0; float ss = 0.f;
; #pragma unroll
;                 for (int bj = 0; bj < 2; ++bj) {
;                     const f32x4 b0 = *(const f32x4*)(base + off + bj * HALF), b1 = *(const f32x4*)(base + off + bj * HALF + 4);
;                     const f32x4 v0 = b0 + acc[ai][bj][m][0], v1 = b1 + acc[ai][bj][m][1];
;                     *(f32x4*)(out + off + bj * HALF) = v0; *(f32x4*)(out + off + bj * HALF + 4) = v1;
;                     if (xb) { u32x4 w; w.x = cvt_pk_bf16(v0[0], v0[1]); w.y = cvt_pk_bf16(v0[2], v0[3]); w.z = cvt_pk_bf16(v1[0], v1[1]); w.w = cvt_pk_bf16(v1[2], v1[3]);
;                         *(u32x4*)(xb + off + bj * HALF) = w;
;                         ss += ((v0[0] * v0[0] + v0[1] * v0[1]) + (v0[2] * v0[2] + v0[3] * v0[3])) + ((v1[0] * v1[0] + v1[1] * v1[1]) + (v1[2] * v1[2] + v1[3] * v1[3])); } }
;                 if (xb) { ss += __shfl_xor(ss, 16); ss += __shfl_xor(ss, 32); if (fq == 0) ssq[(size_t)row * 16 + u.pn * 4 + wc] = ss; } }
.LBB0_671:
	s_or_b64 exec, exec, s[24:25]
	v_add_u32_e32 v48, 0x90, v146
	s_waitcnt lgkmcnt(0)
	v_ashrrev_i32_e32 v49, 31, v48
	v_lshlrev_b64 v[50:51], 10, v[48:49]
	v_lshl_add_u64 v[58:59], v[50:51], 0, v[144:145]
	v_readlane_b32 s48, v254, 3
	v_lshlrev_b64 v[60:61], 2, v[58:59]
	v_readlane_b32 s49, v254, 4
	v_readlane_b32 s24, v254, 39
	v_readlane_b32 s25, v254, 40
	v_lshl_add_u64 v[62:63], s[48:49], 0, v[60:61]
	global_load_dwordx4 v[50:53], v[62:63], off
	global_load_dwordx4 v[54:57], v[62:63], off offset:16
	v_lshl_add_u64 v[58:59], v[58:59], 1, s[24:25]
	v_lshl_add_u64 v[60:61], s[68:69], 0, v[60:61]
	v_readlane_b32 s50, v254, 5
	v_readlane_b32 s51, v254, 6
	v_readlane_b32 s52, v254, 7
	v_readlane_b32 s53, v254, 8
	v_readlane_b32 s54, v254, 9
	v_readlane_b32 s55, v254, 10
	v_readlane_b32 s56, v254, 11
	v_readlane_b32 s57, v254, 12
	v_readlane_b32 s58, v254, 13
	v_readlane_b32 s59, v254, 14
	v_readlane_b32 s60, v254, 15
	v_readlane_b32 s61, v254, 16
	v_readlane_b32 s62, v254, 17
	v_readlane_b32 s63, v254, 18
	s_waitcnt vmcnt(1)
	v_pk_add_f32 v[46:47], v[46:47], v[52:53]
	v_pk_add_f32 v[44:45], v[44:45], v[50:51]
	s_waitcnt vmcnt(0)
	v_pk_add_f32 v[42:43], v[42:43], v[56:57]
	v_pk_add_f32 v[40:41], v[40:41], v[54:55]
	v_cvt_pk_bf16_f32 v50, v44, v45
	v_cvt_pk_bf16_f32 v51, v46, v47
	v_cvt_pk_bf16_f32 v52, v40, v41
	v_cvt_pk_bf16_f32 v53, v42, v43
	v_lshl_add_u64 v[228:229], v[60:61], 0, v[230:231]
	v_lshl_add_u64 v[232:233], v[60:61], 0, v[244:245]
	s_nop 1
	v_mov_b32_dpp v236, v40 row_ror:8 row_mask:0xf bank_mask:0xf
	v_mov_b32_dpp v237, v41 row_ror:8 row_mask:0xf bank_mask:0xf
	v_mov_b32_dpp v238, v42 row_ror:8 row_mask:0xf bank_mask:0xf
	v_mov_b32_dpp v239, v43 row_ror:8 row_mask:0xf bank_mask:0xf
	v_mov_b32_dpp v240, v44 row_ror:8 row_mask:0xf bank_mask:0xf
	v_mov_b32_dpp v241, v45 row_ror:8 row_mask:0xf bank_mask:0xf
	v_mov_b32_dpp v242, v46 row_ror:8 row_mask:0xf bank_mask:0xf
	v_mov_b32_dpp v243, v47 row_ror:8 row_mask:0xf bank_mask:0xf
	s_nop 0
	v_cndmask_b32_e64 v236, v236, v44, s[98:99]
	v_cndmask_b32_e64 v237, v237, v45, s[98:99]
	v_cndmask_b32_e64 v238, v238, v46, s[98:99]
	v_cndmask_b32_e64 v239, v239, v47, s[98:99]
	v_cndmask_b32_e64 v240, v40, v240, s[98:99]
	v_cndmask_b32_e64 v241, v41, v241, s[98:99]
	v_cndmask_b32_e64 v242, v42, v242, s[98:99]
	v_cndmask_b32_e64 v243, v43, v243, s[98:99]
	global_store_dwordx4 v[228:229], v[236:239], off
	global_store_dwordx4 v[232:233], v[240:243], off
	global_store_dwordx4 v[58:59], v[50:53], off
	global_load_dwordx4 v[50:53], v[62:63], off offset:512
	s_nop 0
	global_load_dwordx4 v[54:57], v[62:63], off offset:528
	v_mul_f32_e32 v45, v45, v45
	v_mul_f32_e32 v47, v47, v47
	v_mul_f32_e32 v41, v41, v41
	v_mul_f32_e32 v43, v43, v43
	v_fmac_f32_e32 v45, v44, v44
	v_fmac_f32_e32 v47, v46, v46
	v_fmac_f32_e32 v41, v40, v40
	v_fmac_f32_e32 v43, v42, v42
	v_add_f32_e32 v40, v45, v47
	v_add_f32_e32 v41, v41, v43
	v_add_f32_e32 v44, v40, v41
	s_waitcnt vmcnt(1)
	v_pk_add_f32 v[38:39], v[38:39], v[52:53]
	v_pk_add_f32 v[36:37], v[36:37], v[50:51]
	s_waitcnt vmcnt(0)
	v_pk_add_f32 v[42:43], v[34:35], v[56:57]
	v_pk_add_f32 v[40:41], v[32:33], v[54:55]
	v_mul_f32_e32 v32, v37, v37
	v_mul_f32_e32 v33, v39, v39
	v_mul_f32_e32 v34, v41, v41
	v_mul_f32_e32 v35, v43, v43
	v_fmac_f32_e32 v32, v36, v36
	v_fmac_f32_e32 v33, v38, v38
	v_fmac_f32_e32 v34, v40, v40
	v_fmac_f32_e32 v35, v42, v42
	v_add_f32_e32 v32, v32, v33
	v_add_f32_e32 v33, v34, v35
	v_add_f32_e32 v32, v32, v33
	v_add_f32_e32 v32, v44, v32
	ds_bpermute_b32 v33, v120, v32
	v_lshl_add_u64 v[228:229], v[60:61], 0, v[230:231]
	v_lshl_add_u64 v[232:233], v[60:61], 0, v[244:245]
	s_nop 1
	v_mov_b32_dpp v236, v40 row_ror:8 row_mask:0xf bank_mask:0xf
	v_mov_b32_dpp v237, v41 row_ror:8 row_mask:0xf bank_mask:0xf
	v_mov_b32_dpp v238, v42 row_ror:8 row_mask:0xf bank_mask:0xf
	v_mov_b32_dpp v239, v43 row_ror:8 row_mask:0xf bank_mask:0xf
	v_mov_b32_dpp v240, v36 row_ror:8 row_mask:0xf bank_mask:0xf
	v_mov_b32_dpp v241, v37 row_ror:8 row_mask:0xf bank_mask:0xf
	v_mov_b32_dpp v242, v38 row_ror:8 row_mask:0xf bank_mask:0xf
	v_mov_b32_dpp v243, v39 row_ror:8 row_mask:0xf bank_mask:0xf
	s_nop 0
	v_cndmask_b32_e64 v236, v236, v36, s[98:99]
	v_cndmask_b32_e64 v237, v237, v37, s[98:99]
	v_cndmask_b32_e64 v238, v238, v38, s[98:99]
	v_cndmask_b32_e64 v239, v239, v39, s[98:99]
	v_cndmask_b32_e64 v240, v40, v240, s[98:99]
	v_cndmask_b32_e64 v241, v41, v241, s[98:99]
	v_cndmask_b32_e64 v242, v42, v242, s[98:99]
	v_cndmask_b32_e64 v243, v43, v243, s[98:99]
	global_store_dwordx4 v[228:229], v[236:239], off offset:512
	global_store_dwordx4 v[232:233], v[240:243], off offset:512
	v_cvt_pk_bf16_f32 v34, v36, v37
	v_cvt_pk_bf16_f32 v35, v38, v39
	v_cvt_pk_bf16_f32 v36, v40, v41
	s_waitcnt lgkmcnt(0)
	v_add_f32_e32 v32, v32, v33
	ds_bpermute_b32 v33, v114, v32
	v_cvt_pk_bf16_f32 v37, v42, v43
	global_store_dwordx4 v[58:59], v[34:37], off offset:256
	s_and_saveexec_b64 s[24:25], s[2:3]
	s_cbranch_execz .LBB0_673
	v_readlane_b32 s26, v254, 41
	s_waitcnt lgkmcnt(0)
	v_add_f32_e32 v34, v32, v33
	v_lshlrev_b64 v[32:33], 6, v[48:49]
	v_readlane_b32 s27, v254, 42
	s_lshl_b32 s6, s38, 2
	s_nop 0
	v_lshl_add_u64 v[32:33], s[26:27], 0, v[32:33]
	v_lshl_add_u64 v[32:33], s[22:23], 2, v[32:33]
	v_lshl_add_u64 v[32:33], v[32:33], 0, s[6:7]
	global_store_dword v[32:33], v34, off
; __device__ __forceinline__ unsigned cvt_pk_bf16(float lo, float hi) { const f32x2_t v = {lo, hi}; const bf16x2_t b = __builtin_convertvector(v, bf16x2_t); return __builtin_bit_cast(unsigned, b); }
;     __device__ __forceinline__ void operator()(const f32x4 (&acc)[2][2][4][2], const Unit& u, int wr, int wc, int fr, int fq, const PG8_LAS float*) const {
;     ...
;             for (int m = 0; m < 4; ++m) { const int row = row0 + ai * HALF + m * 16; const size_t off = (size_t)row * ldc + col0; float ss = 0.f;
; #pragma unroll
;                 for (int bj = 0; bj < 2; ++bj) {
;                     const f32x4 b0 = *(const f32x4*)(base + off + bj * HALF), b1 = *(const f32x4*)(base + off + bj * HALF + 4);
;                     const f32x4 v0 = b0 + acc[ai][bj][m][0], v1 = b1 + acc[ai][bj][m][1];
;                     *(f32x4*)(out + off + bj * HALF) = v0; *(f32x4*)(out + off + bj * HALF + 4) = v1;
;                     if (xb) { u32x4 w; w.x = cvt_pk_bf16(v0[0], v0[1]); w.y = cvt_pk_bf16(v0[2], v0[3]); w.z = cvt_pk_bf16(v1[0], v1[1]); w.w = cvt_pk_bf16(v1[2], v1[3]);
;                         *(u32x4*)(xb + off + bj * HALF) = w;
;                         ss += ((v0[0] * v0[0] + v0[1] * v0[1]) + (v0[2] * v0[2] + v0[3] * v0[3])) + ((v1[0] * v1[0] + v1[1] * v1[1]) + (v1[2] * v1[2] + v1[3] * v1[3])); } }
;                 if (xb) { ss += __shfl_xor(ss, 16); ss += __shfl_xor(ss, 32); if (fq == 0) ssq[(size_t)row * 16 + u.pn * 4 + wc] = ss; } }
.LBB0_673:
	s_or_b64 exec, exec, s[24:25]
	v_add_u32_e32 v32, 0xa0, v146
	s_waitcnt lgkmcnt(0)
	v_ashrrev_i32_e32 v33, 31, v32
	v_lshlrev_b64 v[34:35], 10, v[32:33]
	v_lshl_add_u64 v[42:43], v[34:35], 0, v[144:145]
	v_readlane_b32 s48, v254, 3
	v_lshlrev_b64 v[44:45], 2, v[42:43]
	v_readlane_b32 s49, v254, 4
	v_readlane_b32 s24, v254, 39
	v_readlane_b32 s25, v254, 40
	v_lshl_add_u64 v[46:47], s[48:49], 0, v[44:45]
	global_load_dwordx4 v[34:37], v[46:47], off
	global_load_dwordx4 v[38:41], v[46:47], off offset:16
	v_lshl_add_u64 v[42:43], v[42:43], 1, s[24:25]
	v_lshl_add_u64 v[44:45], s[68:69], 0, v[44:45]
	v_readlane_b32 s50, v254, 5
	v_readlane_b32 s51, v254, 6
	v_readlane_b32 s52, v254, 7
	v_readlane_b32 s53, v254, 8
	v_readlane_b32 s54, v254, 9
	v_readlane_b32 s55, v254, 10
	v_readlane_b32 s56, v254, 11
	v_readlane_b32 s57, v254, 12
	v_readlane_b32 s58, v254, 13
	v_readlane_b32 s59, v254, 14
	v_readlane_b32 s60, v254, 15
	v_readlane_b32 s61, v254, 16
	v_readlane_b32 s62, v254, 17
	v_readlane_b32 s63, v254, 18
	s_waitcnt vmcnt(1)
	v_pk_add_f32 v[30:31], v[30:31], v[36:37]
	v_pk_add_f32 v[28:29], v[28:29], v[34:35]
	s_waitcnt vmcnt(0)
	v_pk_add_f32 v[26:27], v[26:27], v[40:41]
	v_pk_add_f32 v[24:25], v[24:25], v[38:39]
	v_cvt_pk_bf16_f32 v34, v28, v29
	v_cvt_pk_bf16_f32 v35, v30, v31
	v_cvt_pk_bf16_f32 v36, v24, v25
	v_cvt_pk_bf16_f32 v37, v26, v27
	v_lshl_add_u64 v[228:229], v[44:45], 0, v[230:231]
	v_lshl_add_u64 v[232:233], v[44:45], 0, v[244:245]
	s_nop 1
	v_mov_b32_dpp v236, v24 row_ror:8 row_mask:0xf bank_mask:0xf
	v_mov_b32_dpp v237, v25 row_ror:8 row_mask:0xf bank_mask:0xf
	v_mov_b32_dpp v238, v26 row_ror:8 row_mask:0xf bank_mask:0xf
	v_mov_b32_dpp v239, v27 row_ror:8 row_mask:0xf bank_mask:0xf
	v_mov_b32_dpp v240, v28 row_ror:8 row_mask:0xf bank_mask:0xf
	v_mov_b32_dpp v241, v29 row_ror:8 row_mask:0xf bank_mask:0xf
	v_mov_b32_dpp v242, v30 row_ror:8 row_mask:0xf bank_mask:0xf
	v_mov_b32_dpp v243, v31 row_ror:8 row_mask:0xf bank_mask:0xf
	s_nop 0
	v_cndmask_b32_e64 v236, v236, v28, s[98:99]
	v_cndmask_b32_e64 v237, v237, v29, s[98:99]
	v_cndmask_b32_e64 v238, v238, v30, s[98:99]
	v_cndmask_b32_e64 v239, v239, v31, s[98:99]
	v_cndmask_b32_e64 v240, v24, v240, s[98:99]
	v_cndmask_b32_e64 v241, v25, v241, s[98:99]
	v_cndmask_b32_e64 v242, v26, v242, s[98:99]
	v_cndmask_b32_e64 v243, v27, v243, s[98:99]
	global_store_dwordx4 v[228:229], v[236:239], off
	global_store_dwordx4 v[232:233], v[240:243], off
	global_store_dwordx4 v[42:43], v[34:37], off
	global_load_dwordx4 v[34:37], v[46:47], off offset:512
	s_nop 0
	global_load_dwordx4 v[38:41], v[46:47], off offset:528
	v_mul_f32_e32 v29, v29, v29
	v_mul_f32_e32 v31, v31, v31
	v_mul_f32_e32 v25, v25, v25
	v_mul_f32_e32 v27, v27, v27
	v_fmac_f32_e32 v29, v28, v28
	v_fmac_f32_e32 v31, v30, v30
	v_fmac_f32_e32 v25, v24, v24
	v_fmac_f32_e32 v27, v26, v26
	v_add_f32_e32 v24, v29, v31
	v_add_f32_e32 v25, v25, v27
	v_add_f32_e32 v28, v24, v25
	s_waitcnt vmcnt(1)
	v_pk_add_f32 v[22:23], v[22:23], v[36:37]
	v_pk_add_f32 v[20:21], v[20:21], v[34:35]
	s_waitcnt vmcnt(0)
	v_pk_add_f32 v[26:27], v[18:19], v[40:41]
	v_pk_add_f32 v[24:25], v[16:17], v[38:39]
	v_mul_f32_e32 v16, v21, v21
	v_mul_f32_e32 v17, v23, v23
	v_mul_f32_e32 v18, v25, v25
	v_mul_f32_e32 v19, v27, v27
	v_fmac_f32_e32 v16, v20, v20
	v_fmac_f32_e32 v17, v22, v22
	v_fmac_f32_e32 v18, v24, v24
	v_fmac_f32_e32 v19, v26, v26
	v_add_f32_e32 v16, v16, v17
	v_add_f32_e32 v17, v18, v19
	v_add_f32_e32 v16, v16, v17
	v_add_f32_e32 v16, v28, v16
	ds_bpermute_b32 v17, v120, v16
	v_lshl_add_u64 v[228:229], v[44:45], 0, v[230:231]
	v_lshl_add_u64 v[232:233], v[44:45], 0, v[244:245]
	s_nop 1
	v_mov_b32_dpp v236, v24 row_ror:8 row_mask:0xf bank_mask:0xf
	v_mov_b32_dpp v237, v25 row_ror:8 row_mask:0xf bank_mask:0xf
	v_mov_b32_dpp v238, v26 row_ror:8 row_mask:0xf bank_mask:0xf
	v_mov_b32_dpp v239, v27 row_ror:8 row_mask:0xf bank_mask:0xf
	v_mov_b32_dpp v240, v20 row_ror:8 row_mask:0xf bank_mask:0xf
	v_mov_b32_dpp v241, v21 row_ror:8 row_mask:0xf bank_mask:0xf
	v_mov_b32_dpp v242, v22 row_ror:8 row_mask:0xf bank_mask:0xf
	v_mov_b32_dpp v243, v23 row_ror:8 row_mask:0xf bank_mask:0xf
	s_nop 0
	v_cndmask_b32_e64 v236, v236, v20, s[98:99]
	v_cndmask_b32_e64 v237, v237, v21, s[98:99]
	v_cndmask_b32_e64 v238, v238, v22, s[98:99]
	v_cndmask_b32_e64 v239, v239, v23, s[98:99]
	v_cndmask_b32_e64 v240, v24, v240, s[98:99]
	v_cndmask_b32_e64 v241, v25, v241, s[98:99]
	v_cndmask_b32_e64 v242, v26, v242, s[98:99]
	v_cndmask_b32_e64 v243, v27, v243, s[98:99]
	global_store_dwordx4 v[228:229], v[236:239], off offset:512
	global_store_dwordx4 v[232:233], v[240:243], off offset:512
	v_cvt_pk_bf16_f32 v18, v20, v21
	v_cvt_pk_bf16_f32 v19, v22, v23
	v_cvt_pk_bf16_f32 v20, v24, v25
	s_waitcnt lgkmcnt(0)
	v_add_f32_e32 v16, v16, v17
	ds_bpermute_b32 v17, v114, v16
	v_cvt_pk_bf16_f32 v21, v26, v27
	global_store_dwordx4 v[42:43], v[18:21], off offset:256
	s_and_saveexec_b64 s[24:25], s[2:3]
	s_cbranch_execz .LBB0_675
	v_readlane_b32 s26, v254, 41
	s_waitcnt lgkmcnt(0)
	v_add_f32_e32 v18, v16, v17
	v_lshlrev_b64 v[16:17], 6, v[32:33]
	v_readlane_b32 s27, v254, 42
	s_lshl_b32 s6, s38, 2
	s_nop 0
	v_lshl_add_u64 v[16:17], s[26:27], 0, v[16:17]
	v_lshl_add_u64 v[16:17], s[22:23], 2, v[16:17]
	v_lshl_add_u64 v[16:17], v[16:17], 0, s[6:7]
	global_store_dword v[16:17], v18, off
; __device__ __forceinline__ unsigned cvt_pk_bf16(float lo, float hi) { const f32x2_t v = {lo, hi}; const bf16x2_t b = __builtin_convertvector(v, bf16x2_t); return __builtin_bit_cast(unsigned, b); }
;     __device__ __forceinline__ void operator()(const f32x4 (&acc)[2][2][4][2], const Unit& u, int wr, int wc, int fr, int fq, const PG8_LAS float*) const {
;     ...
;             for (int m = 0; m < 4; ++m) { const int row = row0 + ai * HALF + m * 16; const size_t off = (size_t)row * ldc + col0; float ss = 0.f;
; #pragma unroll
;                 for (int bj = 0; bj < 2; ++bj) {
;                     const f32x4 b0 = *(const f32x4*)(base + off + bj * HALF), b1 = *(const f32x4*)(base + off + bj * HALF + 4);
;                     const f32x4 v0 = b0 + acc[ai][bj][m][0], v1 = b1 + acc[ai][bj][m][1];
;                     *(f32x4*)(out + off + bj * HALF) = v0; *(f32x4*)(out + off + bj * HALF + 4) = v1;
;                     if (xb) { u32x4 w; w.x = cvt_pk_bf16(v0[0], v0[1]); w.y = cvt_pk_bf16(v0[2], v0[3]); w.z = cvt_pk_bf16(v1[0], v1[1]); w.w = cvt_pk_bf16(v1[2], v1[3]);
;                         *(u32x4*)(xb + off + bj * HALF) = w;
;                         ss += ((v0[0] * v0[0] + v0[1] * v0[1]) + (v0[2] * v0[2] + v0[3] * v0[3])) + ((v1[0] * v1[0] + v1[1] * v1[1]) + (v1[2] * v1[2] + v1[3] * v1[3])); } }
;                 if (xb) { ss += __shfl_xor(ss, 16); ss += __shfl_xor(ss, 32); if (fq == 0) ssq[(size_t)row * 16 + u.pn * 4 + wc] = ss; } }
.LBB0_675:
	s_or_b64 exec, exec, s[24:25]
	v_add_u32_e32 v16, 0xb0, v146
	s_waitcnt lgkmcnt(0)
	v_ashrrev_i32_e32 v17, 31, v16
	v_lshlrev_b64 v[18:19], 10, v[16:17]
	v_lshl_add_u64 v[26:27], v[18:19], 0, v[144:145]
	v_readlane_b32 s48, v254, 3
	v_lshlrev_b64 v[28:29], 2, v[26:27]
	v_readlane_b32 s49, v254, 4
	v_readlane_b32 s24, v254, 39
	v_readlane_b32 s25, v254, 40
	v_lshl_add_u64 v[30:31], s[48:49], 0, v[28:29]
	global_load_dwordx4 v[18:21], v[30:31], off
	global_load_dwordx4 v[22:25], v[30:31], off offset:16
	v_lshl_add_u64 v[26:27], v[26:27], 1, s[24:25]
	v_lshl_add_u64 v[28:29], s[68:69], 0, v[28:29]
	v_readlane_b32 s50, v254, 5
	v_readlane_b32 s51, v254, 6
	v_readlane_b32 s52, v254, 7
	v_readlane_b32 s53, v254, 8
	v_readlane_b32 s54, v254, 9
	v_readlane_b32 s55, v254, 10
	v_readlane_b32 s56, v254, 11
	v_readlane_b32 s57, v254, 12
	v_readlane_b32 s58, v254, 13
	v_readlane_b32 s59, v254, 14
	v_readlane_b32 s60, v254, 15
	v_readlane_b32 s61, v254, 16
	v_readlane_b32 s62, v254, 17
	v_readlane_b32 s63, v254, 18
	s_waitcnt vmcnt(1)
	v_pk_add_f32 v[14:15], v[14:15], v[20:21]
	v_pk_add_f32 v[12:13], v[12:13], v[18:19]
	s_waitcnt vmcnt(0)
	v_pk_add_f32 v[10:11], v[10:11], v[24:25]
	v_pk_add_f32 v[8:9], v[8:9], v[22:23]
	v_cvt_pk_bf16_f32 v18, v12, v13
	v_cvt_pk_bf16_f32 v19, v14, v15
	v_cvt_pk_bf16_f32 v20, v8, v9
	v_cvt_pk_bf16_f32 v21, v10, v11
	v_lshl_add_u64 v[228:229], v[28:29], 0, v[230:231]
	v_lshl_add_u64 v[232:233], v[28:29], 0, v[244:245]
	s_nop 1
	v_mov_b32_dpp v236, v8 row_ror:8 row_mask:0xf bank_mask:0xf
	v_mov_b32_dpp v237, v9 row_ror:8 row_mask:0xf bank_mask:0xf
	v_mov_b32_dpp v238, v10 row_ror:8 row_mask:0xf bank_mask:0xf
	v_mov_b32_dpp v239, v11 row_ror:8 row_mask:0xf bank_mask:0xf
	v_mov_b32_dpp v240, v12 row_ror:8 row_mask:0xf bank_mask:0xf
	v_mov_b32_dpp v241, v13 row_ror:8 row_mask:0xf bank_mask:0xf
	v_mov_b32_dpp v242, v14 row_ror:8 row_mask:0xf bank_mask:0xf
	v_mov_b32_dpp v243, v15 row_ror:8 row_mask:0xf bank_mask:0xf
	s_nop 0
	v_cndmask_b32_e64 v236, v236, v12, s[98:99]
	v_cndmask_b32_e64 v237, v237, v13, s[98:99]
	v_cndmask_b32_e64 v238, v238, v14, s[98:99]
	v_cndmask_b32_e64 v239, v239, v15, s[98:99]
	v_cndmask_b32_e64 v240, v8, v240, s[98:99]
	v_cndmask_b32_e64 v241, v9, v241, s[98:99]
	v_cndmask_b32_e64 v242, v10, v242, s[98:99]
	v_cndmask_b32_e64 v243, v11, v243, s[98:99]
	global_store_dwordx4 v[228:229], v[236:239], off
	global_store_dwordx4 v[232:233], v[240:243], off
	global_store_dwordx4 v[26:27], v[18:21], off
	global_load_dwordx4 v[18:21], v[30:31], off offset:512
	s_nop 0
	global_load_dwordx4 v[22:25], v[30:31], off offset:528
	v_mul_f32_e32 v13, v13, v13
	v_mul_f32_e32 v15, v15, v15
	v_mul_f32_e32 v9, v9, v9
	v_mul_f32_e32 v11, v11, v11
	v_fmac_f32_e32 v13, v12, v12
	v_fmac_f32_e32 v15, v14, v14
	v_fmac_f32_e32 v9, v8, v8
	v_fmac_f32_e32 v11, v10, v10
	v_add_f32_e32 v8, v13, v15
	v_add_f32_e32 v9, v9, v11
	v_add_f32_e32 v12, v8, v9
	s_waitcnt vmcnt(1)
	v_pk_add_f32 v[6:7], v[6:7], v[20:21]
	v_pk_add_f32 v[4:5], v[4:5], v[18:19]
	s_waitcnt vmcnt(0)
	v_pk_add_f32 v[10:11], v[2:3], v[24:25]
	v_pk_add_f32 v[8:9], v[0:1], v[22:23]
	v_mul_f32_e32 v0, v5, v5
	v_mul_f32_e32 v1, v7, v7
	v_mul_f32_e32 v2, v9, v9
	v_mul_f32_e32 v3, v11, v11
	v_fmac_f32_e32 v0, v4, v4
	v_fmac_f32_e32 v1, v6, v6
	v_fmac_f32_e32 v2, v8, v8
	v_fmac_f32_e32 v3, v10, v10
	v_add_f32_e32 v0, v0, v1
	v_add_f32_e32 v1, v2, v3
	v_add_f32_e32 v0, v0, v1
	v_add_f32_e32 v0, v12, v0
	ds_bpermute_b32 v1, v120, v0
	v_lshl_add_u64 v[228:229], v[28:29], 0, v[230:231]
	v_lshl_add_u64 v[232:233], v[28:29], 0, v[244:245]
	s_nop 1
	v_mov_b32_dpp v236, v8 row_ror:8 row_mask:0xf bank_mask:0xf
	v_mov_b32_dpp v237, v9 row_ror:8 row_mask:0xf bank_mask:0xf
	v_mov_b32_dpp v238, v10 row_ror:8 row_mask:0xf bank_mask:0xf
	v_mov_b32_dpp v239, v11 row_ror:8 row_mask:0xf bank_mask:0xf
	v_mov_b32_dpp v240, v4 row_ror:8 row_mask:0xf bank_mask:0xf
	v_mov_b32_dpp v241, v5 row_ror:8 row_mask:0xf bank_mask:0xf
	v_mov_b32_dpp v242, v6 row_ror:8 row_mask:0xf bank_mask:0xf
	v_mov_b32_dpp v243, v7 row_ror:8 row_mask:0xf bank_mask:0xf
	s_nop 0
	v_cndmask_b32_e64 v236, v236, v4, s[98:99]
	v_cndmask_b32_e64 v237, v237, v5, s[98:99]
	v_cndmask_b32_e64 v238, v238, v6, s[98:99]
	v_cndmask_b32_e64 v239, v239, v7, s[98:99]
	v_cndmask_b32_e64 v240, v8, v240, s[98:99]
	v_cndmask_b32_e64 v241, v9, v241, s[98:99]
	v_cndmask_b32_e64 v242, v10, v242, s[98:99]
	v_cndmask_b32_e64 v243, v11, v243, s[98:99]
	global_store_dwordx4 v[228:229], v[236:239], off offset:512
	global_store_dwordx4 v[232:233], v[240:243], off offset:512
	v_cvt_pk_bf16_f32 v2, v4, v5
	v_cvt_pk_bf16_f32 v3, v6, v7
	v_cvt_pk_bf16_f32 v4, v8, v9
	s_waitcnt lgkmcnt(0)
	v_add_f32_e32 v0, v0, v1
	ds_bpermute_b32 v1, v114, v0
	v_cvt_pk_bf16_f32 v5, v10, v11
	global_store_dwordx4 v[26:27], v[2:5], off offset:256
	s_and_saveexec_b64 s[24:25], s[2:3]
	s_cbranch_execz .LBB0_677
	v_readlane_b32 s26, v254, 41
	s_waitcnt lgkmcnt(0)
	v_add_f32_e32 v2, v0, v1
	v_lshlrev_b64 v[0:1], 6, v[16:17]
	v_readlane_b32 s27, v254, 42
	s_lshl_b32 s6, s38, 2
	s_nop 0
	v_lshl_add_u64 v[0:1], s[26:27], 0, v[0:1]
	v_lshl_add_u64 v[0:1], s[22:23], 2, v[0:1]
	v_lshl_add_u64 v[0:1], v[0:1], 0, s[6:7]
	global_store_dword v[0:1], v2, off

; __device__ __forceinline__ unsigned cvt_pk_bf16(float lo, float hi) { const f32x2_t v = {lo, hi}; const bf16x2_t b = __builtin_convertvector(v, bf16x2_t); return __builtin_bit_cast(unsigned, b); }
;     __device__ __forceinline__ void operator()(const f32x4 (&acc)[2][2][4][2], const Unit& u, int wr, int wc, int fr, int fq, const PG8_LAS float*) const {
;     ...
;             for (int m = 0; m < 4; ++m) { const int row = row0 + ai * HALF + m * 16; const size_t off = (size_t)row * ldc + col0; float ss = 0.f;
; #pragma unroll
;                 for (int bj = 0; bj < 2; ++bj) {
;                     const f32x4 b0 = *(const f32x4*)(base + off + bj * HALF), b1 = *(const f32x4*)(base + off + bj * HALF + 4);
;                     const f32x4 v0 = b0 + acc[ai][bj][m][0], v1 = b1 + acc[ai][bj][m][1];
;                     *(f32x4*)(out + off + bj * HALF) = v0; *(f32x4*)(out + off + bj * HALF + 4) = v1;
;                     if (xb) { u32x4 w; w.x = cvt_pk_bf16(v0[0], v0[1]); w.y = cvt_pk_bf16(v0[2], v0[3]); w.z = cvt_pk_bf16(v1[0], v1[1]); w.w = cvt_pk_bf16(v1[2], v1[3]);
;                         *(u32x4*)(xb + off + bj * HALF) = w;
;                         ss += ((v0[0] * v0[0] + v0[1] * v0[1]) + (v0[2] * v0[2] + v0[3] * v0[3])) + ((v1[0] * v1[0] + v1[1] * v1[1]) + (v1[2] * v1[2] + v1[3] * v1[3])); } }
;                 if (xb) { ss += __shfl_xor(ss, 16); ss += __shfl_xor(ss, 32); if (fq == 0) ssq[(size_t)row * 16 + u.pn * 4 + wc] = ss; } }
.LBB0_845:
	v_lshl_add_u32 v146, s22, 8, v148
	v_lshl_or_b32 v144, s6, 8, v150
	v_ashrrev_i32_e32 v147, 31, v146
	v_ashrrev_i32_e32 v145, 31, v144
	v_lshlrev_b64 v[156:157], 10, v[146:147]
	v_lshl_add_u64 v[164:165], v[156:157], 0, v[144:145]
	v_lshl_add_u64 v[172:173], v[164:165], 2, s[68:69]
	global_load_dwordx4 v[156:159], v[172:173], off
	global_load_dwordx4 v[160:163], v[172:173], off offset:16
	v_readlane_b32 s22, v254, 39
	v_readlane_b32 s23, v254, 40
	v_xor_b32_e32 v155, 32, v154
	s_waitcnt vmcnt(0)
	v_pk_add_f32 v[126:127], v[126:127], v[158:159]
	v_pk_add_f32 v[124:125], v[124:125], v[156:157]
	v_pk_add_f32 v[158:159], v[122:123], v[162:163]
	v_pk_add_f32 v[156:157], v[120:121], v[160:161]
	v_lshl_add_u64 v[164:165], v[164:165], 1, s[22:23]
	v_cvt_pk_bf16_f32 v120, v124, v125
	v_cvt_pk_bf16_f32 v121, v126, v127
	v_cvt_pk_bf16_f32 v122, v156, v157
	v_cvt_pk_bf16_f32 v123, v158, v159
	v_lshl_add_u64 v[228:229], v[172:173], 0, v[230:231]
	v_lshl_add_u64 v[232:233], v[172:173], 0, v[244:245]
	s_nop 1
	v_mov_b32_dpp v236, v156 row_ror:8 row_mask:0xf bank_mask:0xf
	v_mov_b32_dpp v237, v157 row_ror:8 row_mask:0xf bank_mask:0xf
	v_mov_b32_dpp v238, v158 row_ror:8 row_mask:0xf bank_mask:0xf
	v_mov_b32_dpp v239, v159 row_ror:8 row_mask:0xf bank_mask:0xf
	v_mov_b32_dpp v240, v124 row_ror:8 row_mask:0xf bank_mask:0xf
	v_mov_b32_dpp v241, v125 row_ror:8 row_mask:0xf bank_mask:0xf
	v_mov_b32_dpp v242, v126 row_ror:8 row_mask:0xf bank_mask:0xf
	v_mov_b32_dpp v243, v127 row_ror:8 row_mask:0xf bank_mask:0xf
	s_nop 0
	v_cndmask_b32_e64 v236, v236, v124, s[98:99]
	v_cndmask_b32_e64 v237, v237, v125, s[98:99]
	v_cndmask_b32_e64 v238, v238, v126, s[98:99]
	v_cndmask_b32_e64 v239, v239, v127, s[98:99]
	v_cndmask_b32_e64 v240, v156, v240, s[98:99]
	v_cndmask_b32_e64 v241, v157, v241, s[98:99]
	v_cndmask_b32_e64 v242, v158, v242, s[98:99]
	v_cndmask_b32_e64 v243, v159, v243, s[98:99]
	global_store_dwordx4 v[228:229], v[236:239], off
	global_store_dwordx4 v[232:233], v[240:243], off
	global_store_dwordx4 v[164:165], v[120:123], off
	global_load_dwordx4 v[160:163], v[172:173], off offset:512
	global_load_dwordx4 v[168:171], v[172:173], off offset:528
	v_mul_f32_e32 v122, v125, v125
	v_mul_f32_e32 v123, v127, v127
	v_mul_f32_e32 v125, v157, v157
	v_mul_f32_e32 v127, v159, v159
	v_fmac_f32_e32 v122, v124, v124
	v_fmac_f32_e32 v123, v126, v126
	v_fmac_f32_e32 v125, v156, v156
	v_fmac_f32_e32 v127, v158, v158
	v_add_f32_e32 v122, v122, v123
	v_add_f32_e32 v123, v125, v127
	v_add_f32_e32 v126, v122, v123
	v_and_b32_e32 v121, 64, v154
	v_xor_b32_e32 v120, 16, v154
	v_add_u32_e32 v121, 64, v121
	v_cmp_lt_i32_e32 vcc, v120, v121
	s_lshl_b32 s22, s6, 2
	s_ashr_i32 s23, s22, 31
	v_cndmask_b32_e32 v120, v154, v120, vcc
	v_lshlrev_b32_e32 v120, 2, v120
	v_cmp_lt_i32_e32 vcc, v155, v121
	s_waitcnt vmcnt(1)
	v_pk_add_f32 v[118:119], v[118:119], v[162:163]
	v_pk_add_f32 v[116:117], v[116:117], v[160:161]
	s_waitcnt vmcnt(0)
	v_pk_add_f32 v[124:125], v[114:115], v[170:171]
	v_pk_add_f32 v[122:123], v[112:113], v[168:169]
	v_mul_f32_e32 v112, v117, v117
	v_mul_f32_e32 v113, v119, v119
	v_mul_f32_e32 v114, v123, v123
	v_mul_f32_e32 v115, v125, v125
	v_fmac_f32_e32 v112, v116, v116
	v_fmac_f32_e32 v113, v118, v118
	v_fmac_f32_e32 v114, v122, v122
	v_fmac_f32_e32 v115, v124, v124
	v_add_f32_e32 v112, v112, v113
	v_add_f32_e32 v113, v114, v115
	v_add_f32_e32 v112, v112, v113
	v_add_f32_e32 v112, v126, v112
	ds_bpermute_b32 v113, v120, v112
	v_cndmask_b32_e32 v114, v154, v155, vcc
	v_lshlrev_b32_e32 v114, 2, v114
	v_lshl_add_u64 v[228:229], v[172:173], 0, v[230:231]
	v_lshl_add_u64 v[232:233], v[172:173], 0, v[244:245]
	s_nop 1
	v_mov_b32_dpp v236, v122 row_ror:8 row_mask:0xf bank_mask:0xf
	v_mov_b32_dpp v237, v123 row_ror:8 row_mask:0xf bank_mask:0xf
	v_mov_b32_dpp v238, v124 row_ror:8 row_mask:0xf bank_mask:0xf
	v_mov_b32_dpp v239, v125 row_ror:8 row_mask:0xf bank_mask:0xf
	v_mov_b32_dpp v240, v116 row_ror:8 row_mask:0xf bank_mask:0xf
	v_mov_b32_dpp v241, v117 row_ror:8 row_mask:0xf bank_mask:0xf
	v_mov_b32_dpp v242, v118 row_ror:8 row_mask:0xf bank_mask:0xf
	v_mov_b32_dpp v243, v119 row_ror:8 row_mask:0xf bank_mask:0xf
	s_nop 0
	v_cndmask_b32_e64 v236, v236, v116, s[98:99]
	v_cndmask_b32_e64 v237, v237, v117, s[98:99]
	v_cndmask_b32_e64 v238, v238, v118, s[98:99]
	v_cndmask_b32_e64 v239, v239, v119, s[98:99]
	v_cndmask_b32_e64 v240, v122, v240, s[98:99]
	v_cndmask_b32_e64 v241, v123, v241, s[98:99]
	v_cndmask_b32_e64 v242, v124, v242, s[98:99]
	v_cndmask_b32_e64 v243, v125, v243, s[98:99]
	global_store_dwordx4 v[228:229], v[236:239], off offset:512
	global_store_dwordx4 v[232:233], v[240:243], off offset:512
	s_waitcnt lgkmcnt(0)
	v_add_f32_e32 v112, v112, v113
	ds_bpermute_b32 v113, v114, v112
	v_cvt_pk_bf16_f32 v116, v116, v117
	v_cvt_pk_bf16_f32 v117, v118, v119
	v_cvt_pk_bf16_f32 v118, v122, v123
	v_cvt_pk_bf16_f32 v119, v124, v125
	global_store_dwordx4 v[164:165], v[116:119], off offset:256
	s_and_saveexec_b64 s[24:25], s[2:3]
	s_cbranch_execz .LBB0_847
	v_readlane_b32 s26, v254, 41
	s_waitcnt lgkmcnt(0)
	v_add_f32_e32 v115, v112, v113
	v_lshlrev_b64 v[112:113], 6, v[146:147]
	v_readlane_b32 s27, v254, 42
	s_lshl_b32 s6, s38, 2
	s_nop 0
	v_lshl_add_u64 v[112:113], s[26:27], 0, v[112:113]
	v_lshl_add_u64 v[112:113], s[22:23], 2, v[112:113]
	v_lshl_add_u64 v[112:113], v[112:113], 0, s[6:7]
	global_store_dword v[112:113], v115, off
; __device__ __forceinline__ unsigned cvt_pk_bf16(float lo, float hi) { const f32x2_t v = {lo, hi}; const bf16x2_t b = __builtin_convertvector(v, bf16x2_t); return __builtin_bit_cast(unsigned, b); }
;     __device__ __forceinline__ void operator()(const f32x4 (&acc)[2][2][4][2], const Unit& u, int wr, int wc, int fr, int fq, const PG8_LAS float*) const {
;     ...
;             for (int m = 0; m < 4; ++m) { const int row = row0 + ai * HALF + m * 16; const size_t off = (size_t)row * ldc + col0; float ss = 0.f;
; #pragma unroll
;                 for (int bj = 0; bj < 2; ++bj) {
;                     const f32x4 b0 = *(const f32x4*)(base + off + bj * HALF), b1 = *(const f32x4*)(base + off + bj * HALF + 4);
;                     const f32x4 v0 = b0 + acc[ai][bj][m][0], v1 = b1 + acc[ai][bj][m][1];
;                     *(f32x4*)(out + off + bj * HALF) = v0; *(f32x4*)(out + off + bj * HALF + 4) = v1;
;                     if (xb) { u32x4 w; w.x = cvt_pk_bf16(v0[0], v0[1]); w.y = cvt_pk_bf16(v0[2], v0[3]); w.z = cvt_pk_bf16(v1[0], v1[1]); w.w = cvt_pk_bf16(v1[2], v1[3]);
;                         *(u32x4*)(xb + off + bj * HALF) = w;
;                         ss += ((v0[0] * v0[0] + v0[1] * v0[1]) + (v0[2] * v0[2] + v0[3] * v0[3])) + ((v1[0] * v1[0] + v1[1] * v1[1]) + (v1[2] * v1[2] + v1[3] * v1[3])); } }
;                 if (xb) { ss += __shfl_xor(ss, 16); ss += __shfl_xor(ss, 32); if (fq == 0) ssq[(size_t)row * 16 + u.pn * 4 + wc] = ss; } }
.LBB0_847:
	s_or_b64 exec, exec, s[24:25]
	v_or_b32_e32 v112, 16, v146
	s_waitcnt lgkmcnt(0)
	v_ashrrev_i32_e32 v113, 31, v112
	v_lshlrev_b64 v[116:117], 10, v[112:113]
	v_lshl_add_u64 v[126:127], v[116:117], 0, v[144:145]
	v_lshl_add_u64 v[156:157], v[126:127], 2, s[68:69]
	global_load_dwordx4 v[116:119], v[156:157], off
	global_load_dwordx4 v[122:125], v[156:157], off offset:16
	v_readlane_b32 s24, v254, 39
	v_readlane_b32 s25, v254, 40
	s_waitcnt vmcnt(1)
	v_pk_add_f32 v[110:111], v[110:111], v[118:119]
	v_pk_add_f32 v[108:109], v[108:109], v[116:117]
	s_waitcnt vmcnt(0)
	v_pk_add_f32 v[106:107], v[106:107], v[124:125]
	v_pk_add_f32 v[104:105], v[104:105], v[122:123]
	v_lshl_add_u64 v[126:127], v[126:127], 1, s[24:25]
	v_cvt_pk_bf16_f32 v116, v108, v109
	v_cvt_pk_bf16_f32 v117, v110, v111
	v_cvt_pk_bf16_f32 v118, v104, v105
	v_cvt_pk_bf16_f32 v119, v106, v107
	v_lshl_add_u64 v[228:229], v[156:157], 0, v[230:231]
	v_lshl_add_u64 v[232:233], v[156:157], 0, v[244:245]
	s_nop 1
	v_mov_b32_dpp v236, v104 row_ror:8 row_mask:0xf bank_mask:0xf
	v_mov_b32_dpp v237, v105 row_ror:8 row_mask:0xf bank_mask:0xf
	v_mov_b32_dpp v238, v106 row_ror:8 row_mask:0xf bank_mask:0xf
	v_mov_b32_dpp v239, v107 row_ror:8 row_mask:0xf bank_mask:0xf
	v_mov_b32_dpp v240, v108 row_ror:8 row_mask:0xf bank_mask:0xf
	v_mov_b32_dpp v241, v109 row_ror:8 row_mask:0xf bank_mask:0xf
	v_mov_b32_dpp v242, v110 row_ror:8 row_mask:0xf bank_mask:0xf
	v_mov_b32_dpp v243, v111 row_ror:8 row_mask:0xf bank_mask:0xf
	s_nop 0
	v_cndmask_b32_e64 v236, v236, v108, s[98:99]
	v_cndmask_b32_e64 v237, v237, v109, s[98:99]
	v_cndmask_b32_e64 v238, v238, v110, s[98:99]
	v_cndmask_b32_e64 v239, v239, v111, s[98:99]
	v_cndmask_b32_e64 v240, v104, v240, s[98:99]
	v_cndmask_b32_e64 v241, v105, v241, s[98:99]
	v_cndmask_b32_e64 v242, v106, v242, s[98:99]
	v_cndmask_b32_e64 v243, v107, v243, s[98:99]
	global_store_dwordx4 v[228:229], v[236:239], off
	global_store_dwordx4 v[232:233], v[240:243], off
	global_store_dwordx4 v[126:127], v[116:119], off
	global_load_dwordx4 v[116:119], v[156:157], off offset:512
	s_nop 0
	global_load_dwordx4 v[122:125], v[156:157], off offset:528
	v_mul_f32_e32 v109, v109, v109
	v_mul_f32_e32 v111, v111, v111
	v_mul_f32_e32 v105, v105, v105
	v_mul_f32_e32 v107, v107, v107
	v_fmac_f32_e32 v109, v108, v108
	v_fmac_f32_e32 v111, v110, v110
	v_fmac_f32_e32 v105, v104, v104
	v_fmac_f32_e32 v107, v106, v106
	v_add_f32_e32 v104, v109, v111
	v_add_f32_e32 v105, v105, v107
	v_add_f32_e32 v108, v104, v105
	s_waitcnt vmcnt(1)
	v_pk_add_f32 v[102:103], v[102:103], v[118:119]
	v_pk_add_f32 v[100:101], v[100:101], v[116:117]
	s_waitcnt vmcnt(0)
	v_pk_add_f32 v[106:107], v[98:99], v[124:125]
	v_pk_add_f32 v[104:105], v[96:97], v[122:123]
	v_mul_f32_e32 v96, v101, v101
	v_mul_f32_e32 v97, v103, v103
	v_mul_f32_e32 v98, v105, v105
	v_mul_f32_e32 v99, v107, v107
	v_fmac_f32_e32 v96, v100, v100
	v_fmac_f32_e32 v97, v102, v102
	v_fmac_f32_e32 v98, v104, v104
	v_fmac_f32_e32 v99, v106, v106
	v_add_f32_e32 v96, v96, v97
	v_add_f32_e32 v97, v98, v99
	v_add_f32_e32 v96, v96, v97
	v_add_f32_e32 v96, v108, v96
	ds_bpermute_b32 v97, v120, v96
	v_lshl_add_u64 v[228:229], v[156:157], 0, v[230:231]
	v_lshl_add_u64 v[232:233], v[156:157], 0, v[244:245]
	s_nop 1
	v_mov_b32_dpp v236, v104 row_ror:8 row_mask:0xf bank_mask:0xf
	v_mov_b32_dpp v237, v105 row_ror:8 row_mask:0xf bank_mask:0xf
	v_mov_b32_dpp v238, v106 row_ror:8 row_mask:0xf bank_mask:0xf
	v_mov_b32_dpp v239, v107 row_ror:8 row_mask:0xf bank_mask:0xf
	v_mov_b32_dpp v240, v100 row_ror:8 row_mask:0xf bank_mask:0xf
	v_mov_b32_dpp v241, v101 row_ror:8 row_mask:0xf bank_mask:0xf
	v_mov_b32_dpp v242, v102 row_ror:8 row_mask:0xf bank_mask:0xf
	v_mov_b32_dpp v243, v103 row_ror:8 row_mask:0xf bank_mask:0xf
	s_nop 0
	v_cndmask_b32_e64 v236, v236, v100, s[98:99]
	v_cndmask_b32_e64 v237, v237, v101, s[98:99]
	v_cndmask_b32_e64 v238, v238, v102, s[98:99]
	v_cndmask_b32_e64 v239, v239, v103, s[98:99]
	v_cndmask_b32_e64 v240, v104, v240, s[98:99]
	v_cndmask_b32_e64 v241, v105, v241, s[98:99]
	v_cndmask_b32_e64 v242, v106, v242, s[98:99]
	v_cndmask_b32_e64 v243, v107, v243, s[98:99]
	global_store_dwordx4 v[228:229], v[236:239], off offset:512
	global_store_dwordx4 v[232:233], v[240:243], off offset:512
	v_cvt_pk_bf16_f32 v98, v100, v101
	v_cvt_pk_bf16_f32 v99, v102, v103
	v_cvt_pk_bf16_f32 v100, v104, v105
	s_waitcnt lgkmcnt(0)
	v_add_f32_e32 v96, v96, v97
	ds_bpermute_b32 v97, v114, v96
	v_cvt_pk_bf16_f32 v101, v106, v107
	global_store_dwordx4 v[126:127], v[98:101], off offset:256
	s_and_saveexec_b64 s[24:25], s[2:3]
	s_cbranch_execz .LBB0_849
	v_readlane_b32 s26, v254, 41
	s_waitcnt lgkmcnt(0)
	v_add_f32_e32 v98, v96, v97
	v_lshlrev_b64 v[96:97], 6, v[112:113]
	v_readlane_b32 s27, v254, 42
	s_lshl_b32 s6, s38, 2
	s_nop 0
	v_lshl_add_u64 v[96:97], s[26:27], 0, v[96:97]
	v_lshl_add_u64 v[96:97], s[22:23], 2, v[96:97]
	v_lshl_add_u64 v[96:97], v[96:97], 0, s[6:7]
	global_store_dword v[96:97], v98, off
; __device__ __forceinline__ unsigned cvt_pk_bf16(float lo, float hi) { const f32x2_t v = {lo, hi}; const bf16x2_t b = __builtin_convertvector(v, bf16x2_t); return __builtin_bit_cast(unsigned, b); }
;     __device__ __forceinline__ void operator()(const f32x4 (&acc)[2][2][4][2], const Unit& u, int wr, int wc, int fr, int fq, const PG8_LAS float*) const {
;     ...
;             for (int m = 0; m < 4; ++m) { const int row = row0 + ai * HALF + m * 16; const size_t off = (size_t)row * ldc + col0; float ss = 0.f;
; #pragma unroll
;                 for (int bj = 0; bj < 2; ++bj) {
;                     const f32x4 b0 = *(const f32x4*)(base + off + bj * HALF), b1 = *(const f32x4*)(base + off + bj * HALF + 4);
;                     const f32x4 v0 = b0 + acc[ai][bj][m][0], v1 = b1 + acc[ai][bj][m][1];
;                     *(f32x4*)(out + off + bj * HALF) = v0; *(f32x4*)(out + off + bj * HALF + 4) = v1;
;                     if (xb) { u32x4 w; w.x = cvt_pk_bf16(v0[0], v0[1]); w.y = cvt_pk_bf16(v0[2], v0[3]); w.z = cvt_pk_bf16(v1[0], v1[1]); w.w = cvt_pk_bf16(v1[2], v1[3]);
;                         *(u32x4*)(xb + off + bj * HALF) = w;
;                         ss += ((v0[0] * v0[0] + v0[1] * v0[1]) + (v0[2] * v0[2] + v0[3] * v0[3])) + ((v1[0] * v1[0] + v1[1] * v1[1]) + (v1[2] * v1[2] + v1[3] * v1[3])); } }
;                 if (xb) { ss += __shfl_xor(ss, 16); ss += __shfl_xor(ss, 32); if (fq == 0) ssq[(size_t)row * 16 + u.pn * 4 + wc] = ss; } }
.LBB0_849:
	s_or_b64 exec, exec, s[24:25]
	v_or_b32_e32 v96, 32, v146
	s_waitcnt lgkmcnt(0)
	v_ashrrev_i32_e32 v97, 31, v96
	v_lshlrev_b64 v[98:99], 10, v[96:97]
	v_lshl_add_u64 v[106:107], v[98:99], 0, v[144:145]
	v_lshl_add_u64 v[108:109], v[106:107], 2, s[68:69]
	global_load_dwordx4 v[98:101], v[108:109], off
	global_load_dwordx4 v[102:105], v[108:109], off offset:16
	v_readlane_b32 s24, v254, 39
	v_readlane_b32 s25, v254, 40
	s_waitcnt vmcnt(1)
	v_pk_add_f32 v[94:95], v[94:95], v[100:101]
	v_pk_add_f32 v[92:93], v[92:93], v[98:99]
	s_waitcnt vmcnt(0)
	v_pk_add_f32 v[90:91], v[90:91], v[104:105]
	v_pk_add_f32 v[88:89], v[88:89], v[102:103]
	v_lshl_add_u64 v[106:107], v[106:107], 1, s[24:25]
	v_cvt_pk_bf16_f32 v98, v92, v93
	v_cvt_pk_bf16_f32 v99, v94, v95
	v_cvt_pk_bf16_f32 v100, v88, v89
	v_cvt_pk_bf16_f32 v101, v90, v91
	v_lshl_add_u64 v[228:229], v[108:109], 0, v[230:231]
	v_lshl_add_u64 v[232:233], v[108:109], 0, v[244:245]
	s_nop 1
	v_mov_b32_dpp v236, v88 row_ror:8 row_mask:0xf bank_mask:0xf
	v_mov_b32_dpp v237, v89 row_ror:8 row_mask:0xf bank_mask:0xf
	v_mov_b32_dpp v238, v90 row_ror:8 row_mask:0xf bank_mask:0xf
	v_mov_b32_dpp v239, v91 row_ror:8 row_mask:0xf bank_mask:0xf
	v_mov_b32_dpp v240, v92 row_ror:8 row_mask:0xf bank_mask:0xf
	v_mov_b32_dpp v241, v93 row_ror:8 row_mask:0xf bank_mask:0xf
	v_mov_b32_dpp v242, v94 row_ror:8 row_mask:0xf bank_mask:0xf
	v_mov_b32_dpp v243, v95 row_ror:8 row_mask:0xf bank_mask:0xf
	s_nop 0
	v_cndmask_b32_e64 v236, v236, v92, s[98:99]
	v_cndmask_b32_e64 v237, v237, v93, s[98:99]
	v_cndmask_b32_e64 v238, v238, v94, s[98:99]
	v_cndmask_b32_e64 v239, v239, v95, s[98:99]
	v_cndmask_b32_e64 v240, v88, v240, s[98:99]
	v_cndmask_b32_e64 v241, v89, v241, s[98:99]
	v_cndmask_b32_e64 v242, v90, v242, s[98:99]
	v_cndmask_b32_e64 v243, v91, v243, s[98:99]
	global_store_dwordx4 v[228:229], v[236:239], off
	global_store_dwordx4 v[232:233], v[240:243], off
	global_store_dwordx4 v[106:107], v[98:101], off
	global_load_dwordx4 v[98:101], v[108:109], off offset:512
	s_nop 0
	global_load_dwordx4 v[102:105], v[108:109], off offset:528
	v_mul_f32_e32 v93, v93, v93
	v_mul_f32_e32 v95, v95, v95
	v_mul_f32_e32 v89, v89, v89
	v_mul_f32_e32 v91, v91, v91
	v_fmac_f32_e32 v93, v92, v92
	v_fmac_f32_e32 v95, v94, v94
	v_fmac_f32_e32 v89, v88, v88
	v_fmac_f32_e32 v91, v90, v90
	v_add_f32_e32 v88, v93, v95
	v_add_f32_e32 v89, v89, v91
	v_add_f32_e32 v92, v88, v89
	s_waitcnt vmcnt(1)
	v_pk_add_f32 v[86:87], v[86:87], v[100:101]
	v_pk_add_f32 v[84:85], v[84:85], v[98:99]
	s_waitcnt vmcnt(0)
	v_pk_add_f32 v[90:91], v[82:83], v[104:105]
	v_pk_add_f32 v[88:89], v[80:81], v[102:103]
	v_mul_f32_e32 v80, v85, v85
	v_mul_f32_e32 v81, v87, v87
	v_mul_f32_e32 v82, v89, v89
	v_mul_f32_e32 v83, v91, v91
	v_fmac_f32_e32 v80, v84, v84
	v_fmac_f32_e32 v81, v86, v86
	v_fmac_f32_e32 v82, v88, v88
	v_fmac_f32_e32 v83, v90, v90
	v_add_f32_e32 v80, v80, v81
	v_add_f32_e32 v81, v82, v83
	v_add_f32_e32 v80, v80, v81
	v_add_f32_e32 v80, v92, v80
	ds_bpermute_b32 v81, v120, v80
	v_lshl_add_u64 v[228:229], v[108:109], 0, v[230:231]
	v_lshl_add_u64 v[232:233], v[108:109], 0, v[244:245]
	s_nop 1
	v_mov_b32_dpp v236, v88 row_ror:8 row_mask:0xf bank_mask:0xf
	v_mov_b32_dpp v237, v89 row_ror:8 row_mask:0xf bank_mask:0xf
	v_mov_b32_dpp v238, v90 row_ror:8 row_mask:0xf bank_mask:0xf
	v_mov_b32_dpp v239, v91 row_ror:8 row_mask:0xf bank_mask:0xf
	v_mov_b32_dpp v240, v84 row_ror:8 row_mask:0xf bank_mask:0xf
	v_mov_b32_dpp v241, v85 row_ror:8 row_mask:0xf bank_mask:0xf
	v_mov_b32_dpp v242, v86 row_ror:8 row_mask:0xf bank_mask:0xf
	v_mov_b32_dpp v243, v87 row_ror:8 row_mask:0xf bank_mask:0xf
	s_nop 0
	v_cndmask_b32_e64 v236, v236, v84, s[98:99]
	v_cndmask_b32_e64 v237, v237, v85, s[98:99]
	v_cndmask_b32_e64 v238, v238, v86, s[98:99]
	v_cndmask_b32_e64 v239, v239, v87, s[98:99]
	v_cndmask_b32_e64 v240, v88, v240, s[98:99]
	v_cndmask_b32_e64 v241, v89, v241, s[98:99]
	v_cndmask_b32_e64 v242, v90, v242, s[98:99]
	v_cndmask_b32_e64 v243, v91, v243, s[98:99]
	global_store_dwordx4 v[228:229], v[236:239], off offset:512
	global_store_dwordx4 v[232:233], v[240:243], off offset:512
	v_cvt_pk_bf16_f32 v82, v84, v85
	v_cvt_pk_bf16_f32 v83, v86, v87
	v_cvt_pk_bf16_f32 v84, v88, v89
	s_waitcnt lgkmcnt(0)
	v_add_f32_e32 v80, v80, v81
	ds_bpermute_b32 v81, v114, v80
	v_cvt_pk_bf16_f32 v85, v90, v91
	global_store_dwordx4 v[106:107], v[82:85], off offset:256
	s_and_saveexec_b64 s[24:25], s[2:3]
	s_cbranch_execz .LBB0_851
	v_readlane_b32 s26, v254, 41
	s_waitcnt lgkmcnt(0)
	v_add_f32_e32 v82, v80, v81
	v_lshlrev_b64 v[80:81], 6, v[96:97]
	v_readlane_b32 s27, v254, 42
	s_lshl_b32 s6, s38, 2
	s_nop 0
	v_lshl_add_u64 v[80:81], s[26:27], 0, v[80:81]
	v_lshl_add_u64 v[80:81], s[22:23], 2, v[80:81]
	v_lshl_add_u64 v[80:81], v[80:81], 0, s[6:7]
	global_store_dword v[80:81], v82, off
; __device__ __forceinline__ unsigned cvt_pk_bf16(float lo, float hi) { const f32x2_t v = {lo, hi}; const bf16x2_t b = __builtin_convertvector(v, bf16x2_t); return __builtin_bit_cast(unsigned, b); }
;     __device__ __forceinline__ void operator()(const f32x4 (&acc)[2][2][4][2], const Unit& u, int wr, int wc, int fr, int fq, const PG8_LAS float*) const {
;     ...
;             for (int m = 0; m < 4; ++m) { const int row = row0 + ai * HALF + m * 16; const size_t off = (size_t)row * ldc + col0; float ss = 0.f;
; #pragma unroll
;                 for (int bj = 0; bj < 2; ++bj) {
;                     const f32x4 b0 = *(const f32x4*)(base + off + bj * HALF), b1 = *(const f32x4*)(base + off + bj * HALF + 4);
;                     const f32x4 v0 = b0 + acc[ai][bj][m][0], v1 = b1 + acc[ai][bj][m][1];
;                     *(f32x4*)(out + off + bj * HALF) = v0; *(f32x4*)(out + off + bj * HALF + 4) = v1;
;                     if (xb) { u32x4 w; w.x = cvt_pk_bf16(v0[0], v0[1]); w.y = cvt_pk_bf16(v0[2], v0[3]); w.z = cvt_pk_bf16(v1[0], v1[1]); w.w = cvt_pk_bf16(v1[2], v1[3]);
;                         *(u32x4*)(xb + off + bj * HALF) = w;
;                         ss += ((v0[0] * v0[0] + v0[1] * v0[1]) + (v0[2] * v0[2] + v0[3] * v0[3])) + ((v1[0] * v1[0] + v1[1] * v1[1]) + (v1[2] * v1[2] + v1[3] * v1[3])); } }
;                 if (xb) { ss += __shfl_xor(ss, 16); ss += __shfl_xor(ss, 32); if (fq == 0) ssq[(size_t)row * 16 + u.pn * 4 + wc] = ss; } }
.LBB0_851:
	s_or_b64 exec, exec, s[24:25]
	v_or_b32_e32 v80, 48, v146
	s_waitcnt lgkmcnt(0)
	v_ashrrev_i32_e32 v81, 31, v80
	v_lshlrev_b64 v[82:83], 10, v[80:81]
	v_lshl_add_u64 v[90:91], v[82:83], 0, v[144:145]
	v_lshl_add_u64 v[92:93], v[90:91], 2, s[68:69]
	global_load_dwordx4 v[82:85], v[92:93], off
	global_load_dwordx4 v[86:89], v[92:93], off offset:16
	v_readlane_b32 s24, v254, 39
	v_readlane_b32 s25, v254, 40
	s_waitcnt vmcnt(1)
	v_pk_add_f32 v[78:79], v[78:79], v[84:85]
	v_pk_add_f32 v[76:77], v[76:77], v[82:83]
	s_waitcnt vmcnt(0)
	v_pk_add_f32 v[74:75], v[74:75], v[88:89]
	v_pk_add_f32 v[72:73], v[72:73], v[86:87]
	v_lshl_add_u64 v[90:91], v[90:91], 1, s[24:25]
	v_cvt_pk_bf16_f32 v82, v76, v77
	v_cvt_pk_bf16_f32 v83, v78, v79
	v_cvt_pk_bf16_f32 v84, v72, v73
	v_cvt_pk_bf16_f32 v85, v74, v75
	v_lshl_add_u64 v[228:229], v[92:93], 0, v[230:231]
	v_lshl_add_u64 v[232:233], v[92:93], 0, v[244:245]
	s_nop 1
	v_mov_b32_dpp v236, v72 row_ror:8 row_mask:0xf bank_mask:0xf
	v_mov_b32_dpp v237, v73 row_ror:8 row_mask:0xf bank_mask:0xf
	v_mov_b32_dpp v238, v74 row_ror:8 row_mask:0xf bank_mask:0xf
	v_mov_b32_dpp v239, v75 row_ror:8 row_mask:0xf bank_mask:0xf
	v_mov_b32_dpp v240, v76 row_ror:8 row_mask:0xf bank_mask:0xf
	v_mov_b32_dpp v241, v77 row_ror:8 row_mask:0xf bank_mask:0xf
	v_mov_b32_dpp v242, v78 row_ror:8 row_mask:0xf bank_mask:0xf
	v_mov_b32_dpp v243, v79 row_ror:8 row_mask:0xf bank_mask:0xf
	s_nop 0
	v_cndmask_b32_e64 v236, v236, v76, s[98:99]
	v_cndmask_b32_e64 v237, v237, v77, s[98:99]
	v_cndmask_b32_e64 v238, v238, v78, s[98:99]
	v_cndmask_b32_e64 v239, v239, v79, s[98:99]
	v_cndmask_b32_e64 v240, v72, v240, s[98:99]
	v_cndmask_b32_e64 v241, v73, v241, s[98:99]
	v_cndmask_b32_e64 v242, v74, v242, s[98:99]
	v_cndmask_b32_e64 v243, v75, v243, s[98:99]
	global_store_dwordx4 v[228:229], v[236:239], off
	global_store_dwordx4 v[232:233], v[240:243], off
	global_store_dwordx4 v[90:91], v[82:85], off
	global_load_dwordx4 v[82:85], v[92:93], off offset:512
	s_nop 0
	global_load_dwordx4 v[86:89], v[92:93], off offset:528
	v_mul_f32_e32 v77, v77, v77
	v_mul_f32_e32 v79, v79, v79
	v_mul_f32_e32 v73, v73, v73
	v_mul_f32_e32 v75, v75, v75
	v_fmac_f32_e32 v77, v76, v76
	v_fmac_f32_e32 v79, v78, v78
	v_fmac_f32_e32 v73, v72, v72
	v_fmac_f32_e32 v75, v74, v74
	v_add_f32_e32 v72, v77, v79
	v_add_f32_e32 v73, v73, v75
	v_add_f32_e32 v76, v72, v73
	s_waitcnt vmcnt(1)
	v_pk_add_f32 v[70:71], v[70:71], v[84:85]
	v_pk_add_f32 v[68:69], v[68:69], v[82:83]
	s_waitcnt vmcnt(0)
	v_pk_add_f32 v[74:75], v[66:67], v[88:89]
	v_pk_add_f32 v[72:73], v[64:65], v[86:87]
	v_mul_f32_e32 v64, v69, v69
	v_mul_f32_e32 v65, v71, v71
	v_mul_f32_e32 v66, v73, v73
	v_mul_f32_e32 v67, v75, v75
	v_fmac_f32_e32 v64, v68, v68
	v_fmac_f32_e32 v65, v70, v70
	v_fmac_f32_e32 v66, v72, v72
	v_fmac_f32_e32 v67, v74, v74
	v_add_f32_e32 v64, v64, v65
	v_add_f32_e32 v65, v66, v67
	v_add_f32_e32 v64, v64, v65
	v_add_f32_e32 v64, v76, v64
	ds_bpermute_b32 v65, v120, v64
	v_lshl_add_u64 v[228:229], v[92:93], 0, v[230:231]
	v_lshl_add_u64 v[232:233], v[92:93], 0, v[244:245]
	s_nop 1
	v_mov_b32_dpp v236, v72 row_ror:8 row_mask:0xf bank_mask:0xf
	v_mov_b32_dpp v237, v73 row_ror:8 row_mask:0xf bank_mask:0xf
	v_mov_b32_dpp v238, v74 row_ror:8 row_mask:0xf bank_mask:0xf
	v_mov_b32_dpp v239, v75 row_ror:8 row_mask:0xf bank_mask:0xf
	v_mov_b32_dpp v240, v68 row_ror:8 row_mask:0xf bank_mask:0xf
	v_mov_b32_dpp v241, v69 row_ror:8 row_mask:0xf bank_mask:0xf
	v_mov_b32_dpp v242, v70 row_ror:8 row_mask:0xf bank_mask:0xf
	v_mov_b32_dpp v243, v71 row_ror:8 row_mask:0xf bank_mask:0xf
	s_nop 0
	v_cndmask_b32_e64 v236, v236, v68, s[98:99]
	v_cndmask_b32_e64 v237, v237, v69, s[98:99]
	v_cndmask_b32_e64 v238, v238, v70, s[98:99]
	v_cndmask_b32_e64 v239, v239, v71, s[98:99]
	v_cndmask_b32_e64 v240, v72, v240, s[98:99]
	v_cndmask_b32_e64 v241, v73, v241, s[98:99]
	v_cndmask_b32_e64 v242, v74, v242, s[98:99]
	v_cndmask_b32_e64 v243, v75, v243, s[98:99]
	global_store_dwordx4 v[228:229], v[236:239], off offset:512
	global_store_dwordx4 v[232:233], v[240:243], off offset:512
	v_cvt_pk_bf16_f32 v66, v68, v69
	v_cvt_pk_bf16_f32 v67, v70, v71
	v_cvt_pk_bf16_f32 v68, v72, v73
	s_waitcnt lgkmcnt(0)
	v_add_f32_e32 v64, v64, v65
	ds_bpermute_b32 v65, v114, v64
	v_cvt_pk_bf16_f32 v69, v74, v75
	global_store_dwordx4 v[90:91], v[66:69], off offset:256
	s_and_saveexec_b64 s[24:25], s[2:3]
	s_cbranch_execz .LBB0_853
	v_readlane_b32 s26, v254, 41
	s_waitcnt lgkmcnt(0)
	v_add_f32_e32 v66, v64, v65
	v_lshlrev_b64 v[64:65], 6, v[80:81]
	v_readlane_b32 s27, v254, 42
	s_lshl_b32 s6, s38, 2
	s_nop 0
	v_lshl_add_u64 v[64:65], s[26:27], 0, v[64:65]
	v_lshl_add_u64 v[64:65], s[22:23], 2, v[64:65]
	v_lshl_add_u64 v[64:65], v[64:65], 0, s[6:7]
	global_store_dword v[64:65], v66, off
; __device__ __forceinline__ unsigned cvt_pk_bf16(float lo, float hi) { const f32x2_t v = {lo, hi}; const bf16x2_t b = __builtin_convertvector(v, bf16x2_t); return __builtin_bit_cast(unsigned, b); }
;     __device__ __forceinline__ void operator()(const f32x4 (&acc)[2][2][4][2], const Unit& u, int wr, int wc, int fr, int fq, const PG8_LAS float*) const {
;     ...
;             for (int m = 0; m < 4; ++m) { const int row = row0 + ai * HALF + m * 16; const size_t off = (size_t)row * ldc + col0; float ss = 0.f;
; #pragma unroll
;                 for (int bj = 0; bj < 2; ++bj) {
;                     const f32x4 b0 = *(const f32x4*)(base + off + bj * HALF), b1 = *(const f32x4*)(base + off + bj * HALF + 4);
;                     const f32x4 v0 = b0 + acc[ai][bj][m][0], v1 = b1 + acc[ai][bj][m][1];
;                     *(f32x4*)(out + off + bj * HALF) = v0; *(f32x4*)(out + off + bj * HALF + 4) = v1;
;                     if (xb) { u32x4 w; w.x = cvt_pk_bf16(v0[0], v0[1]); w.y = cvt_pk_bf16(v0[2], v0[3]); w.z = cvt_pk_bf16(v1[0], v1[1]); w.w = cvt_pk_bf16(v1[2], v1[3]);
;                         *(u32x4*)(xb + off + bj * HALF) = w;
;                         ss += ((v0[0] * v0[0] + v0[1] * v0[1]) + (v0[2] * v0[2] + v0[3] * v0[3])) + ((v1[0] * v1[0] + v1[1] * v1[1]) + (v1[2] * v1[2] + v1[3] * v1[3])); } }
;                 if (xb) { ss += __shfl_xor(ss, 16); ss += __shfl_xor(ss, 32); if (fq == 0) ssq[(size_t)row * 16 + u.pn * 4 + wc] = ss; } }
.LBB0_853:
	s_or_b64 exec, exec, s[24:25]
	v_add_u32_e32 v64, 0x80, v146
	s_waitcnt lgkmcnt(0)
	v_ashrrev_i32_e32 v65, 31, v64
	v_lshlrev_b64 v[66:67], 10, v[64:65]
	v_lshl_add_u64 v[74:75], v[66:67], 0, v[144:145]
	v_lshl_add_u64 v[76:77], v[74:75], 2, s[68:69]
	global_load_dwordx4 v[66:69], v[76:77], off
	global_load_dwordx4 v[70:73], v[76:77], off offset:16
	v_readlane_b32 s24, v254, 39
	v_readlane_b32 s25, v254, 40
	s_waitcnt vmcnt(1)
	v_pk_add_f32 v[62:63], v[62:63], v[68:69]
	v_pk_add_f32 v[60:61], v[60:61], v[66:67]
	s_waitcnt vmcnt(0)
	v_pk_add_f32 v[58:59], v[58:59], v[72:73]
	v_pk_add_f32 v[56:57], v[56:57], v[70:71]
	v_lshl_add_u64 v[74:75], v[74:75], 1, s[24:25]
	v_cvt_pk_bf16_f32 v66, v60, v61
	v_cvt_pk_bf16_f32 v67, v62, v63
	v_cvt_pk_bf16_f32 v68, v56, v57
	v_cvt_pk_bf16_f32 v69, v58, v59
	v_lshl_add_u64 v[228:229], v[76:77], 0, v[230:231]
	v_lshl_add_u64 v[232:233], v[76:77], 0, v[244:245]
	s_nop 1
	v_mov_b32_dpp v236, v56 row_ror:8 row_mask:0xf bank_mask:0xf
	v_mov_b32_dpp v237, v57 row_ror:8 row_mask:0xf bank_mask:0xf
	v_mov_b32_dpp v238, v58 row_ror:8 row_mask:0xf bank_mask:0xf
	v_mov_b32_dpp v239, v59 row_ror:8 row_mask:0xf bank_mask:0xf
	v_mov_b32_dpp v240, v60 row_ror:8 row_mask:0xf bank_mask:0xf
	v_mov_b32_dpp v241, v61 row_ror:8 row_mask:0xf bank_mask:0xf
	v_mov_b32_dpp v242, v62 row_ror:8 row_mask:0xf bank_mask:0xf
	v_mov_b32_dpp v243, v63 row_ror:8 row_mask:0xf bank_mask:0xf
	s_nop 0
	v_cndmask_b32_e64 v236, v236, v60, s[98:99]
	v_cndmask_b32_e64 v237, v237, v61, s[98:99]
	v_cndmask_b32_e64 v238, v238, v62, s[98:99]
	v_cndmask_b32_e64 v239, v239, v63, s[98:99]
	v_cndmask_b32_e64 v240, v56, v240, s[98:99]
	v_cndmask_b32_e64 v241, v57, v241, s[98:99]
	v_cndmask_b32_e64 v242, v58, v242, s[98:99]
	v_cndmask_b32_e64 v243, v59, v243, s[98:99]
	global_store_dwordx4 v[228:229], v[236:239], off
	global_store_dwordx4 v[232:233], v[240:243], off
	global_store_dwordx4 v[74:75], v[66:69], off
	global_load_dwordx4 v[66:69], v[76:77], off offset:512
	s_nop 0
	global_load_dwordx4 v[70:73], v[76:77], off offset:528
	v_mul_f32_e32 v61, v61, v61
	v_mul_f32_e32 v63, v63, v63
	v_mul_f32_e32 v57, v57, v57
	v_mul_f32_e32 v59, v59, v59
	v_fmac_f32_e32 v61, v60, v60
	v_fmac_f32_e32 v63, v62, v62
	v_fmac_f32_e32 v57, v56, v56
	v_fmac_f32_e32 v59, v58, v58
	v_add_f32_e32 v56, v61, v63
	v_add_f32_e32 v57, v57, v59
	v_add_f32_e32 v60, v56, v57
	s_waitcnt vmcnt(1)
	v_pk_add_f32 v[54:55], v[54:55], v[68:69]
	v_pk_add_f32 v[52:53], v[52:53], v[66:67]
	s_waitcnt vmcnt(0)
	v_pk_add_f32 v[58:59], v[50:51], v[72:73]
	v_pk_add_f32 v[56:57], v[48:49], v[70:71]
	v_mul_f32_e32 v48, v53, v53
	v_mul_f32_e32 v49, v55, v55
	v_mul_f32_e32 v50, v57, v57
	v_mul_f32_e32 v51, v59, v59
	v_fmac_f32_e32 v48, v52, v52
	v_fmac_f32_e32 v49, v54, v54
	v_fmac_f32_e32 v50, v56, v56
	v_fmac_f32_e32 v51, v58, v58
	v_add_f32_e32 v48, v48, v49
	v_add_f32_e32 v49, v50, v51
	v_add_f32_e32 v48, v48, v49
	v_add_f32_e32 v48, v60, v48
	ds_bpermute_b32 v49, v120, v48
	v_lshl_add_u64 v[228:229], v[76:77], 0, v[230:231]
	v_lshl_add_u64 v[232:233], v[76:77], 0, v[244:245]
	s_nop 1
	v_mov_b32_dpp v236, v56 row_ror:8 row_mask:0xf bank_mask:0xf
	v_mov_b32_dpp v237, v57 row_ror:8 row_mask:0xf bank_mask:0xf
	v_mov_b32_dpp v238, v58 row_ror:8 row_mask:0xf bank_mask:0xf
	v_mov_b32_dpp v239, v59 row_ror:8 row_mask:0xf bank_mask:0xf
	v_mov_b32_dpp v240, v52 row_ror:8 row_mask:0xf bank_mask:0xf
	v_mov_b32_dpp v241, v53 row_ror:8 row_mask:0xf bank_mask:0xf
	v_mov_b32_dpp v242, v54 row_ror:8 row_mask:0xf bank_mask:0xf
	v_mov_b32_dpp v243, v55 row_ror:8 row_mask:0xf bank_mask:0xf
	s_nop 0
	v_cndmask_b32_e64 v236, v236, v52, s[98:99]
	v_cndmask_b32_e64 v237, v237, v53, s[98:99]
	v_cndmask_b32_e64 v238, v238, v54, s[98:99]
	v_cndmask_b32_e64 v239, v239, v55, s[98:99]
	v_cndmask_b32_e64 v240, v56, v240, s[98:99]
	v_cndmask_b32_e64 v241, v57, v241, s[98:99]
	v_cndmask_b32_e64 v242, v58, v242, s[98:99]
	v_cndmask_b32_e64 v243, v59, v243, s[98:99]
	global_store_dwordx4 v[228:229], v[236:239], off offset:512
	global_store_dwordx4 v[232:233], v[240:243], off offset:512
	v_cvt_pk_bf16_f32 v50, v52, v53
	v_cvt_pk_bf16_f32 v51, v54, v55
	v_cvt_pk_bf16_f32 v52, v56, v57
	s_waitcnt lgkmcnt(0)
	v_add_f32_e32 v48, v48, v49
	ds_bpermute_b32 v49, v114, v48
	v_cvt_pk_bf16_f32 v53, v58, v59
	global_store_dwordx4 v[74:75], v[50:53], off offset:256
	s_and_saveexec_b64 s[24:25], s[2:3]
	s_cbranch_execz .LBB0_855
	v_readlane_b32 s26, v254, 41
	s_waitcnt lgkmcnt(0)
	v_add_f32_e32 v50, v48, v49
	v_lshlrev_b64 v[48:49], 6, v[64:65]
	v_readlane_b32 s27, v254, 42
	s_lshl_b32 s6, s38, 2
	s_nop 0
	v_lshl_add_u64 v[48:49], s[26:27], 0, v[48:49]
	v_lshl_add_u64 v[48:49], s[22:23], 2, v[48:49]
	v_lshl_add_u64 v[48:49], v[48:49], 0, s[6:7]
	global_store_dword v[48:49], v50, off
; __device__ __forceinline__ unsigned cvt_pk_bf16(float lo, float hi) { const f32x2_t v = {lo, hi}; const bf16x2_t b = __builtin_convertvector(v, bf16x2_t); return __builtin_bit_cast(unsigned, b); }
;     __device__ __forceinline__ void operator()(const f32x4 (&acc)[2][2][4][2], const Unit& u, int wr, int wc, int fr, int fq, const PG8_LAS float*) const {
;     ...
;             for (int m = 0; m < 4; ++m) { const int row = row0 + ai * HALF + m * 16; const size_t off = (size_t)row * ldc + col0; float ss = 0.f;
; #pragma unroll
;                 for (int bj = 0; bj < 2; ++bj) {
;                     const f32x4 b0 = *(const f32x4*)(base + off + bj * HALF), b1 = *(const f32x4*)(base + off + bj * HALF + 4);
;                     const f32x4 v0 = b0 + acc[ai][bj][m][0], v1 = b1 + acc[ai][bj][m][1];
;                     *(f32x4*)(out + off + bj * HALF) = v0; *(f32x4*)(out + off + bj * HALF + 4) = v1;
;                     if (xb) { u32x4 w; w.x = cvt_pk_bf16(v0[0], v0[1]); w.y = cvt_pk_bf16(v0[2], v0[3]); w.z = cvt_pk_bf16(v1[0], v1[1]); w.w = cvt_pk_bf16(v1[2], v1[3]);
;                         *(u32x4*)(xb + off + bj * HALF) = w;
;                         ss += ((v0[0] * v0[0] + v0[1] * v0[1]) + (v0[2] * v0[2] + v0[3] * v0[3])) + ((v1[0] * v1[0] + v1[1] * v1[1]) + (v1[2] * v1[2] + v1[3] * v1[3])); } }
;                 if (xb) { ss += __shfl_xor(ss, 16); ss += __shfl_xor(ss, 32); if (fq == 0) ssq[(size_t)row * 16 + u.pn * 4 + wc] = ss; } }
.LBB0_855:
	s_or_b64 exec, exec, s[24:25]
	v_add_u32_e32 v48, 0x90, v146
	s_waitcnt lgkmcnt(0)
	v_ashrrev_i32_e32 v49, 31, v48
	v_lshlrev_b64 v[50:51], 10, v[48:49]
	v_lshl_add_u64 v[58:59], v[50:51], 0, v[144:145]
	v_lshl_add_u64 v[60:61], v[58:59], 2, s[68:69]
	global_load_dwordx4 v[50:53], v[60:61], off
	global_load_dwordx4 v[54:57], v[60:61], off offset:16
	v_readlane_b32 s24, v254, 39
	v_readlane_b32 s25, v254, 40
	s_waitcnt vmcnt(1)
	v_pk_add_f32 v[46:47], v[46:47], v[52:53]
	v_pk_add_f32 v[44:45], v[44:45], v[50:51]
	s_waitcnt vmcnt(0)
	v_pk_add_f32 v[42:43], v[42:43], v[56:57]
	v_pk_add_f32 v[40:41], v[40:41], v[54:55]
	v_lshl_add_u64 v[58:59], v[58:59], 1, s[24:25]
	v_cvt_pk_bf16_f32 v50, v44, v45
	v_cvt_pk_bf16_f32 v51, v46, v47
	v_cvt_pk_bf16_f32 v52, v40, v41
	v_cvt_pk_bf16_f32 v53, v42, v43
	v_lshl_add_u64 v[228:229], v[60:61], 0, v[230:231]
	v_lshl_add_u64 v[232:233], v[60:61], 0, v[244:245]
	s_nop 1
	v_mov_b32_dpp v236, v40 row_ror:8 row_mask:0xf bank_mask:0xf
	v_mov_b32_dpp v237, v41 row_ror:8 row_mask:0xf bank_mask:0xf
	v_mov_b32_dpp v238, v42 row_ror:8 row_mask:0xf bank_mask:0xf
	v_mov_b32_dpp v239, v43 row_ror:8 row_mask:0xf bank_mask:0xf
	v_mov_b32_dpp v240, v44 row_ror:8 row_mask:0xf bank_mask:0xf
	v_mov_b32_dpp v241, v45 row_ror:8 row_mask:0xf bank_mask:0xf
	v_mov_b32_dpp v242, v46 row_ror:8 row_mask:0xf bank_mask:0xf
	v_mov_b32_dpp v243, v47 row_ror:8 row_mask:0xf bank_mask:0xf
	s_nop 0
	v_cndmask_b32_e64 v236, v236, v44, s[98:99]
	v_cndmask_b32_e64 v237, v237, v45, s[98:99]
	v_cndmask_b32_e64 v238, v238, v46, s[98:99]
	v_cndmask_b32_e64 v239, v239, v47, s[98:99]
	v_cndmask_b32_e64 v240, v40, v240, s[98:99]
	v_cndmask_b32_e64 v241, v41, v241, s[98:99]
	v_cndmask_b32_e64 v242, v42, v242, s[98:99]
	v_cndmask_b32_e64 v243, v43, v243, s[98:99]
	global_store_dwordx4 v[228:229], v[236:239], off
	global_store_dwordx4 v[232:233], v[240:243], off
	global_store_dwordx4 v[58:59], v[50:53], off
	global_load_dwordx4 v[50:53], v[60:61], off offset:512
	s_nop 0
	global_load_dwordx4 v[54:57], v[60:61], off offset:528
	v_mul_f32_e32 v45, v45, v45
	v_mul_f32_e32 v47, v47, v47
	v_mul_f32_e32 v41, v41, v41
	v_mul_f32_e32 v43, v43, v43
	v_fmac_f32_e32 v45, v44, v44
	v_fmac_f32_e32 v47, v46, v46
	v_fmac_f32_e32 v41, v40, v40
	v_fmac_f32_e32 v43, v42, v42
	v_add_f32_e32 v40, v45, v47
	v_add_f32_e32 v41, v41, v43
	v_add_f32_e32 v44, v40, v41
	s_waitcnt vmcnt(1)
	v_pk_add_f32 v[38:39], v[38:39], v[52:53]
	v_pk_add_f32 v[36:37], v[36:37], v[50:51]
	s_waitcnt vmcnt(0)
	v_pk_add_f32 v[42:43], v[34:35], v[56:57]
	v_pk_add_f32 v[40:41], v[32:33], v[54:55]
	v_mul_f32_e32 v32, v37, v37
	v_mul_f32_e32 v33, v39, v39
	v_mul_f32_e32 v34, v41, v41
	v_mul_f32_e32 v35, v43, v43
	v_fmac_f32_e32 v32, v36, v36
	v_fmac_f32_e32 v33, v38, v38
	v_fmac_f32_e32 v34, v40, v40
	v_fmac_f32_e32 v35, v42, v42
	v_add_f32_e32 v32, v32, v33
	v_add_f32_e32 v33, v34, v35
	v_add_f32_e32 v32, v32, v33
	v_add_f32_e32 v32, v44, v32
	ds_bpermute_b32 v33, v120, v32
	v_lshl_add_u64 v[228:229], v[60:61], 0, v[230:231]
	v_lshl_add_u64 v[232:233], v[60:61], 0, v[244:245]
	s_nop 1
	v_mov_b32_dpp v236, v40 row_ror:8 row_mask:0xf bank_mask:0xf
	v_mov_b32_dpp v237, v41 row_ror:8 row_mask:0xf bank_mask:0xf
	v_mov_b32_dpp v238, v42 row_ror:8 row_mask:0xf bank_mask:0xf
	v_mov_b32_dpp v239, v43 row_ror:8 row_mask:0xf bank_mask:0xf
	v_mov_b32_dpp v240, v36 row_ror:8 row_mask:0xf bank_mask:0xf
	v_mov_b32_dpp v241, v37 row_ror:8 row_mask:0xf bank_mask:0xf
	v_mov_b32_dpp v242, v38 row_ror:8 row_mask:0xf bank_mask:0xf
	v_mov_b32_dpp v243, v39 row_ror:8 row_mask:0xf bank_mask:0xf
	s_nop 0
	v_cndmask_b32_e64 v236, v236, v36, s[98:99]
	v_cndmask_b32_e64 v237, v237, v37, s[98:99]
	v_cndmask_b32_e64 v238, v238, v38, s[98:99]
	v_cndmask_b32_e64 v239, v239, v39, s[98:99]
	v_cndmask_b32_e64 v240, v40, v240, s[98:99]
	v_cndmask_b32_e64 v241, v41, v241, s[98:99]
	v_cndmask_b32_e64 v242, v42, v242, s[98:99]
	v_cndmask_b32_e64 v243, v43, v243, s[98:99]
	global_store_dwordx4 v[228:229], v[236:239], off offset:512
	global_store_dwordx4 v[232:233], v[240:243], off offset:512
	v_cvt_pk_bf16_f32 v34, v36, v37
	v_cvt_pk_bf16_f32 v35, v38, v39
	v_cvt_pk_bf16_f32 v36, v40, v41
	s_waitcnt lgkmcnt(0)
	v_add_f32_e32 v32, v32, v33
	ds_bpermute_b32 v33, v114, v32
	v_cvt_pk_bf16_f32 v37, v42, v43
	global_store_dwordx4 v[58:59], v[34:37], off offset:256
	s_and_saveexec_b64 s[24:25], s[2:3]
	s_cbranch_execz .LBB0_857
	v_readlane_b32 s26, v254, 41
	s_waitcnt lgkmcnt(0)
	v_add_f32_e32 v34, v32, v33
	v_lshlrev_b64 v[32:33], 6, v[48:49]
	v_readlane_b32 s27, v254, 42
	s_lshl_b32 s6, s38, 2
	s_nop 0
	v_lshl_add_u64 v[32:33], s[26:27], 0, v[32:33]
	v_lshl_add_u64 v[32:33], s[22:23], 2, v[32:33]
	v_lshl_add_u64 v[32:33], v[32:33], 0, s[6:7]
	global_store_dword v[32:33], v34, off
; __device__ __forceinline__ unsigned cvt_pk_bf16(float lo, float hi) { const f32x2_t v = {lo, hi}; const bf16x2_t b = __builtin_convertvector(v, bf16x2_t); return __builtin_bit_cast(unsigned, b); }
;     __device__ __forceinline__ void operator()(const f32x4 (&acc)[2][2][4][2], const Unit& u, int wr, int wc, int fr, int fq, const PG8_LAS float*) const {
;     ...
;             for (int m = 0; m < 4; ++m) { const int row = row0 + ai * HALF + m * 16; const size_t off = (size_t)row * ldc + col0; float ss = 0.f;
; #pragma unroll
;                 for (int bj = 0; bj < 2; ++bj) {
;                     const f32x4 b0 = *(const f32x4*)(base + off + bj * HALF), b1 = *(const f32x4*)(base + off + bj * HALF + 4);
;                     const f32x4 v0 = b0 + acc[ai][bj][m][0], v1 = b1 + acc[ai][bj][m][1];
;                     *(f32x4*)(out + off + bj * HALF) = v0; *(f32x4*)(out + off + bj * HALF + 4) = v1;
;                     if (xb) { u32x4 w; w.x = cvt_pk_bf16(v0[0], v0[1]); w.y = cvt_pk_bf16(v0[2], v0[3]); w.z = cvt_pk_bf16(v1[0], v1[1]); w.w = cvt_pk_bf16(v1[2], v1[3]);
;                         *(u32x4*)(xb + off + bj * HALF) = w;
;                         ss += ((v0[0] * v0[0] + v0[1] * v0[1]) + (v0[2] * v0[2] + v0[3] * v0[3])) + ((v1[0] * v1[0] + v1[1] * v1[1]) + (v1[2] * v1[2] + v1[3] * v1[3])); } }
;                 if (xb) { ss += __shfl_xor(ss, 16); ss += __shfl_xor(ss, 32); if (fq == 0) ssq[(size_t)row * 16 + u.pn * 4 + wc] = ss; } }
.LBB0_857:
	s_or_b64 exec, exec, s[24:25]
	v_add_u32_e32 v32, 0xa0, v146
	s_waitcnt lgkmcnt(0)
	v_ashrrev_i32_e32 v33, 31, v32
	v_lshlrev_b64 v[34:35], 10, v[32:33]
	v_lshl_add_u64 v[42:43], v[34:35], 0, v[144:145]
	v_lshl_add_u64 v[44:45], v[42:43], 2, s[68:69]
	global_load_dwordx4 v[34:37], v[44:45], off
	global_load_dwordx4 v[38:41], v[44:45], off offset:16
	v_readlane_b32 s24, v254, 39
	v_readlane_b32 s25, v254, 40
	s_waitcnt vmcnt(1)
	v_pk_add_f32 v[30:31], v[30:31], v[36:37]
	v_pk_add_f32 v[28:29], v[28:29], v[34:35]
	s_waitcnt vmcnt(0)
	v_pk_add_f32 v[26:27], v[26:27], v[40:41]
	v_pk_add_f32 v[24:25], v[24:25], v[38:39]
	v_lshl_add_u64 v[42:43], v[42:43], 1, s[24:25]
	v_cvt_pk_bf16_f32 v34, v28, v29
	v_cvt_pk_bf16_f32 v35, v30, v31
	v_cvt_pk_bf16_f32 v36, v24, v25
	v_cvt_pk_bf16_f32 v37, v26, v27
	v_lshl_add_u64 v[228:229], v[44:45], 0, v[230:231]
	v_lshl_add_u64 v[232:233], v[44:45], 0, v[244:245]
	s_nop 1
	v_mov_b32_dpp v236, v24 row_ror:8 row_mask:0xf bank_mask:0xf
	v_mov_b32_dpp v237, v25 row_ror:8 row_mask:0xf bank_mask:0xf
	v_mov_b32_dpp v238, v26 row_ror:8 row_mask:0xf bank_mask:0xf
	v_mov_b32_dpp v239, v27 row_ror:8 row_mask:0xf bank_mask:0xf
	v_mov_b32_dpp v240, v28 row_ror:8 row_mask:0xf bank_mask:0xf
	v_mov_b32_dpp v241, v29 row_ror:8 row_mask:0xf bank_mask:0xf
	v_mov_b32_dpp v242, v30 row_ror:8 row_mask:0xf bank_mask:0xf
	v_mov_b32_dpp v243, v31 row_ror:8 row_mask:0xf bank_mask:0xf
	s_nop 0
	v_cndmask_b32_e64 v236, v236, v28, s[98:99]
	v_cndmask_b32_e64 v237, v237, v29, s[98:99]
	v_cndmask_b32_e64 v238, v238, v30, s[98:99]
	v_cndmask_b32_e64 v239, v239, v31, s[98:99]
	v_cndmask_b32_e64 v240, v24, v240, s[98:99]
	v_cndmask_b32_e64 v241, v25, v241, s[98:99]
	v_cndmask_b32_e64 v242, v26, v242, s[98:99]
	v_cndmask_b32_e64 v243, v27, v243, s[98:99]
	global_store_dwordx4 v[228:229], v[236:239], off
	global_store_dwordx4 v[232:233], v[240:243], off
	global_store_dwordx4 v[42:43], v[34:37], off
	global_load_dwordx4 v[34:37], v[44:45], off offset:512
	s_nop 0
	global_load_dwordx4 v[38:41], v[44:45], off offset:528
	v_mul_f32_e32 v29, v29, v29
	v_mul_f32_e32 v31, v31, v31
	v_mul_f32_e32 v25, v25, v25
	v_mul_f32_e32 v27, v27, v27
	v_fmac_f32_e32 v29, v28, v28
	v_fmac_f32_e32 v31, v30, v30
	v_fmac_f32_e32 v25, v24, v24
	v_fmac_f32_e32 v27, v26, v26
	v_add_f32_e32 v24, v29, v31
	v_add_f32_e32 v25, v25, v27
	v_add_f32_e32 v28, v24, v25
	s_waitcnt vmcnt(1)
	v_pk_add_f32 v[22:23], v[22:23], v[36:37]
	v_pk_add_f32 v[20:21], v[20:21], v[34:35]
	s_waitcnt vmcnt(0)
	v_pk_add_f32 v[26:27], v[18:19], v[40:41]
	v_pk_add_f32 v[24:25], v[16:17], v[38:39]
	v_mul_f32_e32 v16, v21, v21
	v_mul_f32_e32 v17, v23, v23
	v_mul_f32_e32 v18, v25, v25
	v_mul_f32_e32 v19, v27, v27
	v_fmac_f32_e32 v16, v20, v20
	v_fmac_f32_e32 v17, v22, v22
	v_fmac_f32_e32 v18, v24, v24
	v_fmac_f32_e32 v19, v26, v26
	v_add_f32_e32 v16, v16, v17
	v_add_f32_e32 v17, v18, v19
	v_add_f32_e32 v16, v16, v17
	v_add_f32_e32 v16, v28, v16
	ds_bpermute_b32 v17, v120, v16
	v_lshl_add_u64 v[228:229], v[44:45], 0, v[230:231]
	v_lshl_add_u64 v[232:233], v[44:45], 0, v[244:245]
	s_nop 1
	v_mov_b32_dpp v236, v24 row_ror:8 row_mask:0xf bank_mask:0xf
	v_mov_b32_dpp v237, v25 row_ror:8 row_mask:0xf bank_mask:0xf
	v_mov_b32_dpp v238, v26 row_ror:8 row_mask:0xf bank_mask:0xf
	v_mov_b32_dpp v239, v27 row_ror:8 row_mask:0xf bank_mask:0xf
	v_mov_b32_dpp v240, v20 row_ror:8 row_mask:0xf bank_mask:0xf
	v_mov_b32_dpp v241, v21 row_ror:8 row_mask:0xf bank_mask:0xf
	v_mov_b32_dpp v242, v22 row_ror:8 row_mask:0xf bank_mask:0xf
	v_mov_b32_dpp v243, v23 row_ror:8 row_mask:0xf bank_mask:0xf
	s_nop 0
	v_cndmask_b32_e64 v236, v236, v20, s[98:99]
	v_cndmask_b32_e64 v237, v237, v21, s[98:99]
	v_cndmask_b32_e64 v238, v238, v22, s[98:99]
	v_cndmask_b32_e64 v239, v239, v23, s[98:99]
	v_cndmask_b32_e64 v240, v24, v240, s[98:99]
	v_cndmask_b32_e64 v241, v25, v241, s[98:99]
	v_cndmask_b32_e64 v242, v26, v242, s[98:99]
	v_cndmask_b32_e64 v243, v27, v243, s[98:99]
	global_store_dwordx4 v[228:229], v[236:239], off offset:512
	global_store_dwordx4 v[232:233], v[240:243], off offset:512
	v_cvt_pk_bf16_f32 v18, v20, v21
	v_cvt_pk_bf16_f32 v19, v22, v23
	v_cvt_pk_bf16_f32 v20, v24, v25
	s_waitcnt lgkmcnt(0)
	v_add_f32_e32 v16, v16, v17
	ds_bpermute_b32 v17, v114, v16
	v_cvt_pk_bf16_f32 v21, v26, v27
	global_store_dwordx4 v[42:43], v[18:21], off offset:256
	s_and_saveexec_b64 s[24:25], s[2:3]
	s_cbranch_execz .LBB0_859
	v_readlane_b32 s26, v254, 41
	s_waitcnt lgkmcnt(0)
	v_add_f32_e32 v18, v16, v17
	v_lshlrev_b64 v[16:17], 6, v[32:33]
	v_readlane_b32 s27, v254, 42
	s_lshl_b32 s6, s38, 2
	s_nop 0
	v_lshl_add_u64 v[16:17], s[26:27], 0, v[16:17]
	v_lshl_add_u64 v[16:17], s[22:23], 2, v[16:17]
	v_lshl_add_u64 v[16:17], v[16:17], 0, s[6:7]
	global_store_dword v[16:17], v18, off
; __device__ __forceinline__ unsigned cvt_pk_bf16(float lo, float hi) { const f32x2_t v = {lo, hi}; const bf16x2_t b = __builtin_convertvector(v, bf16x2_t); return __builtin_bit_cast(unsigned, b); }
;     __device__ __forceinline__ void operator()(const f32x4 (&acc)[2][2][4][2], const Unit& u, int wr, int wc, int fr, int fq, const PG8_LAS float*) const {
;     ...
;             for (int m = 0; m < 4; ++m) { const int row = row0 + ai * HALF + m * 16; const size_t off = (size_t)row * ldc + col0; float ss = 0.f;
; #pragma unroll
;                 for (int bj = 0; bj < 2; ++bj) {
;                     const f32x4 b0 = *(const f32x4*)(base + off + bj * HALF), b1 = *(const f32x4*)(base + off + bj * HALF + 4);
;                     const f32x4 v0 = b0 + acc[ai][bj][m][0], v1 = b1 + acc[ai][bj][m][1];
;                     *(f32x4*)(out + off + bj * HALF) = v0; *(f32x4*)(out + off + bj * HALF + 4) = v1;
;                     if (xb) { u32x4 w; w.x = cvt_pk_bf16(v0[0], v0[1]); w.y = cvt_pk_bf16(v0[2], v0[3]); w.z = cvt_pk_bf16(v1[0], v1[1]); w.w = cvt_pk_bf16(v1[2], v1[3]);
;                         *(u32x4*)(xb + off + bj * HALF) = w;
;                         ss += ((v0[0] * v0[0] + v0[1] * v0[1]) + (v0[2] * v0[2] + v0[3] * v0[3])) + ((v1[0] * v1[0] + v1[1] * v1[1]) + (v1[2] * v1[2] + v1[3] * v1[3])); } }
;                 if (xb) { ss += __shfl_xor(ss, 16); ss += __shfl_xor(ss, 32); if (fq == 0) ssq[(size_t)row * 16 + u.pn * 4 + wc] = ss; } }
.LBB0_859:
	s_or_b64 exec, exec, s[24:25]
	v_add_u32_e32 v16, 0xb0, v146
	s_waitcnt lgkmcnt(0)
	v_ashrrev_i32_e32 v17, 31, v16
	v_lshlrev_b64 v[18:19], 10, v[16:17]
	v_lshl_add_u64 v[26:27], v[18:19], 0, v[144:145]
	v_lshl_add_u64 v[28:29], v[26:27], 2, s[68:69]
	global_load_dwordx4 v[18:21], v[28:29], off
	global_load_dwordx4 v[22:25], v[28:29], off offset:16
	v_readlane_b32 s24, v254, 39
	v_readlane_b32 s25, v254, 40
	s_waitcnt vmcnt(1)
	v_pk_add_f32 v[14:15], v[14:15], v[20:21]
	v_pk_add_f32 v[12:13], v[12:13], v[18:19]
	s_waitcnt vmcnt(0)
	v_pk_add_f32 v[10:11], v[10:11], v[24:25]
	v_pk_add_f32 v[8:9], v[8:9], v[22:23]
	v_lshl_add_u64 v[26:27], v[26:27], 1, s[24:25]
	v_cvt_pk_bf16_f32 v18, v12, v13
	v_cvt_pk_bf16_f32 v19, v14, v15
	v_cvt_pk_bf16_f32 v20, v8, v9
	v_cvt_pk_bf16_f32 v21, v10, v11
	v_lshl_add_u64 v[228:229], v[28:29], 0, v[230:231]
	v_lshl_add_u64 v[232:233], v[28:29], 0, v[244:245]
	s_nop 1
	v_mov_b32_dpp v236, v8 row_ror:8 row_mask:0xf bank_mask:0xf
	v_mov_b32_dpp v237, v9 row_ror:8 row_mask:0xf bank_mask:0xf
	v_mov_b32_dpp v238, v10 row_ror:8 row_mask:0xf bank_mask:0xf
	v_mov_b32_dpp v239, v11 row_ror:8 row_mask:0xf bank_mask:0xf
	v_mov_b32_dpp v240, v12 row_ror:8 row_mask:0xf bank_mask:0xf
	v_mov_b32_dpp v241, v13 row_ror:8 row_mask:0xf bank_mask:0xf
	v_mov_b32_dpp v242, v14 row_ror:8 row_mask:0xf bank_mask:0xf
	v_mov_b32_dpp v243, v15 row_ror:8 row_mask:0xf bank_mask:0xf
	s_nop 0
	v_cndmask_b32_e64 v236, v236, v12, s[98:99]
	v_cndmask_b32_e64 v237, v237, v13, s[98:99]
	v_cndmask_b32_e64 v238, v238, v14, s[98:99]
	v_cndmask_b32_e64 v239, v239, v15, s[98:99]
	v_cndmask_b32_e64 v240, v8, v240, s[98:99]
	v_cndmask_b32_e64 v241, v9, v241, s[98:99]
	v_cndmask_b32_e64 v242, v10, v242, s[98:99]
	v_cndmask_b32_e64 v243, v11, v243, s[98:99]
	global_store_dwordx4 v[228:229], v[236:239], off
	global_store_dwordx4 v[232:233], v[240:243], off
	global_store_dwordx4 v[26:27], v[18:21], off
	global_load_dwordx4 v[18:21], v[28:29], off offset:512
	s_nop 0
	global_load_dwordx4 v[22:25], v[28:29], off offset:528
	v_mul_f32_e32 v13, v13, v13
	v_mul_f32_e32 v15, v15, v15
	v_mul_f32_e32 v9, v9, v9
	v_mul_f32_e32 v11, v11, v11
	v_fmac_f32_e32 v13, v12, v12
	v_fmac_f32_e32 v15, v14, v14
	v_fmac_f32_e32 v9, v8, v8
	v_fmac_f32_e32 v11, v10, v10
	v_add_f32_e32 v8, v13, v15
	v_add_f32_e32 v9, v9, v11
	v_add_f32_e32 v12, v8, v9
	s_waitcnt vmcnt(1)
	v_pk_add_f32 v[6:7], v[6:7], v[20:21]
	v_pk_add_f32 v[4:5], v[4:5], v[18:19]
	s_waitcnt vmcnt(0)
	v_pk_add_f32 v[10:11], v[2:3], v[24:25]
	v_pk_add_f32 v[8:9], v[0:1], v[22:23]
	v_mul_f32_e32 v0, v5, v5
	v_mul_f32_e32 v1, v7, v7
	v_mul_f32_e32 v2, v9, v9
	v_mul_f32_e32 v3, v11, v11
	v_fmac_f32_e32 v0, v4, v4
	v_fmac_f32_e32 v1, v6, v6
	v_fmac_f32_e32 v2, v8, v8
	v_fmac_f32_e32 v3, v10, v10
	v_add_f32_e32 v0, v0, v1
	v_add_f32_e32 v1, v2, v3
	v_add_f32_e32 v0, v0, v1
	v_add_f32_e32 v0, v12, v0
	ds_bpermute_b32 v1, v120, v0
	v_lshl_add_u64 v[228:229], v[28:29], 0, v[230:231]
	v_lshl_add_u64 v[232:233], v[28:29], 0, v[244:245]
	s_nop 1
	v_mov_b32_dpp v236, v8 row_ror:8 row_mask:0xf bank_mask:0xf
	v_mov_b32_dpp v237, v9 row_ror:8 row_mask:0xf bank_mask:0xf
	v_mov_b32_dpp v238, v10 row_ror:8 row_mask:0xf bank_mask:0xf
	v_mov_b32_dpp v239, v11 row_ror:8 row_mask:0xf bank_mask:0xf
	v_mov_b32_dpp v240, v4 row_ror:8 row_mask:0xf bank_mask:0xf
	v_mov_b32_dpp v241, v5 row_ror:8 row_mask:0xf bank_mask:0xf
	v_mov_b32_dpp v242, v6 row_ror:8 row_mask:0xf bank_mask:0xf
	v_mov_b32_dpp v243, v7 row_ror:8 row_mask:0xf bank_mask:0xf
	s_nop 0
	v_cndmask_b32_e64 v236, v236, v4, s[98:99]
	v_cndmask_b32_e64 v237, v237, v5, s[98:99]
	v_cndmask_b32_e64 v238, v238, v6, s[98:99]
	v_cndmask_b32_e64 v239, v239, v7, s[98:99]
	v_cndmask_b32_e64 v240, v8, v240, s[98:99]
	v_cndmask_b32_e64 v241, v9, v241, s[98:99]
	v_cndmask_b32_e64 v242, v10, v242, s[98:99]
	v_cndmask_b32_e64 v243, v11, v243, s[98:99]
	global_store_dwordx4 v[228:229], v[236:239], off offset:512
	global_store_dwordx4 v[232:233], v[240:243], off offset:512
	v_cvt_pk_bf16_f32 v2, v4, v5
	v_cvt_pk_bf16_f32 v3, v6, v7
	v_cvt_pk_bf16_f32 v4, v8, v9
	s_waitcnt lgkmcnt(0)
	v_add_f32_e32 v0, v0, v1
	ds_bpermute_b32 v1, v114, v0
	v_cvt_pk_bf16_f32 v5, v10, v11
	global_store_dwordx4 v[26:27], v[2:5], off offset:256
	s_and_saveexec_b64 s[24:25], s[2:3]
	s_cbranch_execz .LBB0_861
	v_readlane_b32 s26, v254, 41
	s_waitcnt lgkmcnt(0)
	v_add_f32_e32 v2, v0, v1
	v_lshlrev_b64 v[0:1], 6, v[16:17]
	v_readlane_b32 s27, v254, 42
	s_lshl_b32 s6, s38, 2
	s_nop 0
	v_lshl_add_u64 v[0:1], s[26:27], 0, v[0:1]
	v_lshl_add_u64 v[0:1], s[22:23], 2, v[0:1]
	v_lshl_add_u64 v[0:1], v[0:1], 0, s[6:7]
	global_store_dword v[0:1], v2, off

;     __device__ __forceinline__ void operator()(const f32x4 (&acc)[2][2][4][2], const Unit& u, int wr, int wc, int fr, int fq, const PG8_LAS float*) const {
;     ...
;             for (int m = 0; m < 4; ++m) { const int row = row0 + ai * HALF + m * 16; const size_t off = (size_t)row * ldc + col0; float ss = 0.f;
; #pragma unroll
;                 for (int bj = 0; bj < 2; ++bj) {
;                     const f32x4 b0 = *(const f32x4*)(base + off + bj * HALF), b1 = *(const f32x4*)(base + off + bj * HALF + 4);
;                     const f32x4 v0 = b0 + acc[ai][bj][m][0], v1 = b1 + acc[ai][bj][m][1];
;                     *(f32x4*)(out + off + bj * HALF) = v0; *(f32x4*)(out + off + bj * HALF + 4) = v1;
.LBB0_1644:
	v_lshl_add_u32 v146, s26, 8, v150
	v_lshl_or_b32 v144, s27, 8, v152
	v_ashrrev_i32_e32 v147, 31, v146
	v_ashrrev_i32_e32 v145, 31, v144
	v_lshlrev_b64 v[148:149], 12, v[146:147]
	v_lshl_add_u64 v[156:157], s[68:69], 0, v[148:149]
	v_lshlrev_b64 v[148:149], 2, v[144:145]
	v_lshl_add_u64 v[144:145], v[156:157], 0, v[148:149]
	global_load_dwordx4 v[156:159], v[144:145], off offset:16
	global_load_dwordx4 v[160:163], v[144:145], off
	s_mov_b64 s[26:27], -1
	s_waitcnt vmcnt(0)
	v_pk_add_f32 v[122:123], v[122:123], v[158:159]
	v_pk_add_f32 v[126:127], v[126:127], v[162:163]
	v_pk_add_f32 v[124:125], v[124:125], v[160:161]
	v_pk_add_f32 v[120:121], v[120:121], v[156:157]
	v_lshl_add_u64 v[228:229], v[144:145], 0, v[230:231]
	v_lshl_add_u64 v[232:233], v[144:145], 0, v[244:245]
	s_nop 1
	v_mov_b32_dpp v236, v120 row_ror:8 row_mask:0xf bank_mask:0xf
	v_mov_b32_dpp v237, v121 row_ror:8 row_mask:0xf bank_mask:0xf
	v_mov_b32_dpp v238, v122 row_ror:8 row_mask:0xf bank_mask:0xf
	v_mov_b32_dpp v239, v123 row_ror:8 row_mask:0xf bank_mask:0xf
	v_mov_b32_dpp v240, v124 row_ror:8 row_mask:0xf bank_mask:0xf
	v_mov_b32_dpp v241, v125 row_ror:8 row_mask:0xf bank_mask:0xf
	v_mov_b32_dpp v242, v126 row_ror:8 row_mask:0xf bank_mask:0xf
	v_mov_b32_dpp v243, v127 row_ror:8 row_mask:0xf bank_mask:0xf
	s_nop 0
	v_cndmask_b32_e64 v236, v236, v124, s[98:99]
	v_cndmask_b32_e64 v237, v237, v125, s[98:99]
	v_cndmask_b32_e64 v238, v238, v126, s[98:99]
	v_cndmask_b32_e64 v239, v239, v127, s[98:99]
	v_cndmask_b32_e64 v240, v120, v240, s[98:99]
	v_cndmask_b32_e64 v241, v121, v241, s[98:99]
	v_cndmask_b32_e64 v242, v122, v242, s[98:99]
	v_cndmask_b32_e64 v243, v123, v243, s[98:99]
	global_store_dwordx4 v[228:229], v[236:239], off
	global_store_dwordx4 v[232:233], v[240:243], off
	global_load_dwordx4 v[120:123], v[144:145], off offset:528
	s_nop 0
	global_load_dwordx4 v[124:127], v[144:145], off offset:512
	s_waitcnt vmcnt(1)
	v_pk_add_f32 v[112:113], v[112:113], v[120:121]
	s_waitcnt vmcnt(0)
	v_pk_add_f32 v[118:119], v[118:119], v[126:127]
	v_pk_add_f32 v[116:117], v[116:117], v[124:125]
	v_pk_add_f32 v[114:115], v[114:115], v[122:123]
	v_lshl_add_u64 v[228:229], v[144:145], 0, v[230:231]
	v_lshl_add_u64 v[232:233], v[144:145], 0, v[244:245]
	s_nop 1
	v_mov_b32_dpp v236, v112 row_ror:8 row_mask:0xf bank_mask:0xf
	v_mov_b32_dpp v237, v113 row_ror:8 row_mask:0xf bank_mask:0xf
	v_mov_b32_dpp v238, v114 row_ror:8 row_mask:0xf bank_mask:0xf
	v_mov_b32_dpp v239, v115 row_ror:8 row_mask:0xf bank_mask:0xf
	v_mov_b32_dpp v240, v116 row_ror:8 row_mask:0xf bank_mask:0xf
	v_mov_b32_dpp v241, v117 row_ror:8 row_mask:0xf bank_mask:0xf
	v_mov_b32_dpp v242, v118 row_ror:8 row_mask:0xf bank_mask:0xf
	v_mov_b32_dpp v243, v119 row_ror:8 row_mask:0xf bank_mask:0xf
	s_nop 0
	v_cndmask_b32_e64 v236, v236, v116, s[98:99]
	v_cndmask_b32_e64 v237, v237, v117, s[98:99]
	v_cndmask_b32_e64 v238, v238, v118, s[98:99]
	v_cndmask_b32_e64 v239, v239, v119, s[98:99]
	v_cndmask_b32_e64 v240, v112, v240, s[98:99]
	v_cndmask_b32_e64 v241, v113, v241, s[98:99]
	v_cndmask_b32_e64 v242, v114, v242, s[98:99]
	v_cndmask_b32_e64 v243, v115, v243, s[98:99]
	global_store_dwordx4 v[228:229], v[236:239], off offset:512
	global_store_dwordx4 v[232:233], v[240:243], off offset:512
	s_nop 1
	v_or_b32_e32 v112, 16, v146
	v_ashrrev_i32_e32 v113, 31, v112
	v_lshlrev_b64 v[112:113], 12, v[112:113]
	v_lshl_add_u64 v[112:113], s[68:69], 0, v[112:113]
	v_lshl_add_u64 v[120:121], v[112:113], 0, v[148:149]
	global_load_dwordx4 v[112:115], v[120:121], off offset:16
	global_load_dwordx4 v[116:119], v[120:121], off
	s_waitcnt vmcnt(1)
	v_pk_add_f32 v[106:107], v[106:107], v[114:115]
	s_waitcnt vmcnt(0)
	v_pk_add_f32 v[110:111], v[110:111], v[118:119]
	v_pk_add_f32 v[108:109], v[108:109], v[116:117]
	v_pk_add_f32 v[104:105], v[104:105], v[112:113]
	v_lshl_add_u64 v[228:229], v[120:121], 0, v[230:231]
	v_lshl_add_u64 v[232:233], v[120:121], 0, v[244:245]
	s_nop 1
	v_mov_b32_dpp v236, v104 row_ror:8 row_mask:0xf bank_mask:0xf
	v_mov_b32_dpp v237, v105 row_ror:8 row_mask:0xf bank_mask:0xf
	v_mov_b32_dpp v238, v106 row_ror:8 row_mask:0xf bank_mask:0xf
	v_mov_b32_dpp v239, v107 row_ror:8 row_mask:0xf bank_mask:0xf
	v_mov_b32_dpp v240, v108 row_ror:8 row_mask:0xf bank_mask:0xf
	v_mov_b32_dpp v241, v109 row_ror:8 row_mask:0xf bank_mask:0xf
	v_mov_b32_dpp v242, v110 row_ror:8 row_mask:0xf bank_mask:0xf
	v_mov_b32_dpp v243, v111 row_ror:8 row_mask:0xf bank_mask:0xf
	s_nop 0
	v_cndmask_b32_e64 v236, v236, v108, s[98:99]
	v_cndmask_b32_e64 v237, v237, v109, s[98:99]
	v_cndmask_b32_e64 v238, v238, v110, s[98:99]
	v_cndmask_b32_e64 v239, v239, v111, s[98:99]
	v_cndmask_b32_e64 v240, v104, v240, s[98:99]
	v_cndmask_b32_e64 v241, v105, v241, s[98:99]
	v_cndmask_b32_e64 v242, v106, v242, s[98:99]
	v_cndmask_b32_e64 v243, v107, v243, s[98:99]
	global_store_dwordx4 v[228:229], v[236:239], off
	global_store_dwordx4 v[232:233], v[240:243], off
	global_load_dwordx4 v[104:107], v[120:121], off offset:528
	s_nop 0
	global_load_dwordx4 v[108:111], v[120:121], off offset:512
	s_waitcnt vmcnt(1)
	v_pk_add_f32 v[96:97], v[96:97], v[104:105]
	s_waitcnt vmcnt(0)
;     __device__ __forceinline__ void operator()(const f32x4 (&acc)[2][2][4][2], const Unit& u, int wr, int wc, int fr, int fq, const PG8_LAS float*) const {
;     ...
;             for (int m = 0; m < 4; ++m) { const int row = row0 + ai * HALF + m * 16; const size_t off = (size_t)row * ldc + col0; float ss = 0.f;
; #pragma unroll
;                 for (int bj = 0; bj < 2; ++bj) {
;                     const f32x4 b0 = *(const f32x4*)(base + off + bj * HALF), b1 = *(const f32x4*)(base + off + bj * HALF + 4);
;                     const f32x4 v0 = b0 + acc[ai][bj][m][0], v1 = b1 + acc[ai][bj][m][1];
;                     *(f32x4*)(out + off + bj * HALF) = v0; *(f32x4*)(out + off + bj * HALF + 4) = v1;
	v_pk_add_f32 v[102:103], v[102:103], v[110:111]
	v_pk_add_f32 v[100:101], v[100:101], v[108:109]
	v_pk_add_f32 v[98:99], v[98:99], v[106:107]
	v_lshl_add_u64 v[228:229], v[120:121], 0, v[230:231]
	v_lshl_add_u64 v[232:233], v[120:121], 0, v[244:245]
	s_nop 1
	v_mov_b32_dpp v236, v96 row_ror:8 row_mask:0xf bank_mask:0xf
	v_mov_b32_dpp v237, v97 row_ror:8 row_mask:0xf bank_mask:0xf
	v_mov_b32_dpp v238, v98 row_ror:8 row_mask:0xf bank_mask:0xf
	v_mov_b32_dpp v239, v99 row_ror:8 row_mask:0xf bank_mask:0xf
	v_mov_b32_dpp v240, v100 row_ror:8 row_mask:0xf bank_mask:0xf
	v_mov_b32_dpp v241, v101 row_ror:8 row_mask:0xf bank_mask:0xf
	v_mov_b32_dpp v242, v102 row_ror:8 row_mask:0xf bank_mask:0xf
	v_mov_b32_dpp v243, v103 row_ror:8 row_mask:0xf bank_mask:0xf
	s_nop 0
	v_cndmask_b32_e64 v236, v236, v100, s[98:99]
	v_cndmask_b32_e64 v237, v237, v101, s[98:99]
	v_cndmask_b32_e64 v238, v238, v102, s[98:99]
	v_cndmask_b32_e64 v239, v239, v103, s[98:99]
	v_cndmask_b32_e64 v240, v96, v240, s[98:99]
	v_cndmask_b32_e64 v241, v97, v241, s[98:99]
	v_cndmask_b32_e64 v242, v98, v242, s[98:99]
	v_cndmask_b32_e64 v243, v99, v243, s[98:99]
	global_store_dwordx4 v[228:229], v[236:239], off offset:512
	global_store_dwordx4 v[232:233], v[240:243], off offset:512
	s_nop 1
	v_or_b32_e32 v96, 32, v146
	v_ashrrev_i32_e32 v97, 31, v96
	v_lshlrev_b64 v[96:97], 12, v[96:97]
	v_lshl_add_u64 v[96:97], s[68:69], 0, v[96:97]
	v_lshl_add_u64 v[104:105], v[96:97], 0, v[148:149]
	global_load_dwordx4 v[96:99], v[104:105], off offset:16
	global_load_dwordx4 v[100:103], v[104:105], off
	s_waitcnt vmcnt(1)
	v_pk_add_f32 v[90:91], v[90:91], v[98:99]
	s_waitcnt vmcnt(0)
	v_pk_add_f32 v[94:95], v[94:95], v[102:103]
	v_pk_add_f32 v[92:93], v[92:93], v[100:101]
	v_pk_add_f32 v[88:89], v[88:89], v[96:97]
	v_lshl_add_u64 v[228:229], v[104:105], 0, v[230:231]
	v_lshl_add_u64 v[232:233], v[104:105], 0, v[244:245]
	s_nop 1
	v_mov_b32_dpp v236, v88 row_ror:8 row_mask:0xf bank_mask:0xf
	v_mov_b32_dpp v237, v89 row_ror:8 row_mask:0xf bank_mask:0xf
	v_mov_b32_dpp v238, v90 row_ror:8 row_mask:0xf bank_mask:0xf
	v_mov_b32_dpp v239, v91 row_ror:8 row_mask:0xf bank_mask:0xf
	v_mov_b32_dpp v240, v92 row_ror:8 row_mask:0xf bank_mask:0xf
	v_mov_b32_dpp v241, v93 row_ror:8 row_mask:0xf bank_mask:0xf
	v_mov_b32_dpp v242, v94 row_ror:8 row_mask:0xf bank_mask:0xf
	v_mov_b32_dpp v243, v95 row_ror:8 row_mask:0xf bank_mask:0xf
	s_nop 0
	v_cndmask_b32_e64 v236, v236, v92, s[98:99]
	v_cndmask_b32_e64 v237, v237, v93, s[98:99]
	v_cndmask_b32_e64 v238, v238, v94, s[98:99]
	v_cndmask_b32_e64 v239, v239, v95, s[98:99]
	v_cndmask_b32_e64 v240, v88, v240, s[98:99]
	v_cndmask_b32_e64 v241, v89, v241, s[98:99]
	v_cndmask_b32_e64 v242, v90, v242, s[98:99]
	v_cndmask_b32_e64 v243, v91, v243, s[98:99]
	global_store_dwordx4 v[228:229], v[236:239], off
	global_store_dwordx4 v[232:233], v[240:243], off
	global_load_dwordx4 v[88:91], v[104:105], off offset:528
	s_nop 0
	global_load_dwordx4 v[92:95], v[104:105], off offset:512
	s_waitcnt vmcnt(1)
	v_pk_add_f32 v[80:81], v[80:81], v[88:89]
	s_waitcnt vmcnt(0)
	v_pk_add_f32 v[86:87], v[86:87], v[94:95]
	v_pk_add_f32 v[84:85], v[84:85], v[92:93]
	v_pk_add_f32 v[82:83], v[82:83], v[90:91]
	v_lshl_add_u64 v[228:229], v[104:105], 0, v[230:231]
	v_lshl_add_u64 v[232:233], v[104:105], 0, v[244:245]
	s_nop 1
	v_mov_b32_dpp v236, v80 row_ror:8 row_mask:0xf bank_mask:0xf
	v_mov_b32_dpp v237, v81 row_ror:8 row_mask:0xf bank_mask:0xf
	v_mov_b32_dpp v238, v82 row_ror:8 row_mask:0xf bank_mask:0xf
	v_mov_b32_dpp v239, v83 row_ror:8 row_mask:0xf bank_mask:0xf
	v_mov_b32_dpp v240, v84 row_ror:8 row_mask:0xf bank_mask:0xf
	v_mov_b32_dpp v241, v85 row_ror:8 row_mask:0xf bank_mask:0xf
	v_mov_b32_dpp v242, v86 row_ror:8 row_mask:0xf bank_mask:0xf
	v_mov_b32_dpp v243, v87 row_ror:8 row_mask:0xf bank_mask:0xf
	s_nop 0
	v_cndmask_b32_e64 v236, v236, v84, s[98:99]
	v_cndmask_b32_e64 v237, v237, v85, s[98:99]
	v_cndmask_b32_e64 v238, v238, v86, s[98:99]
	v_cndmask_b32_e64 v239, v239, v87, s[98:99]
	v_cndmask_b32_e64 v240, v80, v240, s[98:99]
	v_cndmask_b32_e64 v241, v81, v241, s[98:99]
	v_cndmask_b32_e64 v242, v82, v242, s[98:99]
	v_cndmask_b32_e64 v243, v83, v243, s[98:99]
	global_store_dwordx4 v[228:229], v[236:239], off offset:512
	global_store_dwordx4 v[232:233], v[240:243], off offset:512
	s_nop 1
	v_or_b32_e32 v80, 48, v146
	v_ashrrev_i32_e32 v81, 31, v80
	v_lshlrev_b64 v[80:81], 12, v[80:81]
	v_lshl_add_u64 v[80:81], s[68:69], 0, v[80:81]
	v_lshl_add_u64 v[88:89], v[80:81], 0, v[148:149]
	global_load_dwordx4 v[80:83], v[88:89], off offset:16
	global_load_dwordx4 v[84:87], v[88:89], off
	s_waitcnt vmcnt(1)
	v_pk_add_f32 v[74:75], v[74:75], v[82:83]
	s_waitcnt vmcnt(0)
	v_pk_add_f32 v[78:79], v[78:79], v[86:87]
	v_pk_add_f32 v[76:77], v[76:77], v[84:85]
	v_pk_add_f32 v[72:73], v[72:73], v[80:81]
	v_lshl_add_u64 v[228:229], v[88:89], 0, v[230:231]
	v_lshl_add_u64 v[232:233], v[88:89], 0, v[244:245]
	s_nop 1
	v_mov_b32_dpp v236, v72 row_ror:8 row_mask:0xf bank_mask:0xf
	v_mov_b32_dpp v237, v73 row_ror:8 row_mask:0xf bank_mask:0xf
	v_mov_b32_dpp v238, v74 row_ror:8 row_mask:0xf bank_mask:0xf
	v_mov_b32_dpp v239, v75 row_ror:8 row_mask:0xf bank_mask:0xf
	v_mov_b32_dpp v240, v76 row_ror:8 row_mask:0xf bank_mask:0xf
	v_mov_b32_dpp v241, v77 row_ror:8 row_mask:0xf bank_mask:0xf
	v_mov_b32_dpp v242, v78 row_ror:8 row_mask:0xf bank_mask:0xf
	v_mov_b32_dpp v243, v79 row_ror:8 row_mask:0xf bank_mask:0xf
	s_nop 0
	v_cndmask_b32_e64 v236, v236, v76, s[98:99]
	v_cndmask_b32_e64 v237, v237, v77, s[98:99]
	v_cndmask_b32_e64 v238, v238, v78, s[98:99]
	v_cndmask_b32_e64 v239, v239, v79, s[98:99]
	v_cndmask_b32_e64 v240, v72, v240, s[98:99]
	v_cndmask_b32_e64 v241, v73, v241, s[98:99]
	v_cndmask_b32_e64 v242, v74, v242, s[98:99]
	v_cndmask_b32_e64 v243, v75, v243, s[98:99]
	global_store_dwordx4 v[228:229], v[236:239], off
	global_store_dwordx4 v[232:233], v[240:243], off
	global_load_dwordx4 v[72:75], v[88:89], off offset:528
	s_nop 0
	global_load_dwordx4 v[76:79], v[88:89], off offset:512
	s_waitcnt vmcnt(1)
;     __device__ __forceinline__ void operator()(const f32x4 (&acc)[2][2][4][2], const Unit& u, int wr, int wc, int fr, int fq, const PG8_LAS float*) const {
;     ...
;             for (int m = 0; m < 4; ++m) { const int row = row0 + ai * HALF + m * 16; const size_t off = (size_t)row * ldc + col0; float ss = 0.f;
; #pragma unroll
;                 for (int bj = 0; bj < 2; ++bj) {
;                     const f32x4 b0 = *(const f32x4*)(base + off + bj * HALF), b1 = *(const f32x4*)(base + off + bj * HALF + 4);
;                     const f32x4 v0 = b0 + acc[ai][bj][m][0], v1 = b1 + acc[ai][bj][m][1];
;                     *(f32x4*)(out + off + bj * HALF) = v0; *(f32x4*)(out + off + bj * HALF + 4) = v1;
	v_pk_add_f32 v[66:67], v[66:67], v[74:75]
	s_waitcnt vmcnt(0)
	v_pk_add_f32 v[70:71], v[70:71], v[78:79]
	v_pk_add_f32 v[68:69], v[68:69], v[76:77]
	v_add_co_u32_e32 v74, vcc, s50, v144
	v_pk_add_f32 v[64:65], v[64:65], v[72:73]
	v_lshl_add_u64 v[228:229], v[88:89], 0, v[230:231]
	v_lshl_add_u64 v[232:233], v[88:89], 0, v[244:245]
	s_nop 1
	v_mov_b32_dpp v236, v64 row_ror:8 row_mask:0xf bank_mask:0xf
	v_mov_b32_dpp v237, v65 row_ror:8 row_mask:0xf bank_mask:0xf
	v_mov_b32_dpp v238, v66 row_ror:8 row_mask:0xf bank_mask:0xf
	v_mov_b32_dpp v239, v67 row_ror:8 row_mask:0xf bank_mask:0xf
	v_mov_b32_dpp v240, v68 row_ror:8 row_mask:0xf bank_mask:0xf
	v_mov_b32_dpp v241, v69 row_ror:8 row_mask:0xf bank_mask:0xf
	v_mov_b32_dpp v242, v70 row_ror:8 row_mask:0xf bank_mask:0xf
	v_mov_b32_dpp v243, v71 row_ror:8 row_mask:0xf bank_mask:0xf
	s_nop 0
	v_cndmask_b32_e64 v236, v236, v68, s[98:99]
	v_cndmask_b32_e64 v237, v237, v69, s[98:99]
	v_cndmask_b32_e64 v238, v238, v70, s[98:99]
	v_cndmask_b32_e64 v239, v239, v71, s[98:99]
	v_cndmask_b32_e64 v240, v64, v240, s[98:99]
	v_cndmask_b32_e64 v241, v65, v241, s[98:99]
	v_cndmask_b32_e64 v242, v66, v242, s[98:99]
	v_cndmask_b32_e64 v243, v67, v243, s[98:99]
	global_store_dwordx4 v[228:229], v[236:239], off offset:512
	global_store_dwordx4 v[232:233], v[240:243], off offset:512
	v_addc_co_u32_e32 v75, vcc, 0, v145, vcc
	v_lshl_add_u64 v[72:73], v[144:145], 0, s[10:11]
	global_load_dwordx4 v[64:67], v[74:75], off
	global_load_dwordx4 v[68:71], v[72:73], off offset:16
	s_waitcnt vmcnt(1)
	v_pk_add_f32 v[62:63], v[62:63], v[66:67]
	v_pk_add_f32 v[60:61], v[60:61], v[64:65]
	s_waitcnt vmcnt(0)
	v_pk_add_f32 v[58:59], v[58:59], v[70:71]
	v_pk_add_f32 v[56:57], v[56:57], v[68:69]
	v_lshl_add_u64 v[228:229], v[74:75], 0, v[230:231]
	v_lshl_add_u64 v[232:233], v[72:73], 0, v[244:245]
	s_nop 1
	v_mov_b32_dpp v236, v56 row_ror:8 row_mask:0xf bank_mask:0xf
	v_mov_b32_dpp v237, v57 row_ror:8 row_mask:0xf bank_mask:0xf
	v_mov_b32_dpp v238, v58 row_ror:8 row_mask:0xf bank_mask:0xf
	v_mov_b32_dpp v239, v59 row_ror:8 row_mask:0xf bank_mask:0xf
	v_mov_b32_dpp v240, v60 row_ror:8 row_mask:0xf bank_mask:0xf
	v_mov_b32_dpp v241, v61 row_ror:8 row_mask:0xf bank_mask:0xf
	v_mov_b32_dpp v242, v62 row_ror:8 row_mask:0xf bank_mask:0xf
	v_mov_b32_dpp v243, v63 row_ror:8 row_mask:0xf bank_mask:0xf
	s_nop 0
	v_cndmask_b32_e64 v236, v236, v60, s[98:99]
	v_cndmask_b32_e64 v237, v237, v61, s[98:99]
	v_cndmask_b32_e64 v238, v238, v62, s[98:99]
	v_cndmask_b32_e64 v239, v239, v63, s[98:99]
	v_cndmask_b32_e64 v240, v56, v240, s[98:99]
	v_cndmask_b32_e64 v241, v57, v241, s[98:99]
	v_cndmask_b32_e64 v242, v58, v242, s[98:99]
	v_cndmask_b32_e64 v243, v59, v243, s[98:99]
	global_store_dwordx4 v[228:229], v[236:239], off
	global_store_dwordx4 v[232:233], v[240:243], off
	global_load_dwordx4 v[56:59], v[72:73], off offset:528
	s_nop 0
	global_load_dwordx4 v[60:63], v[72:73], off offset:512
	s_waitcnt vmcnt(1)
	v_pk_add_f32 v[50:51], v[50:51], v[58:59]
	s_waitcnt vmcnt(0)
	v_pk_add_f32 v[54:55], v[54:55], v[62:63]
	v_pk_add_f32 v[52:53], v[52:53], v[60:61]
	v_add_co_u32_e32 v58, vcc, s51, v144
	v_pk_add_f32 v[48:49], v[48:49], v[56:57]
	v_lshl_add_u64 v[228:229], v[72:73], 0, v[230:231]
	v_lshl_add_u64 v[232:233], v[72:73], 0, v[244:245]
	s_nop 1
	v_mov_b32_dpp v236, v48 row_ror:8 row_mask:0xf bank_mask:0xf
	v_mov_b32_dpp v237, v49 row_ror:8 row_mask:0xf bank_mask:0xf
	v_mov_b32_dpp v238, v50 row_ror:8 row_mask:0xf bank_mask:0xf
	v_mov_b32_dpp v239, v51 row_ror:8 row_mask:0xf bank_mask:0xf
	v_mov_b32_dpp v240, v52 row_ror:8 row_mask:0xf bank_mask:0xf
	v_mov_b32_dpp v241, v53 row_ror:8 row_mask:0xf bank_mask:0xf
	v_mov_b32_dpp v242, v54 row_ror:8 row_mask:0xf bank_mask:0xf
	v_mov_b32_dpp v243, v55 row_ror:8 row_mask:0xf bank_mask:0xf
	s_nop 0
	v_cndmask_b32_e64 v236, v236, v52, s[98:99]
	v_cndmask_b32_e64 v237, v237, v53, s[98:99]
	v_cndmask_b32_e64 v238, v238, v54, s[98:99]
	v_cndmask_b32_e64 v239, v239, v55, s[98:99]
	v_cndmask_b32_e64 v240, v48, v240, s[98:99]
	v_cndmask_b32_e64 v241, v49, v241, s[98:99]
	v_cndmask_b32_e64 v242, v50, v242, s[98:99]
	v_cndmask_b32_e64 v243, v51, v243, s[98:99]
	global_store_dwordx4 v[228:229], v[236:239], off offset:512
	global_store_dwordx4 v[232:233], v[240:243], off offset:512
	v_addc_co_u32_e32 v59, vcc, 0, v145, vcc
	v_lshl_add_u64 v[56:57], v[144:145], 0, s[12:13]
	global_load_dwordx4 v[48:51], v[58:59], off
	global_load_dwordx4 v[52:55], v[56:57], off offset:16
	s_waitcnt vmcnt(1)
	v_pk_add_f32 v[46:47], v[46:47], v[50:51]
	v_pk_add_f32 v[44:45], v[44:45], v[48:49]
	s_waitcnt vmcnt(0)
	v_pk_add_f32 v[42:43], v[42:43], v[54:55]
	v_pk_add_f32 v[40:41], v[40:41], v[52:53]
	v_lshl_add_u64 v[228:229], v[58:59], 0, v[230:231]
	v_lshl_add_u64 v[232:233], v[56:57], 0, v[244:245]
	s_nop 1
	v_mov_b32_dpp v236, v40 row_ror:8 row_mask:0xf bank_mask:0xf
	v_mov_b32_dpp v237, v41 row_ror:8 row_mask:0xf bank_mask:0xf
	v_mov_b32_dpp v238, v42 row_ror:8 row_mask:0xf bank_mask:0xf
	v_mov_b32_dpp v239, v43 row_ror:8 row_mask:0xf bank_mask:0xf
	v_mov_b32_dpp v240, v44 row_ror:8 row_mask:0xf bank_mask:0xf
	v_mov_b32_dpp v241, v45 row_ror:8 row_mask:0xf bank_mask:0xf
	v_mov_b32_dpp v242, v46 row_ror:8 row_mask:0xf bank_mask:0xf
	v_mov_b32_dpp v243, v47 row_ror:8 row_mask:0xf bank_mask:0xf
	s_nop 0
	v_cndmask_b32_e64 v236, v236, v44, s[98:99]
	v_cndmask_b32_e64 v237, v237, v45, s[98:99]
	v_cndmask_b32_e64 v238, v238, v46, s[98:99]
	v_cndmask_b32_e64 v239, v239, v47, s[98:99]
	v_cndmask_b32_e64 v240, v40, v240, s[98:99]
	v_cndmask_b32_e64 v241, v41, v241, s[98:99]
	v_cndmask_b32_e64 v242, v42, v242, s[98:99]
	v_cndmask_b32_e64 v243, v43, v243, s[98:99]
	global_store_dwordx4 v[228:229], v[236:239], off
	global_store_dwordx4 v[232:233], v[240:243], off
	global_load_dwordx4 v[40:43], v[56:57], off offset:528
	s_nop 0
	global_load_dwordx4 v[44:47], v[56:57], off offset:512
	s_waitcnt vmcnt(1)
;     __device__ __forceinline__ void operator()(const f32x4 (&acc)[2][2][4][2], const Unit& u, int wr, int wc, int fr, int fq, const PG8_LAS float*) const {
;     ...
;             for (int m = 0; m < 4; ++m) { const int row = row0 + ai * HALF + m * 16; const size_t off = (size_t)row * ldc + col0; float ss = 0.f;
; #pragma unroll
;                 for (int bj = 0; bj < 2; ++bj) {
;                     const f32x4 b0 = *(const f32x4*)(base + off + bj * HALF), b1 = *(const f32x4*)(base + off + bj * HALF + 4);
;                     const f32x4 v0 = b0 + acc[ai][bj][m][0], v1 = b1 + acc[ai][bj][m][1];
;                     *(f32x4*)(out + off + bj * HALF) = v0; *(f32x4*)(out + off + bj * HALF + 4) = v1;
	v_pk_add_f32 v[34:35], v[34:35], v[42:43]
	s_waitcnt vmcnt(0)
	v_pk_add_f32 v[38:39], v[38:39], v[46:47]
	v_pk_add_f32 v[36:37], v[36:37], v[44:45]
	v_add_co_u32_e32 v42, vcc, s52, v144
	v_pk_add_f32 v[32:33], v[32:33], v[40:41]
	v_lshl_add_u64 v[228:229], v[56:57], 0, v[230:231]
	v_lshl_add_u64 v[232:233], v[56:57], 0, v[244:245]
	s_nop 1
	v_mov_b32_dpp v236, v32 row_ror:8 row_mask:0xf bank_mask:0xf
	v_mov_b32_dpp v237, v33 row_ror:8 row_mask:0xf bank_mask:0xf
	v_mov_b32_dpp v238, v34 row_ror:8 row_mask:0xf bank_mask:0xf
	v_mov_b32_dpp v239, v35 row_ror:8 row_mask:0xf bank_mask:0xf
	v_mov_b32_dpp v240, v36 row_ror:8 row_mask:0xf bank_mask:0xf
	v_mov_b32_dpp v241, v37 row_ror:8 row_mask:0xf bank_mask:0xf
	v_mov_b32_dpp v242, v38 row_ror:8 row_mask:0xf bank_mask:0xf
	v_mov_b32_dpp v243, v39 row_ror:8 row_mask:0xf bank_mask:0xf
	s_nop 0
	v_cndmask_b32_e64 v236, v236, v36, s[98:99]
	v_cndmask_b32_e64 v237, v237, v37, s[98:99]
	v_cndmask_b32_e64 v238, v238, v38, s[98:99]
	v_cndmask_b32_e64 v239, v239, v39, s[98:99]
	v_cndmask_b32_e64 v240, v32, v240, s[98:99]
	v_cndmask_b32_e64 v241, v33, v241, s[98:99]
	v_cndmask_b32_e64 v242, v34, v242, s[98:99]
	v_cndmask_b32_e64 v243, v35, v243, s[98:99]
	global_store_dwordx4 v[228:229], v[236:239], off offset:512
	global_store_dwordx4 v[232:233], v[240:243], off offset:512
	v_addc_co_u32_e32 v43, vcc, 0, v145, vcc
	v_lshl_add_u64 v[40:41], v[144:145], 0, s[14:15]
	global_load_dwordx4 v[32:35], v[42:43], off
	global_load_dwordx4 v[36:39], v[40:41], off offset:16
	s_waitcnt vmcnt(1)
	v_pk_add_f32 v[30:31], v[30:31], v[34:35]
	v_pk_add_f32 v[28:29], v[28:29], v[32:33]
	s_waitcnt vmcnt(0)
	v_pk_add_f32 v[26:27], v[26:27], v[38:39]
	v_pk_add_f32 v[24:25], v[24:25], v[36:37]
	v_lshl_add_u64 v[228:229], v[42:43], 0, v[230:231]
	v_lshl_add_u64 v[232:233], v[40:41], 0, v[244:245]
	s_nop 1
	v_mov_b32_dpp v236, v24 row_ror:8 row_mask:0xf bank_mask:0xf
	v_mov_b32_dpp v237, v25 row_ror:8 row_mask:0xf bank_mask:0xf
	v_mov_b32_dpp v238, v26 row_ror:8 row_mask:0xf bank_mask:0xf
	v_mov_b32_dpp v239, v27 row_ror:8 row_mask:0xf bank_mask:0xf
	v_mov_b32_dpp v240, v28 row_ror:8 row_mask:0xf bank_mask:0xf
	v_mov_b32_dpp v241, v29 row_ror:8 row_mask:0xf bank_mask:0xf
	v_mov_b32_dpp v242, v30 row_ror:8 row_mask:0xf bank_mask:0xf
	v_mov_b32_dpp v243, v31 row_ror:8 row_mask:0xf bank_mask:0xf
	s_nop 0
	v_cndmask_b32_e64 v236, v236, v28, s[98:99]
	v_cndmask_b32_e64 v237, v237, v29, s[98:99]
	v_cndmask_b32_e64 v238, v238, v30, s[98:99]
	v_cndmask_b32_e64 v239, v239, v31, s[98:99]
	v_cndmask_b32_e64 v240, v24, v240, s[98:99]
	v_cndmask_b32_e64 v241, v25, v241, s[98:99]
	v_cndmask_b32_e64 v242, v26, v242, s[98:99]
	v_cndmask_b32_e64 v243, v27, v243, s[98:99]
	global_store_dwordx4 v[228:229], v[236:239], off
	global_store_dwordx4 v[232:233], v[240:243], off
	global_load_dwordx4 v[24:27], v[40:41], off offset:528
	s_nop 0
	global_load_dwordx4 v[28:31], v[40:41], off offset:512
	s_waitcnt vmcnt(1)
	v_pk_add_f32 v[18:19], v[18:19], v[26:27]
	s_waitcnt vmcnt(0)
; #define PG8_BAR __builtin_amdgcn_s_barrier()
;     __device__ __forceinline__ void operator()(const f32x4 (&acc)[2][2][4][2], const Unit& u, int wr, int wc, int fr, int fq, const PG8_LAS float*) const {
;     ...
;             for (int m = 0; m < 4; ++m) { const int row = row0 + ai * HALF + m * 16; const size_t off = (size_t)row * ldc + col0; float ss = 0.f;
; #pragma unroll
;                 for (int bj = 0; bj < 2; ++bj) {
;                     const f32x4 b0 = *(const f32x4*)(base + off + bj * HALF), b1 = *(const f32x4*)(base + off + bj * HALF + 4);
;                     const f32x4 v0 = b0 + acc[ai][bj][m][0], v1 = b1 + acc[ai][bj][m][1];
;                     *(f32x4*)(out + off + bj * HALF) = v0; *(f32x4*)(out + off + bj * HALF + 4) = v1;
; template <class Epi, class Sched, bool ALIGN_EPI = false, bool SP2 = false>
; __device__ __forceinline__ void gemm_phase(PG8_LAS unsigned char* lds, const Gemm g, const Sched& S, const Epi& E) {
;     ...
;         S.done(cur);
;         if (!has_next) break;
; #pragma unroll
;         for (int a = 0; a < 2; ++a)
; #pragma unroll
;             for (int b = 0; b < 2; ++b)
; #pragma unroll
;                 for (int m = 0; m < 4; ++m)
; #pragma unroll
;                     for (int n = 0; n < 2; ++n) acc[a][b][m][n] = (f32x4){0.f, 0.f, 0.f, 0.f};
;         cur = nxt; cA = nA; cB = nB; ++ui;
;         if constexpr (ALIGN_EPI) { if (wr == 1) PG8_BAR; }
	v_pk_add_f32 v[22:23], v[22:23], v[30:31]
	v_pk_add_f32 v[20:21], v[20:21], v[28:29]
	v_add_co_u32_e32 v26, vcc, s53, v144
	v_pk_add_f32 v[16:17], v[16:17], v[24:25]
	v_lshl_add_u64 v[228:229], v[40:41], 0, v[230:231]
	v_lshl_add_u64 v[232:233], v[40:41], 0, v[244:245]
	s_nop 1
	v_mov_b32_dpp v236, v16 row_ror:8 row_mask:0xf bank_mask:0xf
	v_mov_b32_dpp v237, v17 row_ror:8 row_mask:0xf bank_mask:0xf
	v_mov_b32_dpp v238, v18 row_ror:8 row_mask:0xf bank_mask:0xf
	v_mov_b32_dpp v239, v19 row_ror:8 row_mask:0xf bank_mask:0xf
	v_mov_b32_dpp v240, v20 row_ror:8 row_mask:0xf bank_mask:0xf
	v_mov_b32_dpp v241, v21 row_ror:8 row_mask:0xf bank_mask:0xf
	v_mov_b32_dpp v242, v22 row_ror:8 row_mask:0xf bank_mask:0xf
	v_mov_b32_dpp v243, v23 row_ror:8 row_mask:0xf bank_mask:0xf
	s_nop 0
	v_cndmask_b32_e64 v236, v236, v20, s[98:99]
	v_cndmask_b32_e64 v237, v237, v21, s[98:99]
	v_cndmask_b32_e64 v238, v238, v22, s[98:99]
	v_cndmask_b32_e64 v239, v239, v23, s[98:99]
	v_cndmask_b32_e64 v240, v16, v240, s[98:99]
	v_cndmask_b32_e64 v241, v17, v241, s[98:99]
	v_cndmask_b32_e64 v242, v18, v242, s[98:99]
	v_cndmask_b32_e64 v243, v19, v243, s[98:99]
	global_store_dwordx4 v[228:229], v[236:239], off offset:512
	global_store_dwordx4 v[232:233], v[240:243], off offset:512
	v_addc_co_u32_e32 v27, vcc, 0, v145, vcc
	s_nop 0
	v_lshl_add_u64 v[16:17], v[144:145], 0, s[16:17]
	global_load_dwordx4 v[18:21], v[26:27], off
	global_load_dwordx4 v[22:25], v[16:17], off offset:16
	s_andn2_b64 vcc, exec, s[2:3]
	s_waitcnt vmcnt(1)
	v_pk_add_f32 v[14:15], v[14:15], v[20:21]
	v_pk_add_f32 v[12:13], v[12:13], v[18:19]
	s_waitcnt vmcnt(0)
	v_pk_add_f32 v[10:11], v[10:11], v[24:25]
	v_pk_add_f32 v[8:9], v[8:9], v[22:23]
	v_lshl_add_u64 v[228:229], v[26:27], 0, v[230:231]
	v_lshl_add_u64 v[232:233], v[16:17], 0, v[244:245]
	s_nop 1
	v_mov_b32_dpp v236, v8 row_ror:8 row_mask:0xf bank_mask:0xf
	v_mov_b32_dpp v237, v9 row_ror:8 row_mask:0xf bank_mask:0xf
	v_mov_b32_dpp v238, v10 row_ror:8 row_mask:0xf bank_mask:0xf
	v_mov_b32_dpp v239, v11 row_ror:8 row_mask:0xf bank_mask:0xf
	v_mov_b32_dpp v240, v12 row_ror:8 row_mask:0xf bank_mask:0xf
	v_mov_b32_dpp v241, v13 row_ror:8 row_mask:0xf bank_mask:0xf
	v_mov_b32_dpp v242, v14 row_ror:8 row_mask:0xf bank_mask:0xf
	v_mov_b32_dpp v243, v15 row_ror:8 row_mask:0xf bank_mask:0xf
	s_nop 0
	v_cndmask_b32_e64 v236, v236, v12, s[98:99]
	v_cndmask_b32_e64 v237, v237, v13, s[98:99]
	v_cndmask_b32_e64 v238, v238, v14, s[98:99]
	v_cndmask_b32_e64 v239, v239, v15, s[98:99]
	v_cndmask_b32_e64 v240, v8, v240, s[98:99]
	v_cndmask_b32_e64 v241, v9, v241, s[98:99]
	v_cndmask_b32_e64 v242, v10, v242, s[98:99]
	v_cndmask_b32_e64 v243, v11, v243, s[98:99]
	global_store_dwordx4 v[228:229], v[236:239], off
	global_store_dwordx4 v[232:233], v[240:243], off
	global_load_dwordx4 v[8:11], v[16:17], off offset:528
	s_nop 0
	global_load_dwordx4 v[12:15], v[16:17], off offset:512
	s_waitcnt vmcnt(1)
	v_pk_add_f32 v[2:3], v[2:3], v[10:11]
	s_waitcnt vmcnt(0)
	v_pk_add_f32 v[6:7], v[6:7], v[14:15]
	v_pk_add_f32 v[4:5], v[4:5], v[12:13]
	v_pk_add_f32 v[0:1], v[0:1], v[8:9]
	v_lshl_add_u64 v[228:229], v[16:17], 0, v[230:231]
	v_lshl_add_u64 v[232:233], v[16:17], 0, v[244:245]
	s_nop 1
	v_mov_b32_dpp v236, v0 row_ror:8 row_mask:0xf bank_mask:0xf
	v_mov_b32_dpp v237, v1 row_ror:8 row_mask:0xf bank_mask:0xf
	v_mov_b32_dpp v238, v2 row_ror:8 row_mask:0xf bank_mask:0xf
	v_mov_b32_dpp v239, v3 row_ror:8 row_mask:0xf bank_mask:0xf
	v_mov_b32_dpp v240, v4 row_ror:8 row_mask:0xf bank_mask:0xf
	v_mov_b32_dpp v241, v5 row_ror:8 row_mask:0xf bank_mask:0xf
	v_mov_b32_dpp v242, v6 row_ror:8 row_mask:0xf bank_mask:0xf
	v_mov_b32_dpp v243, v7 row_ror:8 row_mask:0xf bank_mask:0xf
	s_nop 0
	v_cndmask_b32_e64 v236, v236, v4, s[98:99]
	v_cndmask_b32_e64 v237, v237, v5, s[98:99]
	v_cndmask_b32_e64 v238, v238, v6, s[98:99]
	v_cndmask_b32_e64 v239, v239, v7, s[98:99]
	v_cndmask_b32_e64 v240, v0, v240, s[98:99]
	v_cndmask_b32_e64 v241, v1, v241, s[98:99]
	v_cndmask_b32_e64 v242, v2, v242, s[98:99]
	v_cndmask_b32_e64 v243, v3, v243, s[98:99]
	global_store_dwordx4 v[228:229], v[236:239], off offset:512
	global_store_dwordx4 v[232:233], v[240:243], off offset:512
	s_cbranch_vccnz .LBB0_1633
	s_andn2_b64 vcc, exec, s[4:5]
	s_cbranch_vccnz .LBB0_1632
	s_barrier
	s_branch .LBB0_1632
